# v7: hand-written P0 weight conversion + Ua loop, P1 KV-CU tile remap, part of layer-1 weight conversion moved to idle CUs of layer-0 FFN2 last round, compiler-inserted vmcnt(0) drains in GEMM prologue
# speedup vs baseline: 1.0236x; 1.0058x over previous
; __device__ __forceinline__ void phase_prologue(PtrTab TB, unsigned char* ws, float* xout, int l, LAS unsigned char* lds, int gw, int NGW, int lane, int wave) {
;     ...
;     for (int it = gw; it < S14; it += NGW) {
;         if (it < S1 || (it >= S12 && it < S13)) {
.LBB0_23:
	s_cmpk_eq_u32 s8, 0x800
	s_cbranch_scc0 .Ltr_start
	s_cmpk_eq_u32 s94, 1
	s_cbranch_scc0 .Ltr_start
	s_cmpk_lt_u32 s71, 0xc00
	s_cbranch_scc0 .Ltr_start
	s_addk_i32 s71, 0xc00

; #define LAS __attribute__((address_space(3)))
; #define LDS_WAIT() asm volatile("s_waitcnt lgkmcnt(0)" ::: "memory")
; __device__ __forceinline__ void tr_item(const float* W, int ldn, int col0, int k0, const float* g, bf16* WT, int ldk, int drow0, LAS float* scr, int lane) {
;     const int n4 = (lane & 15) * 4, kr = lane >> 4;
; #pragma unroll
;     for (int i = 0; i < 16; ++i) { const int kk = 4 * i + kr; f32x4 v = *(const f32x4*)(W + (size_t)(k0 + kk) * ldn + col0 + n4); if (g) v = v * g[k0 + kk];
;         LAS float* d = scr + kk * 65 + n4; d[0] = v.x; d[1] = v.y; d[2] = v.z; d[3] = v.w; }
;     LDS_WAIT(); asm volatile("" ::: "memory");
.Ltr_gdone:
	global_load_dwordx4 v[146:149], v232, s[2:3]
	v_add_u32_e32 v232, s38, v232
	global_load_dwordx4 v[150:153], v232, s[2:3]
	v_add_u32_e32 v232, s38, v232
	global_load_dwordx4 v[154:157], v232, s[2:3]
	v_add_u32_e32 v232, s38, v232
	global_load_dwordx4 v[158:161], v232, s[2:3]
	v_add_u32_e32 v232, s38, v232
	global_load_dwordx4 v[162:165], v232, s[2:3]
	v_add_u32_e32 v232, s38, v232
	global_load_dwordx4 v[166:169], v232, s[2:3]
	v_add_u32_e32 v232, s38, v232
	global_load_dwordx4 v[170:173], v232, s[2:3]
	v_add_u32_e32 v232, s38, v232
	global_load_dwordx4 v[174:177], v232, s[2:3]
	v_add_u32_e32 v232, s38, v232
	global_load_dwordx4 v[178:181], v232, s[2:3]
	v_add_u32_e32 v232, s38, v232
	global_load_dwordx4 v[182:185], v232, s[2:3]
	v_add_u32_e32 v232, s38, v232
	global_load_dwordx4 v[186:189], v232, s[2:3]
	v_add_u32_e32 v232, s38, v232
	global_load_dwordx4 v[190:193], v232, s[2:3]
	v_add_u32_e32 v232, s38, v232
	global_load_dwordx4 v[114:117], v232, s[2:3]
	v_add_u32_e32 v232, s38, v232
	global_load_dwordx4 v[118:121], v232, s[2:3]
	v_add_u32_e32 v232, s38, v232
	global_load_dwordx4 v[122:125], v232, s[2:3]
	v_add_u32_e32 v232, s38, v232
	global_load_dwordx4 v[126:129], v232, s[2:3]
	s_waitcnt vmcnt(15)
	v_mul_f32_e32 v146, v210, v146
	v_mul_f32_e32 v147, v210, v147
	v_mul_f32_e32 v148, v210, v148
	v_mul_f32_e32 v149, v210, v149
	ds_write2_b32 v242, v146, v147 offset1:1
	ds_write2_b32 v242, v148, v149 offset0:2 offset1:3
	v_add_u32_e32 v242, 0x410, v242
	s_waitcnt vmcnt(14)
	v_mul_f32_e32 v150, v211, v150
	v_mul_f32_e32 v151, v211, v151
	v_mul_f32_e32 v152, v211, v152
	v_mul_f32_e32 v153, v211, v153
	ds_write2_b32 v242, v150, v151 offset1:1
	ds_write2_b32 v242, v152, v153 offset0:2 offset1:3
	v_add_u32_e32 v242, 0x410, v242
	s_waitcnt vmcnt(13)
	v_mul_f32_e32 v154, v212, v154
	v_mul_f32_e32 v155, v212, v155
	v_mul_f32_e32 v156, v212, v156
	v_mul_f32_e32 v157, v212, v157
	ds_write2_b32 v242, v154, v155 offset1:1
	ds_write2_b32 v242, v156, v157 offset0:2 offset1:3
	v_add_u32_e32 v242, 0x410, v242
	s_waitcnt vmcnt(12)
	v_mul_f32_e32 v158, v213, v158
	v_mul_f32_e32 v159, v213, v159
	v_mul_f32_e32 v160, v213, v160
	v_mul_f32_e32 v161, v213, v161
	ds_write2_b32 v242, v158, v159 offset1:1
	ds_write2_b32 v242, v160, v161 offset0:2 offset1:3
	v_add_u32_e32 v242, 0x410, v242
	s_waitcnt vmcnt(11)
	v_mul_f32_e32 v162, v214, v162
	v_mul_f32_e32 v163, v214, v163
	v_mul_f32_e32 v164, v214, v164
	v_mul_f32_e32 v165, v214, v165
	ds_write2_b32 v242, v162, v163 offset1:1
	ds_write2_b32 v242, v164, v165 offset0:2 offset1:3
	v_add_u32_e32 v242, 0x410, v242
	s_waitcnt vmcnt(10)
	v_mul_f32_e32 v166, v215, v166
	v_mul_f32_e32 v167, v215, v167
	v_mul_f32_e32 v168, v215, v168
	v_mul_f32_e32 v169, v215, v169
	ds_write2_b32 v242, v166, v167 offset1:1
	ds_write2_b32 v242, v168, v169 offset0:2 offset1:3
	v_add_u32_e32 v242, 0x410, v242
	s_waitcnt vmcnt(9)
	v_mul_f32_e32 v170, v216, v170
	v_mul_f32_e32 v171, v216, v171
	v_mul_f32_e32 v172, v216, v172
	v_mul_f32_e32 v173, v216, v173
	ds_write2_b32 v242, v170, v171 offset1:1
	ds_write2_b32 v242, v172, v173 offset0:2 offset1:3
	v_add_u32_e32 v242, 0x410, v242
	s_waitcnt vmcnt(8)
	v_mul_f32_e32 v174, v217, v174
	v_mul_f32_e32 v175, v217, v175
	v_mul_f32_e32 v176, v217, v176
	v_mul_f32_e32 v177, v217, v177
	ds_write2_b32 v242, v174, v175 offset1:1
	ds_write2_b32 v242, v176, v177 offset0:2 offset1:3
	v_add_u32_e32 v242, 0x410, v242
	s_waitcnt vmcnt(7)
	v_mul_f32_e32 v178, v218, v178
	v_mul_f32_e32 v179, v218, v179
	v_mul_f32_e32 v180, v218, v180
	v_mul_f32_e32 v181, v218, v181
	ds_write2_b32 v242, v178, v179 offset1:1
	ds_write2_b32 v242, v180, v181 offset0:2 offset1:3
	v_add_u32_e32 v242, 0x410, v242
	s_waitcnt vmcnt(6)
	v_mul_f32_e32 v182, v219, v182
	v_mul_f32_e32 v183, v219, v183
	v_mul_f32_e32 v184, v219, v184
	v_mul_f32_e32 v185, v219, v185
	ds_write2_b32 v242, v182, v183 offset1:1
	ds_write2_b32 v242, v184, v185 offset0:2 offset1:3
	v_add_u32_e32 v242, 0x410, v242
	s_waitcnt vmcnt(5)
	v_mul_f32_e32 v186, v220, v186
	v_mul_f32_e32 v187, v220, v187
	v_mul_f32_e32 v188, v220, v188
	v_mul_f32_e32 v189, v220, v189
	ds_write2_b32 v242, v186, v187 offset1:1
	ds_write2_b32 v242, v188, v189 offset0:2 offset1:3
	v_add_u32_e32 v242, 0x410, v242
	s_waitcnt vmcnt(4)
	v_mul_f32_e32 v190, v221, v190
	v_mul_f32_e32 v191, v221, v191
	v_mul_f32_e32 v192, v221, v192
	v_mul_f32_e32 v193, v221, v193
	ds_write2_b32 v242, v190, v191 offset1:1
	ds_write2_b32 v242, v192, v193 offset0:2 offset1:3
	v_add_u32_e32 v242, 0x410, v242
	s_waitcnt vmcnt(3)
	v_mul_f32_e32 v114, v222, v114
	v_mul_f32_e32 v115, v222, v115
	v_mul_f32_e32 v116, v222, v116
	v_mul_f32_e32 v117, v222, v117
	ds_write2_b32 v242, v114, v115 offset1:1
	ds_write2_b32 v242, v116, v117 offset0:2 offset1:3
	v_add_u32_e32 v242, 0x410, v242
	s_waitcnt vmcnt(2)
	v_mul_f32_e32 v118, v223, v118
	v_mul_f32_e32 v119, v223, v119
	v_mul_f32_e32 v120, v223, v120
	v_mul_f32_e32 v121, v223, v121
	ds_write2_b32 v242, v118, v119 offset1:1
	ds_write2_b32 v242, v120, v121 offset0:2 offset1:3
	v_add_u32_e32 v242, 0x410, v242
	s_waitcnt vmcnt(1)
	v_mul_f32_e32 v122, v230, v122
	v_mul_f32_e32 v123, v230, v123
	v_mul_f32_e32 v124, v230, v124
	v_mul_f32_e32 v125, v230, v125
	ds_write2_b32 v242, v122, v123 offset1:1
	ds_write2_b32 v242, v124, v125 offset0:2 offset1:3
	v_add_u32_e32 v242, 0x410, v242
	s_waitcnt vmcnt(0)
	v_mul_f32_e32 v126, v231, v126
	v_mul_f32_e32 v127, v231, v127
	v_mul_f32_e32 v128, v231, v128
	v_mul_f32_e32 v129, v231, v129
	ds_write2_b32 v242, v126, v127 offset1:1
	ds_write2_b32 v242, v128, v129 offset0:2 offset1:3
	s_waitcnt lgkmcnt(0)
; #define LAS __attribute__((address_space(3)))
; __device__ __forceinline__ unsigned pk2(float lo, float hi) { return f2bf(lo) | (f2bf(hi) << 16); }
; #define LDS_WAIT() asm volatile("s_waitcnt lgkmcnt(0)" ::: "memory")
; __device__ __forceinline__ void tr_item(const float* W, int ldn, int col0, int k0, const float* g, bf16* WT, int ldk, int drow0, LAS float* scr, int lane) {
;     ...
;     LDS_WAIT(); asm volatile("" ::: "memory");
;     const int c = lane & 7;
; #pragma unroll
;     for (int j = 0; j < 8; ++j) { const int n = (lane >> 3) + 8 * j; const LAS float* s = scr + (8 * c) * 65 + n;
;         v4u o; o.x = pk2(s[0 * 65], s[1 * 65]); o.y = pk2(s[2 * 65], s[3 * 65]); o.z = pk2(s[4 * 65], s[5 * 65]); o.w = pk2(s[6 * 65], s[7 * 65]);
;         *(v4u*)(WT + (size_t)(drow0 + n) * ldk + k0 + 8 * c) = o; }
;     LDS_WAIT(); asm volatile("" ::: "memory");
; __device__ __forceinline__ void phase_prologue(PtrTab TB, unsigned char* ws, float* xout, int l, LAS unsigned char* lds, int gw, int NGW, int lane, int wave) {
;     ...
;     { bf16* UaT = (bf16*)(ws + WS_UA);
;       for (int it = gw; it < 4 * 16 * 16; it += NGW) { const int g = it >> 8, nblk = (it >> 4) & 15, c0 = (it & 15) * 8, n = nblk * 64 + lane;
;           const float* wp = wpool + ((size_t)g * 128 + c0) * 128; const float* sc = psc + g * 128; const float* ua = wua + (size_t)(g * 128) * D + n; float acc[8];
	ds_read2_b32 v[146:147], v62 offset0:0 offset1:65
	ds_read2_b32 v[148:149], v62 offset0:130 offset1:195
	ds_read2_b32 v[150:151], v243 offset0:4 offset1:69
	ds_read2_b32 v[152:153], v243 offset0:134 offset1:199
	ds_read2_b32 v[154:155], v62 offset0:8 offset1:73
	ds_read2_b32 v[156:157], v62 offset0:138 offset1:203
	ds_read2_b32 v[158:159], v243 offset0:12 offset1:77
	ds_read2_b32 v[160:161], v243 offset0:142 offset1:207
	ds_read2_b32 v[162:163], v62 offset0:16 offset1:81
	ds_read2_b32 v[164:165], v62 offset0:146 offset1:211
	ds_read2_b32 v[166:167], v243 offset0:20 offset1:85
	ds_read2_b32 v[168:169], v243 offset0:150 offset1:215
	s_waitcnt lgkmcnt(8)
	v_cvt_pk_bf16_f32 v146, v146, v147
	v_cvt_pk_bf16_f32 v147, v148, v149
	v_cvt_pk_bf16_f32 v148, v150, v151
	v_cvt_pk_bf16_f32 v149, v152, v153
	global_store_dwordx4 v244, v[146:149], s[24:25]
	ds_read2_b32 v[170:171], v62 offset0:24 offset1:89
	ds_read2_b32 v[172:173], v62 offset0:154 offset1:219
	ds_read2_b32 v[174:175], v243 offset0:28 offset1:93
	ds_read2_b32 v[176:177], v243 offset0:158 offset1:223
	s_waitcnt lgkmcnt(8)
	v_cvt_pk_bf16_f32 v154, v154, v155
	v_cvt_pk_bf16_f32 v155, v156, v157
	v_cvt_pk_bf16_f32 v156, v158, v159
	v_cvt_pk_bf16_f32 v157, v160, v161
	global_store_dwordx4 v245, v[154:157], s[24:25]
	ds_read2_b32 v[178:179], v62 offset0:32 offset1:97
	ds_read2_b32 v[180:181], v62 offset0:162 offset1:227
	ds_read2_b32 v[182:183], v243 offset0:36 offset1:101
	ds_read2_b32 v[184:185], v243 offset0:166 offset1:231
	s_waitcnt lgkmcnt(8)
	v_cvt_pk_bf16_f32 v162, v162, v163
	v_cvt_pk_bf16_f32 v163, v164, v165
	v_cvt_pk_bf16_f32 v164, v166, v167
	v_cvt_pk_bf16_f32 v165, v168, v169
	global_store_dwordx4 v246, v[162:165], s[24:25]
	ds_read2_b32 v[186:187], v62 offset0:40 offset1:105
	ds_read2_b32 v[188:189], v62 offset0:170 offset1:235
	ds_read2_b32 v[190:191], v243 offset0:44 offset1:109
	ds_read2_b32 v[192:193], v243 offset0:174 offset1:239
	s_waitcnt lgkmcnt(8)
	v_cvt_pk_bf16_f32 v170, v170, v171
	v_cvt_pk_bf16_f32 v171, v172, v173
	v_cvt_pk_bf16_f32 v172, v174, v175
	v_cvt_pk_bf16_f32 v173, v176, v177
	global_store_dwordx4 v247, v[170:173], s[24:25]
	ds_read2_b32 v[114:115], v62 offset0:48 offset1:113
	ds_read2_b32 v[116:117], v62 offset0:178 offset1:243
	ds_read2_b32 v[118:119], v243 offset0:52 offset1:117
	ds_read2_b32 v[120:121], v243 offset0:182 offset1:247
	s_waitcnt lgkmcnt(8)
	v_cvt_pk_bf16_f32 v178, v178, v179
	v_cvt_pk_bf16_f32 v179, v180, v181
	v_cvt_pk_bf16_f32 v180, v182, v183
	v_cvt_pk_bf16_f32 v181, v184, v185
	global_store_dwordx4 v248, v[178:181], s[24:25]
	ds_read2_b32 v[122:123], v62 offset0:56 offset1:121
	ds_read2_b32 v[124:125], v62 offset0:186 offset1:251
	ds_read2_b32 v[126:127], v243 offset0:60 offset1:125
	ds_read2_b32 v[128:129], v243 offset0:190 offset1:255
	s_waitcnt lgkmcnt(8)
	v_cvt_pk_bf16_f32 v186, v186, v187
	v_cvt_pk_bf16_f32 v187, v188, v189
	v_cvt_pk_bf16_f32 v188, v190, v191
	v_cvt_pk_bf16_f32 v189, v192, v193
	global_store_dwordx4 v249, v[186:189], s[24:25]
	s_waitcnt lgkmcnt(4)
	v_cvt_pk_bf16_f32 v114, v114, v115
	v_cvt_pk_bf16_f32 v115, v116, v117
	v_cvt_pk_bf16_f32 v116, v118, v119
	v_cvt_pk_bf16_f32 v117, v120, v121
	global_store_dwordx4 v250, v[114:117], s[24:25]
	s_waitcnt lgkmcnt(0)
	v_cvt_pk_bf16_f32 v122, v122, v123
	v_cvt_pk_bf16_f32 v123, v124, v125
	v_cvt_pk_bf16_f32 v124, v126, v127
	v_cvt_pk_bf16_f32 v125, v128, v129
	global_store_dwordx4 v251, v[122:125], s[24:25]
	s_cmpk_eq_u32 s8, 0x800
	s_cbranch_scc0 .LBB0_22
	s_cmpk_lg_u32 s94, 0
	s_cbranch_scc1 .Ltr_l1
	s_cmpk_ge_u32 s71, 0x1800
	s_cbranch_scc1 .Ltr_hi
	s_addk_i32 s71, 0x800
	s_cmpk_lt_u32 s71, 0x1800
	s_cbranch_scc1 .LBB0_23
	s_cmpk_lt_u32 s10, 0x400
	s_cbranch_scc1 .LBB0_214
	s_sub_u32 s71, s71, 0x400
	s_branch .LBB0_23
.Ltr_hi:
	s_addk_i32 s71, 0x400
	s_cmpk_gt_i32 s71, 0x1e3f
	s_cbranch_scc1 .LBB0_214
	s_branch .LBB0_23
.Ltr_l1:
	s_addk_i32 s71, 0x800
	s_cmpk_gt_i32 s71, 0x1e3f
	s_cbranch_scc1 .LBB0_214
	s_branch .LBB0_23
.LBB0_214:
	s_cmpk_gt_i32 s10, 0x3ff
	s_cbranch_scc1 .LBB0_219
	s_load_dwordx4 s[0:3], s[100:101], 0x48
	s_load_dwordx2 s[14:15], s[100:101], 0x58
	v_lshrrev_b32_e32 v41, 6, v197
	v_mul_u32_u24_e32 v41, 0x4100, v41
	v_lshlrev_b32_e32 v40, 2, v52
	v_lshlrev_b32_e32 v42, 4, v52
	v_lshlrev_b32_e32 v45, 10, v52
	v_add_u32_e32 v44, v41, v42
	s_mov_b32 s5, s10
; __device__ __forceinline__ void phase_prologue(PtrTab TB, unsigned char* ws, float* xout, int l, LAS unsigned char* lds, int gw, int NGW, int lane, int wave) {
;     ...
;       for (int it = gw; it < 4 * 16 * 16; it += NGW) { const int g = it >> 8, nblk = (it >> 4) & 15, c0 = (it & 15) * 8, n = nblk * 64 + lane;
;           const float* wp = wpool + ((size_t)g * 128 + c0) * 128; const float* sc = psc + g * 128; const float* ua = wua + (size_t)(g * 128) * D + n; float acc[8];
; #pragma unroll
;           for (int c = 0; c < 8; ++c) acc[c] = 0.f;
; #pragma unroll 16
;           for (int j = 0; j < 128; ++j) { const float u = ua[(size_t)j * D] * sc[j];
; #pragma unroll
;               for (int c = 0; c < 8; ++c) acc[c] += wp[c * 128 + j] * u; }
.LUa_item:
	s_lshr_b32 s6, s5, 8
	s_bfe_u32 s9, s5, 0x40004
	s_and_b32 s13, s5, 15
	s_lshl_b32 s13, s13, 3
	s_lshl_b32 s18, s94, 9
	s_lshl_b32 s20, s6, 7
	s_add_u32 s18, s18, s20
	s_add_u32 s21, s18, s13
	s_lshl_b32 s21, s21, 9
	s_waitcnt lgkmcnt(0)
	s_add_u32 s24, s0, s21
	s_addc_u32 s25, s1, 0
	s_lshl_b32 s21, s18, 2
	s_add_u32 s38, s2, s21
	s_addc_u32 s39, s3, 0
	s_lshl_b32 s21, s18, 12
	s_lshl_b32 s23, s9, 8
	s_add_u32 s21, s21, s23
	s_add_u32 s44, s14, s21
	s_addc_u32 s45, s15, 0
	global_load_dwordx4 v[146:149], v42, s[24:25]
	global_load_dwordx4 v[150:153], v42, s[24:25] offset:1024
	global_load_dwordx4 v[154:157], v42, s[24:25] offset:2048
	global_load_dwordx4 v[158:161], v42, s[24:25] offset:3072
	v_cmp_gt_u32_e32 vcc, 32, v52
	s_and_saveexec_b64 s[60:61], vcc
	global_load_dwordx4 v[162:165], v42, s[38:39]
	s_or_b64 exec, exec, s[60:61]
	global_load_dword v242, v40, s[44:45]
	s_add_u32 s44, s44, 0x1000
	s_addc_u32 s45, s45, 0
	global_load_dword v243, v40, s[44:45]
	s_add_u32 s44, s44, 0x1000
	s_addc_u32 s45, s45, 0
	global_load_dword v244, v40, s[44:45]
	s_add_u32 s44, s44, 0x1000
	s_addc_u32 s45, s45, 0
	global_load_dword v245, v40, s[44:45]
	s_add_u32 s44, s44, 0x1000
	s_addc_u32 s45, s45, 0
	global_load_dword v246, v40, s[44:45]
	s_add_u32 s44, s44, 0x1000
	s_addc_u32 s45, s45, 0
	global_load_dword v247, v40, s[44:45]
	s_add_u32 s44, s44, 0x1000
	s_addc_u32 s45, s45, 0
	global_load_dword v248, v40, s[44:45]
	s_add_u32 s44, s44, 0x1000
	s_addc_u32 s45, s45, 0
	global_load_dword v249, v40, s[44:45]
	s_add_u32 s44, s44, 0x1000
	s_addc_u32 s45, s45, 0
	global_load_dword v250, v40, s[44:45]
	s_add_u32 s44, s44, 0x1000
	s_addc_u32 s45, s45, 0
	global_load_dword v251, v40, s[44:45]
	s_add_u32 s44, s44, 0x1000
	s_addc_u32 s45, s45, 0
	global_load_dword v252, v40, s[44:45]
	s_add_u32 s44, s44, 0x1000
	s_addc_u32 s45, s45, 0
	global_load_dword v253, v40, s[44:45]
	s_add_u32 s44, s44, 0x1000
	s_addc_u32 s45, s45, 0
	global_load_dword v230, v40, s[44:45]
	s_add_u32 s44, s44, 0x1000
	s_addc_u32 s45, s45, 0
	global_load_dword v231, v40, s[44:45]
	s_add_u32 s44, s44, 0x1000
	s_addc_u32 s45, s45, 0
	global_load_dword v232, v40, s[44:45]
	s_add_u32 s44, s44, 0x1000
	s_addc_u32 s45, s45, 0
	global_load_dword v233, v40, s[44:45]
	s_add_u32 s44, s44, 0x1000
	s_addc_u32 s45, s45, 0
	global_load_dword v222, v40, s[44:45]
	s_add_u32 s44, s44, 0x1000
	s_addc_u32 s45, s45, 0
	global_load_dword v223, v40, s[44:45]
	s_add_u32 s44, s44, 0x1000
	s_addc_u32 s45, s45, 0
	global_load_dword v134, v40, s[44:45]
	s_add_u32 s44, s44, 0x1000
	s_addc_u32 s45, s45, 0
	global_load_dword v135, v40, s[44:45]
	s_add_u32 s44, s44, 0x1000
	s_addc_u32 s45, s45, 0
	global_load_dword v136, v40, s[44:45]
	s_add_u32 s44, s44, 0x1000
	s_addc_u32 s45, s45, 0
	global_load_dword v194, v40, s[44:45]
	s_add_u32 s44, s44, 0x1000
	s_addc_u32 s45, s45, 0
	global_load_dword v195, v40, s[44:45]
	s_add_u32 s44, s44, 0x1000
	s_addc_u32 s45, s45, 0
	global_load_dword v24, v40, s[44:45]
	s_add_u32 s44, s44, 0x1000
	s_addc_u32 s45, s45, 0
	global_load_dword v25, v40, s[44:45]
	s_add_u32 s44, s44, 0x1000
	s_addc_u32 s45, s45, 0
	global_load_dword v26, v40, s[44:45]
	s_add_u32 s44, s44, 0x1000
	s_addc_u32 s45, s45, 0
	global_load_dword v27, v40, s[44:45]
	s_add_u32 s44, s44, 0x1000
	s_addc_u32 s45, s45, 0
	global_load_dword v29, v40, s[44:45]
	s_add_u32 s44, s44, 0x1000
	s_addc_u32 s45, s45, 0
	global_load_dword v30, v40, s[44:45]
	s_add_u32 s44, s44, 0x1000
	s_addc_u32 s45, s45, 0
	global_load_dword v31, v40, s[44:45]
	s_add_u32 s44, s44, 0x1000
	s_addc_u32 s45, s45, 0
	global_load_dword v32, v40, s[44:45]
	s_add_u32 s44, s44, 0x1000
	s_addc_u32 s45, s45, 0
	global_load_dword v33, v40, s[44:45]
	s_add_u32 s44, s44, 0x1000
	s_addc_u32 s45, s45, 0
	v_mov_b32_e32 v210, 0
	v_mov_b32_e32 v211, 0
	v_mov_b32_e32 v212, 0
	v_mov_b32_e32 v213, 0
	v_mov_b32_e32 v214, 0
	v_mov_b32_e32 v215, 0
	v_mov_b32_e32 v216, 0
	v_mov_b32_e32 v217, 0
	s_waitcnt vmcnt(32)
	ds_write_b128 v44, v[146:149]
	ds_write_b128 v44, v[150:153] offset:1024
	ds_write_b128 v44, v[154:157] offset:2048
	ds_write_b128 v44, v[158:161] offset:3072
	s_and_saveexec_b64 s[60:61], vcc
	ds_write_b128 v44, v[162:165] offset:4096
	s_or_b64 exec, exec, s[60:61]
	s_waitcnt lgkmcnt(0)
	ds_read_b128 v[146:149], v41 offset:0
	ds_read_b128 v[150:153], v41 offset:512
	ds_read_b128 v[154:157], v41 offset:1024
	ds_read_b128 v[158:161], v41 offset:1536
	ds_read_b128 v[162:165], v41 offset:2048
	ds_read_b128 v[166:169], v41 offset:2560
	ds_read_b128 v[170:173], v41 offset:3072
	ds_read_b128 v[174:177], v41 offset:3584
	ds_read_b128 v[218:221], v41 offset:4096
	ds_read_b128 v[178:181], v41 offset:16
	ds_read_b128 v[182:185], v41 offset:528
	ds_read_b128 v[186:189], v41 offset:1040
	ds_read_b128 v[190:193], v41 offset:1552
	ds_read_b128 v[114:117], v41 offset:2064
	ds_read_b128 v[118:121], v41 offset:2576
	ds_read_b128 v[122:125], v41 offset:3088
	ds_read_b128 v[126:129], v41 offset:3600
	ds_read_b128 v[130:133], v41 offset:4112
	s_waitcnt lgkmcnt(9)
	s_waitcnt vmcnt(28)
; __device__ __forceinline__ void phase_prologue(PtrTab TB, unsigned char* ws, float* xout, int l, LAS unsigned char* lds, int gw, int NGW, int lane, int wave) {
;     ...
; #pragma unroll 16
;           for (int j = 0; j < 128; ++j) { const float u = ua[(size_t)j * D] * sc[j];
; #pragma unroll
;               for (int c = 0; c < 8; ++c) acc[c] += wp[c * 128 + j] * u; }
	v_mul_f32_e32 v242, v242, v218
	v_fmac_f32_e32 v210, v146, v242
	v_fmac_f32_e32 v211, v150, v242
	v_fmac_f32_e32 v212, v154, v242
	v_fmac_f32_e32 v213, v158, v242
	v_fmac_f32_e32 v214, v162, v242
	v_fmac_f32_e32 v215, v166, v242
	v_fmac_f32_e32 v216, v170, v242
	v_fmac_f32_e32 v217, v174, v242
	v_mul_f32_e32 v243, v243, v219
	v_fmac_f32_e32 v210, v147, v243
	v_fmac_f32_e32 v211, v151, v243
	v_fmac_f32_e32 v212, v155, v243
	v_fmac_f32_e32 v213, v159, v243
	v_fmac_f32_e32 v214, v163, v243
	v_fmac_f32_e32 v215, v167, v243
	v_fmac_f32_e32 v216, v171, v243
	v_fmac_f32_e32 v217, v175, v243
	v_mul_f32_e32 v244, v244, v220
	v_fmac_f32_e32 v210, v148, v244
	v_fmac_f32_e32 v211, v152, v244
	v_fmac_f32_e32 v212, v156, v244
	v_fmac_f32_e32 v213, v160, v244
	v_fmac_f32_e32 v214, v164, v244
	v_fmac_f32_e32 v215, v168, v244
	v_fmac_f32_e32 v216, v172, v244
	v_fmac_f32_e32 v217, v176, v244
	v_mul_f32_e32 v245, v245, v221
	v_fmac_f32_e32 v210, v149, v245
	v_fmac_f32_e32 v211, v153, v245
	v_fmac_f32_e32 v212, v157, v245
	v_fmac_f32_e32 v213, v161, v245
	v_fmac_f32_e32 v214, v165, v245
	v_fmac_f32_e32 v215, v169, v245
	v_fmac_f32_e32 v216, v173, v245
	v_fmac_f32_e32 v217, v177, v245
	ds_read_b128 v[146:149], v41 offset:32
	ds_read_b128 v[150:153], v41 offset:544
	ds_read_b128 v[154:157], v41 offset:1056
	ds_read_b128 v[158:161], v41 offset:1568
	ds_read_b128 v[162:165], v41 offset:2080
	ds_read_b128 v[166:169], v41 offset:2592
	ds_read_b128 v[170:173], v41 offset:3104
	ds_read_b128 v[174:177], v41 offset:3616
	ds_read_b128 v[218:221], v41 offset:4128
	global_load_dword v242, v40, s[44:45]
	s_add_u32 s44, s44, 0x1000
	s_addc_u32 s45, s45, 0
	global_load_dword v243, v40, s[44:45]
	s_add_u32 s44, s44, 0x1000
	s_addc_u32 s45, s45, 0
	global_load_dword v244, v40, s[44:45]
	s_add_u32 s44, s44, 0x1000
	s_addc_u32 s45, s45, 0
	global_load_dword v245, v40, s[44:45]
	s_add_u32 s44, s44, 0x1000
	s_addc_u32 s45, s45, 0
	s_waitcnt lgkmcnt(9)
	s_waitcnt vmcnt(28)
	v_mul_f32_e32 v246, v246, v130
	v_fmac_f32_e32 v210, v178, v246
	v_fmac_f32_e32 v211, v182, v246
	v_fmac_f32_e32 v212, v186, v246
	v_fmac_f32_e32 v213, v190, v246
	v_fmac_f32_e32 v214, v114, v246
	v_fmac_f32_e32 v215, v118, v246
	v_fmac_f32_e32 v216, v122, v246
	v_fmac_f32_e32 v217, v126, v246
	v_mul_f32_e32 v247, v247, v131
	v_fmac_f32_e32 v210, v179, v247
	v_fmac_f32_e32 v211, v183, v247
	v_fmac_f32_e32 v212, v187, v247
	v_fmac_f32_e32 v213, v191, v247
	v_fmac_f32_e32 v214, v115, v247
	v_fmac_f32_e32 v215, v119, v247
	v_fmac_f32_e32 v216, v123, v247
	v_fmac_f32_e32 v217, v127, v247
	v_mul_f32_e32 v248, v248, v132
	v_fmac_f32_e32 v210, v180, v248
	v_fmac_f32_e32 v211, v184, v248
	v_fmac_f32_e32 v212, v188, v248
	v_fmac_f32_e32 v213, v192, v248
	v_fmac_f32_e32 v214, v116, v248
	v_fmac_f32_e32 v215, v120, v248
	v_fmac_f32_e32 v216, v124, v248
	v_fmac_f32_e32 v217, v128, v248
	v_mul_f32_e32 v249, v249, v133
	v_fmac_f32_e32 v210, v181, v249
	v_fmac_f32_e32 v211, v185, v249
	v_fmac_f32_e32 v212, v189, v249
	v_fmac_f32_e32 v213, v193, v249
	v_fmac_f32_e32 v214, v117, v249
	v_fmac_f32_e32 v215, v121, v249
	v_fmac_f32_e32 v216, v125, v249
	v_fmac_f32_e32 v217, v129, v249
	ds_read_b128 v[178:181], v41 offset:48
	ds_read_b128 v[182:185], v41 offset:560
	ds_read_b128 v[186:189], v41 offset:1072
	ds_read_b128 v[190:193], v41 offset:1584
	ds_read_b128 v[114:117], v41 offset:2096
	ds_read_b128 v[118:121], v41 offset:2608
	ds_read_b128 v[122:125], v41 offset:3120
	ds_read_b128 v[126:129], v41 offset:3632
	ds_read_b128 v[130:133], v41 offset:4144
	global_load_dword v246, v40, s[44:45]
	s_add_u32 s44, s44, 0x1000
	s_addc_u32 s45, s45, 0
	global_load_dword v247, v40, s[44:45]
	s_add_u32 s44, s44, 0x1000
	s_addc_u32 s45, s45, 0
	global_load_dword v248, v40, s[44:45]
	s_add_u32 s44, s44, 0x1000
	s_addc_u32 s45, s45, 0
	global_load_dword v249, v40, s[44:45]
	s_add_u32 s44, s44, 0x1000
	s_addc_u32 s45, s45, 0
	s_waitcnt lgkmcnt(9)
	s_waitcnt vmcnt(28)
	v_mul_f32_e32 v250, v250, v218
	v_fmac_f32_e32 v210, v146, v250
	v_fmac_f32_e32 v211, v150, v250
	v_fmac_f32_e32 v212, v154, v250
	v_fmac_f32_e32 v213, v158, v250
	v_fmac_f32_e32 v214, v162, v250
	v_fmac_f32_e32 v215, v166, v250
	v_fmac_f32_e32 v216, v170, v250
	v_fmac_f32_e32 v217, v174, v250
	v_mul_f32_e32 v251, v251, v219
	v_fmac_f32_e32 v210, v147, v251
	v_fmac_f32_e32 v211, v151, v251
	v_fmac_f32_e32 v212, v155, v251
	v_fmac_f32_e32 v213, v159, v251
	v_fmac_f32_e32 v214, v163, v251
	v_fmac_f32_e32 v215, v167, v251
	v_fmac_f32_e32 v216, v171, v251
	v_fmac_f32_e32 v217, v175, v251
	v_mul_f32_e32 v252, v252, v220
	v_fmac_f32_e32 v210, v148, v252
	v_fmac_f32_e32 v211, v152, v252
	v_fmac_f32_e32 v212, v156, v252
	v_fmac_f32_e32 v213, v160, v252
	v_fmac_f32_e32 v214, v164, v252
	v_fmac_f32_e32 v215, v168, v252
	v_fmac_f32_e32 v216, v172, v252
	v_fmac_f32_e32 v217, v176, v252
	v_mul_f32_e32 v253, v253, v221
	v_fmac_f32_e32 v210, v149, v253
	v_fmac_f32_e32 v211, v153, v253
	v_fmac_f32_e32 v212, v157, v253
	v_fmac_f32_e32 v213, v161, v253
	v_fmac_f32_e32 v214, v165, v253
	v_fmac_f32_e32 v215, v169, v253
	v_fmac_f32_e32 v216, v173, v253
	v_fmac_f32_e32 v217, v177, v253
	ds_read_b128 v[146:149], v41 offset:64
	ds_read_b128 v[150:153], v41 offset:576
	ds_read_b128 v[154:157], v41 offset:1088
	ds_read_b128 v[158:161], v41 offset:1600
	ds_read_b128 v[162:165], v41 offset:2112
	ds_read_b128 v[166:169], v41 offset:2624
	ds_read_b128 v[170:173], v41 offset:3136
	ds_read_b128 v[174:177], v41 offset:3648
	ds_read_b128 v[218:221], v41 offset:4160
	global_load_dword v250, v40, s[44:45]
	s_add_u32 s44, s44, 0x1000
	s_addc_u32 s45, s45, 0
	global_load_dword v251, v40, s[44:45]
	s_add_u32 s44, s44, 0x1000
	s_addc_u32 s45, s45, 0
	global_load_dword v252, v40, s[44:45]
	s_add_u32 s44, s44, 0x1000
	s_addc_u32 s45, s45, 0
	global_load_dword v253, v40, s[44:45]
	s_add_u32 s44, s44, 0x1000
	s_addc_u32 s45, s45, 0
	s_waitcnt lgkmcnt(9)
; __device__ __forceinline__ void phase_prologue(PtrTab TB, unsigned char* ws, float* xout, int l, LAS unsigned char* lds, int gw, int NGW, int lane, int wave) {
;     ...
; #pragma unroll 16
;           for (int j = 0; j < 128; ++j) { const float u = ua[(size_t)j * D] * sc[j];
; #pragma unroll
;               for (int c = 0; c < 8; ++c) acc[c] += wp[c * 128 + j] * u; }
	s_waitcnt vmcnt(28)
	v_mul_f32_e32 v230, v230, v130
	v_fmac_f32_e32 v210, v178, v230
	v_fmac_f32_e32 v211, v182, v230
	v_fmac_f32_e32 v212, v186, v230
	v_fmac_f32_e32 v213, v190, v230
	v_fmac_f32_e32 v214, v114, v230
	v_fmac_f32_e32 v215, v118, v230
	v_fmac_f32_e32 v216, v122, v230
	v_fmac_f32_e32 v217, v126, v230
	v_mul_f32_e32 v231, v231, v131
	v_fmac_f32_e32 v210, v179, v231
	v_fmac_f32_e32 v211, v183, v231
	v_fmac_f32_e32 v212, v187, v231
	v_fmac_f32_e32 v213, v191, v231
	v_fmac_f32_e32 v214, v115, v231
	v_fmac_f32_e32 v215, v119, v231
	v_fmac_f32_e32 v216, v123, v231
	v_fmac_f32_e32 v217, v127, v231
	v_mul_f32_e32 v232, v232, v132
	v_fmac_f32_e32 v210, v180, v232
	v_fmac_f32_e32 v211, v184, v232
	v_fmac_f32_e32 v212, v188, v232
	v_fmac_f32_e32 v213, v192, v232
	v_fmac_f32_e32 v214, v116, v232
	v_fmac_f32_e32 v215, v120, v232
	v_fmac_f32_e32 v216, v124, v232
	v_fmac_f32_e32 v217, v128, v232
	v_mul_f32_e32 v233, v233, v133
	v_fmac_f32_e32 v210, v181, v233
	v_fmac_f32_e32 v211, v185, v233
	v_fmac_f32_e32 v212, v189, v233
	v_fmac_f32_e32 v213, v193, v233
	v_fmac_f32_e32 v214, v117, v233
	v_fmac_f32_e32 v215, v121, v233
	v_fmac_f32_e32 v216, v125, v233
	v_fmac_f32_e32 v217, v129, v233
	ds_read_b128 v[178:181], v41 offset:80
	ds_read_b128 v[182:185], v41 offset:592
	ds_read_b128 v[186:189], v41 offset:1104
	ds_read_b128 v[190:193], v41 offset:1616
	ds_read_b128 v[114:117], v41 offset:2128
	ds_read_b128 v[118:121], v41 offset:2640
	ds_read_b128 v[122:125], v41 offset:3152
	ds_read_b128 v[126:129], v41 offset:3664
	ds_read_b128 v[130:133], v41 offset:4176
	global_load_dword v230, v40, s[44:45]
	s_add_u32 s44, s44, 0x1000
	s_addc_u32 s45, s45, 0
	global_load_dword v231, v40, s[44:45]
	s_add_u32 s44, s44, 0x1000
	s_addc_u32 s45, s45, 0
	global_load_dword v232, v40, s[44:45]
	s_add_u32 s44, s44, 0x1000
	s_addc_u32 s45, s45, 0
	global_load_dword v233, v40, s[44:45]
	s_add_u32 s44, s44, 0x1000
	s_addc_u32 s45, s45, 0
	s_waitcnt lgkmcnt(9)
	s_waitcnt vmcnt(28)
	v_mul_f32_e32 v222, v222, v218
	v_fmac_f32_e32 v210, v146, v222
	v_fmac_f32_e32 v211, v150, v222
	v_fmac_f32_e32 v212, v154, v222
	v_fmac_f32_e32 v213, v158, v222
	v_fmac_f32_e32 v214, v162, v222
	v_fmac_f32_e32 v215, v166, v222
	v_fmac_f32_e32 v216, v170, v222
	v_fmac_f32_e32 v217, v174, v222
	v_mul_f32_e32 v223, v223, v219
	v_fmac_f32_e32 v210, v147, v223
	v_fmac_f32_e32 v211, v151, v223
	v_fmac_f32_e32 v212, v155, v223
	v_fmac_f32_e32 v213, v159, v223
	v_fmac_f32_e32 v214, v163, v223
	v_fmac_f32_e32 v215, v167, v223
	v_fmac_f32_e32 v216, v171, v223
	v_fmac_f32_e32 v217, v175, v223
	v_mul_f32_e32 v134, v134, v220
	v_fmac_f32_e32 v210, v148, v134
	v_fmac_f32_e32 v211, v152, v134
	v_fmac_f32_e32 v212, v156, v134
	v_fmac_f32_e32 v213, v160, v134
	v_fmac_f32_e32 v214, v164, v134
	v_fmac_f32_e32 v215, v168, v134
	v_fmac_f32_e32 v216, v172, v134
	v_fmac_f32_e32 v217, v176, v134
	v_mul_f32_e32 v135, v135, v221
	v_fmac_f32_e32 v210, v149, v135
	v_fmac_f32_e32 v211, v153, v135
	v_fmac_f32_e32 v212, v157, v135
	v_fmac_f32_e32 v213, v161, v135
	v_fmac_f32_e32 v214, v165, v135
	v_fmac_f32_e32 v215, v169, v135
	v_fmac_f32_e32 v216, v173, v135
	v_fmac_f32_e32 v217, v177, v135
	ds_read_b128 v[146:149], v41 offset:96
	ds_read_b128 v[150:153], v41 offset:608
	ds_read_b128 v[154:157], v41 offset:1120
	ds_read_b128 v[158:161], v41 offset:1632
	ds_read_b128 v[162:165], v41 offset:2144
	ds_read_b128 v[166:169], v41 offset:2656
	ds_read_b128 v[170:173], v41 offset:3168
	ds_read_b128 v[174:177], v41 offset:3680
	ds_read_b128 v[218:221], v41 offset:4192
	global_load_dword v222, v40, s[44:45]
	s_add_u32 s44, s44, 0x1000
	s_addc_u32 s45, s45, 0
	global_load_dword v223, v40, s[44:45]
	s_add_u32 s44, s44, 0x1000
	s_addc_u32 s45, s45, 0
	global_load_dword v134, v40, s[44:45]
	s_add_u32 s44, s44, 0x1000
	s_addc_u32 s45, s45, 0
	global_load_dword v135, v40, s[44:45]
	s_add_u32 s44, s44, 0x1000
	s_addc_u32 s45, s45, 0
	s_waitcnt lgkmcnt(9)
	s_waitcnt vmcnt(28)
	v_mul_f32_e32 v136, v136, v130
	v_fmac_f32_e32 v210, v178, v136
	v_fmac_f32_e32 v211, v182, v136
	v_fmac_f32_e32 v212, v186, v136
	v_fmac_f32_e32 v213, v190, v136
	v_fmac_f32_e32 v214, v114, v136
	v_fmac_f32_e32 v215, v118, v136
	v_fmac_f32_e32 v216, v122, v136
	v_fmac_f32_e32 v217, v126, v136
	v_mul_f32_e32 v194, v194, v131
	v_fmac_f32_e32 v210, v179, v194
	v_fmac_f32_e32 v211, v183, v194
	v_fmac_f32_e32 v212, v187, v194
	v_fmac_f32_e32 v213, v191, v194
	v_fmac_f32_e32 v214, v115, v194
	v_fmac_f32_e32 v215, v119, v194
	v_fmac_f32_e32 v216, v123, v194
	v_fmac_f32_e32 v217, v127, v194
	v_mul_f32_e32 v195, v195, v132
	v_fmac_f32_e32 v210, v180, v195
	v_fmac_f32_e32 v211, v184, v195
	v_fmac_f32_e32 v212, v188, v195
	v_fmac_f32_e32 v213, v192, v195
	v_fmac_f32_e32 v214, v116, v195
	v_fmac_f32_e32 v215, v120, v195
	v_fmac_f32_e32 v216, v124, v195
	v_fmac_f32_e32 v217, v128, v195
	v_mul_f32_e32 v24, v24, v133
	v_fmac_f32_e32 v210, v181, v24
	v_fmac_f32_e32 v211, v185, v24
	v_fmac_f32_e32 v212, v189, v24
	v_fmac_f32_e32 v213, v193, v24
	v_fmac_f32_e32 v214, v117, v24
	v_fmac_f32_e32 v215, v121, v24
	v_fmac_f32_e32 v216, v125, v24
	v_fmac_f32_e32 v217, v129, v24
	ds_read_b128 v[178:181], v41 offset:112
	ds_read_b128 v[182:185], v41 offset:624
	ds_read_b128 v[186:189], v41 offset:1136
	ds_read_b128 v[190:193], v41 offset:1648
	ds_read_b128 v[114:117], v41 offset:2160
	ds_read_b128 v[118:121], v41 offset:2672
	ds_read_b128 v[122:125], v41 offset:3184
	ds_read_b128 v[126:129], v41 offset:3696
	ds_read_b128 v[130:133], v41 offset:4208
	global_load_dword v136, v40, s[44:45]
	s_add_u32 s44, s44, 0x1000
	s_addc_u32 s45, s45, 0
	global_load_dword v194, v40, s[44:45]
	s_add_u32 s44, s44, 0x1000
	s_addc_u32 s45, s45, 0
	global_load_dword v195, v40, s[44:45]
	s_add_u32 s44, s44, 0x1000
	s_addc_u32 s45, s45, 0
	global_load_dword v24, v40, s[44:45]
	s_add_u32 s44, s44, 0x1000
	s_addc_u32 s45, s45, 0
	s_waitcnt lgkmcnt(9)
; __device__ __forceinline__ void phase_prologue(PtrTab TB, unsigned char* ws, float* xout, int l, LAS unsigned char* lds, int gw, int NGW, int lane, int wave) {
;     ...
; #pragma unroll 16
;           for (int j = 0; j < 128; ++j) { const float u = ua[(size_t)j * D] * sc[j];
; #pragma unroll
;               for (int c = 0; c < 8; ++c) acc[c] += wp[c * 128 + j] * u; }
	s_waitcnt vmcnt(28)
	v_mul_f32_e32 v25, v25, v218
	v_fmac_f32_e32 v210, v146, v25
	v_fmac_f32_e32 v211, v150, v25
	v_fmac_f32_e32 v212, v154, v25
	v_fmac_f32_e32 v213, v158, v25
	v_fmac_f32_e32 v214, v162, v25
	v_fmac_f32_e32 v215, v166, v25
	v_fmac_f32_e32 v216, v170, v25
	v_fmac_f32_e32 v217, v174, v25
	v_mul_f32_e32 v26, v26, v219
	v_fmac_f32_e32 v210, v147, v26
	v_fmac_f32_e32 v211, v151, v26
	v_fmac_f32_e32 v212, v155, v26
	v_fmac_f32_e32 v213, v159, v26
	v_fmac_f32_e32 v214, v163, v26
	v_fmac_f32_e32 v215, v167, v26
	v_fmac_f32_e32 v216, v171, v26
	v_fmac_f32_e32 v217, v175, v26
	v_mul_f32_e32 v27, v27, v220
	v_fmac_f32_e32 v210, v148, v27
	v_fmac_f32_e32 v211, v152, v27
	v_fmac_f32_e32 v212, v156, v27
	v_fmac_f32_e32 v213, v160, v27
	v_fmac_f32_e32 v214, v164, v27
	v_fmac_f32_e32 v215, v168, v27
	v_fmac_f32_e32 v216, v172, v27
	v_fmac_f32_e32 v217, v176, v27
	v_mul_f32_e32 v29, v29, v221
	v_fmac_f32_e32 v210, v149, v29
	v_fmac_f32_e32 v211, v153, v29
	v_fmac_f32_e32 v212, v157, v29
	v_fmac_f32_e32 v213, v161, v29
	v_fmac_f32_e32 v214, v165, v29
	v_fmac_f32_e32 v215, v169, v29
	v_fmac_f32_e32 v216, v173, v29
	v_fmac_f32_e32 v217, v177, v29
	ds_read_b128 v[146:149], v41 offset:128
	ds_read_b128 v[150:153], v41 offset:640
	ds_read_b128 v[154:157], v41 offset:1152
	ds_read_b128 v[158:161], v41 offset:1664
	ds_read_b128 v[162:165], v41 offset:2176
	ds_read_b128 v[166:169], v41 offset:2688
	ds_read_b128 v[170:173], v41 offset:3200
	ds_read_b128 v[174:177], v41 offset:3712
	ds_read_b128 v[218:221], v41 offset:4224
	global_load_dword v25, v40, s[44:45]
	s_add_u32 s44, s44, 0x1000
	s_addc_u32 s45, s45, 0
	global_load_dword v26, v40, s[44:45]
	s_add_u32 s44, s44, 0x1000
	s_addc_u32 s45, s45, 0
	global_load_dword v27, v40, s[44:45]
	s_add_u32 s44, s44, 0x1000
	s_addc_u32 s45, s45, 0
	global_load_dword v29, v40, s[44:45]
	s_add_u32 s44, s44, 0x1000
	s_addc_u32 s45, s45, 0
	s_waitcnt lgkmcnt(9)
	s_waitcnt vmcnt(28)
	v_mul_f32_e32 v30, v30, v130
	v_fmac_f32_e32 v210, v178, v30
	v_fmac_f32_e32 v211, v182, v30
	v_fmac_f32_e32 v212, v186, v30
	v_fmac_f32_e32 v213, v190, v30
	v_fmac_f32_e32 v214, v114, v30
	v_fmac_f32_e32 v215, v118, v30
	v_fmac_f32_e32 v216, v122, v30
	v_fmac_f32_e32 v217, v126, v30
	v_mul_f32_e32 v31, v31, v131
	v_fmac_f32_e32 v210, v179, v31
	v_fmac_f32_e32 v211, v183, v31
	v_fmac_f32_e32 v212, v187, v31
	v_fmac_f32_e32 v213, v191, v31
	v_fmac_f32_e32 v214, v115, v31
	v_fmac_f32_e32 v215, v119, v31
	v_fmac_f32_e32 v216, v123, v31
	v_fmac_f32_e32 v217, v127, v31
	v_mul_f32_e32 v32, v32, v132
	v_fmac_f32_e32 v210, v180, v32
	v_fmac_f32_e32 v211, v184, v32
	v_fmac_f32_e32 v212, v188, v32
	v_fmac_f32_e32 v213, v192, v32
	v_fmac_f32_e32 v214, v116, v32
	v_fmac_f32_e32 v215, v120, v32
	v_fmac_f32_e32 v216, v124, v32
	v_fmac_f32_e32 v217, v128, v32
	v_mul_f32_e32 v33, v33, v133
	v_fmac_f32_e32 v210, v181, v33
	v_fmac_f32_e32 v211, v185, v33
	v_fmac_f32_e32 v212, v189, v33
	v_fmac_f32_e32 v213, v193, v33
	v_fmac_f32_e32 v214, v117, v33
	v_fmac_f32_e32 v215, v121, v33
	v_fmac_f32_e32 v216, v125, v33
	v_fmac_f32_e32 v217, v129, v33
	ds_read_b128 v[178:181], v41 offset:144
	ds_read_b128 v[182:185], v41 offset:656
	ds_read_b128 v[186:189], v41 offset:1168
	ds_read_b128 v[190:193], v41 offset:1680
	ds_read_b128 v[114:117], v41 offset:2192
	ds_read_b128 v[118:121], v41 offset:2704
	ds_read_b128 v[122:125], v41 offset:3216
	ds_read_b128 v[126:129], v41 offset:3728
	ds_read_b128 v[130:133], v41 offset:4240
	global_load_dword v30, v40, s[44:45]
	s_add_u32 s44, s44, 0x1000
	s_addc_u32 s45, s45, 0
	global_load_dword v31, v40, s[44:45]
	s_add_u32 s44, s44, 0x1000
	s_addc_u32 s45, s45, 0
	global_load_dword v32, v40, s[44:45]
	s_add_u32 s44, s44, 0x1000
	s_addc_u32 s45, s45, 0
	global_load_dword v33, v40, s[44:45]
	s_add_u32 s44, s44, 0x1000
	s_addc_u32 s45, s45, 0
	s_waitcnt lgkmcnt(9)
	s_waitcnt vmcnt(28)
	v_mul_f32_e32 v242, v242, v218
	v_fmac_f32_e32 v210, v146, v242
	v_fmac_f32_e32 v211, v150, v242
	v_fmac_f32_e32 v212, v154, v242
	v_fmac_f32_e32 v213, v158, v242
	v_fmac_f32_e32 v214, v162, v242
	v_fmac_f32_e32 v215, v166, v242
	v_fmac_f32_e32 v216, v170, v242
	v_fmac_f32_e32 v217, v174, v242
	v_mul_f32_e32 v243, v243, v219
	v_fmac_f32_e32 v210, v147, v243
	v_fmac_f32_e32 v211, v151, v243
	v_fmac_f32_e32 v212, v155, v243
	v_fmac_f32_e32 v213, v159, v243
	v_fmac_f32_e32 v214, v163, v243
	v_fmac_f32_e32 v215, v167, v243
	v_fmac_f32_e32 v216, v171, v243
	v_fmac_f32_e32 v217, v175, v243
	v_mul_f32_e32 v244, v244, v220
	v_fmac_f32_e32 v210, v148, v244
	v_fmac_f32_e32 v211, v152, v244
	v_fmac_f32_e32 v212, v156, v244
	v_fmac_f32_e32 v213, v160, v244
	v_fmac_f32_e32 v214, v164, v244
	v_fmac_f32_e32 v215, v168, v244
	v_fmac_f32_e32 v216, v172, v244
	v_fmac_f32_e32 v217, v176, v244
	v_mul_f32_e32 v245, v245, v221
	v_fmac_f32_e32 v210, v149, v245
	v_fmac_f32_e32 v211, v153, v245
	v_fmac_f32_e32 v212, v157, v245
	v_fmac_f32_e32 v213, v161, v245
	v_fmac_f32_e32 v214, v165, v245
	v_fmac_f32_e32 v215, v169, v245
	v_fmac_f32_e32 v216, v173, v245
	v_fmac_f32_e32 v217, v177, v245
	ds_read_b128 v[146:149], v41 offset:160
	ds_read_b128 v[150:153], v41 offset:672
	ds_read_b128 v[154:157], v41 offset:1184
	ds_read_b128 v[158:161], v41 offset:1696
	ds_read_b128 v[162:165], v41 offset:2208
	ds_read_b128 v[166:169], v41 offset:2720
	ds_read_b128 v[170:173], v41 offset:3232
	ds_read_b128 v[174:177], v41 offset:3744
	ds_read_b128 v[218:221], v41 offset:4256
	global_load_dword v242, v40, s[44:45]
	s_add_u32 s44, s44, 0x1000
	s_addc_u32 s45, s45, 0
	global_load_dword v243, v40, s[44:45]
	s_add_u32 s44, s44, 0x1000
	s_addc_u32 s45, s45, 0
	global_load_dword v244, v40, s[44:45]
	s_add_u32 s44, s44, 0x1000
	s_addc_u32 s45, s45, 0
	global_load_dword v245, v40, s[44:45]
	s_add_u32 s44, s44, 0x1000
	s_addc_u32 s45, s45, 0
	s_waitcnt lgkmcnt(9)
; __device__ __forceinline__ void phase_prologue(PtrTab TB, unsigned char* ws, float* xout, int l, LAS unsigned char* lds, int gw, int NGW, int lane, int wave) {
;     ...
; #pragma unroll 16
;           for (int j = 0; j < 128; ++j) { const float u = ua[(size_t)j * D] * sc[j];
; #pragma unroll
;               for (int c = 0; c < 8; ++c) acc[c] += wp[c * 128 + j] * u; }
	s_waitcnt vmcnt(28)
	v_mul_f32_e32 v246, v246, v130
	v_fmac_f32_e32 v210, v178, v246
	v_fmac_f32_e32 v211, v182, v246
	v_fmac_f32_e32 v212, v186, v246
	v_fmac_f32_e32 v213, v190, v246
	v_fmac_f32_e32 v214, v114, v246
	v_fmac_f32_e32 v215, v118, v246
	v_fmac_f32_e32 v216, v122, v246
	v_fmac_f32_e32 v217, v126, v246
	v_mul_f32_e32 v247, v247, v131
	v_fmac_f32_e32 v210, v179, v247
	v_fmac_f32_e32 v211, v183, v247
	v_fmac_f32_e32 v212, v187, v247
	v_fmac_f32_e32 v213, v191, v247
	v_fmac_f32_e32 v214, v115, v247
	v_fmac_f32_e32 v215, v119, v247
	v_fmac_f32_e32 v216, v123, v247
	v_fmac_f32_e32 v217, v127, v247
	v_mul_f32_e32 v248, v248, v132
	v_fmac_f32_e32 v210, v180, v248
	v_fmac_f32_e32 v211, v184, v248
	v_fmac_f32_e32 v212, v188, v248
	v_fmac_f32_e32 v213, v192, v248
	v_fmac_f32_e32 v214, v116, v248
	v_fmac_f32_e32 v215, v120, v248
	v_fmac_f32_e32 v216, v124, v248
	v_fmac_f32_e32 v217, v128, v248
	v_mul_f32_e32 v249, v249, v133
	v_fmac_f32_e32 v210, v181, v249
	v_fmac_f32_e32 v211, v185, v249
	v_fmac_f32_e32 v212, v189, v249
	v_fmac_f32_e32 v213, v193, v249
	v_fmac_f32_e32 v214, v117, v249
	v_fmac_f32_e32 v215, v121, v249
	v_fmac_f32_e32 v216, v125, v249
	v_fmac_f32_e32 v217, v129, v249
	ds_read_b128 v[178:181], v41 offset:176
	ds_read_b128 v[182:185], v41 offset:688
	ds_read_b128 v[186:189], v41 offset:1200
	ds_read_b128 v[190:193], v41 offset:1712
	ds_read_b128 v[114:117], v41 offset:2224
	ds_read_b128 v[118:121], v41 offset:2736
	ds_read_b128 v[122:125], v41 offset:3248
	ds_read_b128 v[126:129], v41 offset:3760
	ds_read_b128 v[130:133], v41 offset:4272
	global_load_dword v246, v40, s[44:45]
	s_add_u32 s44, s44, 0x1000
	s_addc_u32 s45, s45, 0
	global_load_dword v247, v40, s[44:45]
	s_add_u32 s44, s44, 0x1000
	s_addc_u32 s45, s45, 0
	global_load_dword v248, v40, s[44:45]
	s_add_u32 s44, s44, 0x1000
	s_addc_u32 s45, s45, 0
	global_load_dword v249, v40, s[44:45]
	s_add_u32 s44, s44, 0x1000
	s_addc_u32 s45, s45, 0
	s_waitcnt lgkmcnt(9)
	s_waitcnt vmcnt(28)
	v_mul_f32_e32 v250, v250, v218
	v_fmac_f32_e32 v210, v146, v250
	v_fmac_f32_e32 v211, v150, v250
	v_fmac_f32_e32 v212, v154, v250
	v_fmac_f32_e32 v213, v158, v250
	v_fmac_f32_e32 v214, v162, v250
	v_fmac_f32_e32 v215, v166, v250
	v_fmac_f32_e32 v216, v170, v250
	v_fmac_f32_e32 v217, v174, v250
	v_mul_f32_e32 v251, v251, v219
	v_fmac_f32_e32 v210, v147, v251
	v_fmac_f32_e32 v211, v151, v251
	v_fmac_f32_e32 v212, v155, v251
	v_fmac_f32_e32 v213, v159, v251
	v_fmac_f32_e32 v214, v163, v251
	v_fmac_f32_e32 v215, v167, v251
	v_fmac_f32_e32 v216, v171, v251
	v_fmac_f32_e32 v217, v175, v251
	v_mul_f32_e32 v252, v252, v220
	v_fmac_f32_e32 v210, v148, v252
	v_fmac_f32_e32 v211, v152, v252
	v_fmac_f32_e32 v212, v156, v252
	v_fmac_f32_e32 v213, v160, v252
	v_fmac_f32_e32 v214, v164, v252
	v_fmac_f32_e32 v215, v168, v252
	v_fmac_f32_e32 v216, v172, v252
	v_fmac_f32_e32 v217, v176, v252
	v_mul_f32_e32 v253, v253, v221
	v_fmac_f32_e32 v210, v149, v253
	v_fmac_f32_e32 v211, v153, v253
	v_fmac_f32_e32 v212, v157, v253
	v_fmac_f32_e32 v213, v161, v253
	v_fmac_f32_e32 v214, v165, v253
	v_fmac_f32_e32 v215, v169, v253
	v_fmac_f32_e32 v216, v173, v253
	v_fmac_f32_e32 v217, v177, v253
	ds_read_b128 v[146:149], v41 offset:192
	ds_read_b128 v[150:153], v41 offset:704
	ds_read_b128 v[154:157], v41 offset:1216
	ds_read_b128 v[158:161], v41 offset:1728
	ds_read_b128 v[162:165], v41 offset:2240
	ds_read_b128 v[166:169], v41 offset:2752
	ds_read_b128 v[170:173], v41 offset:3264
	ds_read_b128 v[174:177], v41 offset:3776
	ds_read_b128 v[218:221], v41 offset:4288
	global_load_dword v250, v40, s[44:45]
	s_add_u32 s44, s44, 0x1000
	s_addc_u32 s45, s45, 0
	global_load_dword v251, v40, s[44:45]
	s_add_u32 s44, s44, 0x1000
	s_addc_u32 s45, s45, 0
	global_load_dword v252, v40, s[44:45]
	s_add_u32 s44, s44, 0x1000
	s_addc_u32 s45, s45, 0
	global_load_dword v253, v40, s[44:45]
	s_add_u32 s44, s44, 0x1000
	s_addc_u32 s45, s45, 0
	s_waitcnt lgkmcnt(9)
	s_waitcnt vmcnt(28)
	v_mul_f32_e32 v230, v230, v130
	v_fmac_f32_e32 v210, v178, v230
	v_fmac_f32_e32 v211, v182, v230
	v_fmac_f32_e32 v212, v186, v230
	v_fmac_f32_e32 v213, v190, v230
	v_fmac_f32_e32 v214, v114, v230
	v_fmac_f32_e32 v215, v118, v230
	v_fmac_f32_e32 v216, v122, v230
	v_fmac_f32_e32 v217, v126, v230
	v_mul_f32_e32 v231, v231, v131
	v_fmac_f32_e32 v210, v179, v231
	v_fmac_f32_e32 v211, v183, v231
	v_fmac_f32_e32 v212, v187, v231
	v_fmac_f32_e32 v213, v191, v231
	v_fmac_f32_e32 v214, v115, v231
	v_fmac_f32_e32 v215, v119, v231
	v_fmac_f32_e32 v216, v123, v231
	v_fmac_f32_e32 v217, v127, v231
	v_mul_f32_e32 v232, v232, v132
	v_fmac_f32_e32 v210, v180, v232
	v_fmac_f32_e32 v211, v184, v232
	v_fmac_f32_e32 v212, v188, v232
	v_fmac_f32_e32 v213, v192, v232
	v_fmac_f32_e32 v214, v116, v232
	v_fmac_f32_e32 v215, v120, v232
	v_fmac_f32_e32 v216, v124, v232
	v_fmac_f32_e32 v217, v128, v232
	v_mul_f32_e32 v233, v233, v133
	v_fmac_f32_e32 v210, v181, v233
	v_fmac_f32_e32 v211, v185, v233
	v_fmac_f32_e32 v212, v189, v233
	v_fmac_f32_e32 v213, v193, v233
	v_fmac_f32_e32 v214, v117, v233
	v_fmac_f32_e32 v215, v121, v233
	v_fmac_f32_e32 v216, v125, v233
	v_fmac_f32_e32 v217, v129, v233
	ds_read_b128 v[178:181], v41 offset:208
	ds_read_b128 v[182:185], v41 offset:720
	ds_read_b128 v[186:189], v41 offset:1232
	ds_read_b128 v[190:193], v41 offset:1744
	ds_read_b128 v[114:117], v41 offset:2256
	ds_read_b128 v[118:121], v41 offset:2768
	ds_read_b128 v[122:125], v41 offset:3280
	ds_read_b128 v[126:129], v41 offset:3792
	ds_read_b128 v[130:133], v41 offset:4304
	global_load_dword v230, v40, s[44:45]
	s_add_u32 s44, s44, 0x1000
	s_addc_u32 s45, s45, 0
	global_load_dword v231, v40, s[44:45]
	s_add_u32 s44, s44, 0x1000
	s_addc_u32 s45, s45, 0
	global_load_dword v232, v40, s[44:45]
	s_add_u32 s44, s44, 0x1000
	s_addc_u32 s45, s45, 0
	global_load_dword v233, v40, s[44:45]
	s_add_u32 s44, s44, 0x1000
	s_addc_u32 s45, s45, 0
	s_waitcnt lgkmcnt(9)
; __device__ __forceinline__ void phase_prologue(PtrTab TB, unsigned char* ws, float* xout, int l, LAS unsigned char* lds, int gw, int NGW, int lane, int wave) {
;     ...
; #pragma unroll 16
;           for (int j = 0; j < 128; ++j) { const float u = ua[(size_t)j * D] * sc[j];
; #pragma unroll
;               for (int c = 0; c < 8; ++c) acc[c] += wp[c * 128 + j] * u; }
	s_waitcnt vmcnt(28)
	v_mul_f32_e32 v222, v222, v218
	v_fmac_f32_e32 v210, v146, v222
	v_fmac_f32_e32 v211, v150, v222
	v_fmac_f32_e32 v212, v154, v222
	v_fmac_f32_e32 v213, v158, v222
	v_fmac_f32_e32 v214, v162, v222
	v_fmac_f32_e32 v215, v166, v222
	v_fmac_f32_e32 v216, v170, v222
	v_fmac_f32_e32 v217, v174, v222
	v_mul_f32_e32 v223, v223, v219
	v_fmac_f32_e32 v210, v147, v223
	v_fmac_f32_e32 v211, v151, v223
	v_fmac_f32_e32 v212, v155, v223
	v_fmac_f32_e32 v213, v159, v223
	v_fmac_f32_e32 v214, v163, v223
	v_fmac_f32_e32 v215, v167, v223
	v_fmac_f32_e32 v216, v171, v223
	v_fmac_f32_e32 v217, v175, v223
	v_mul_f32_e32 v134, v134, v220
	v_fmac_f32_e32 v210, v148, v134
	v_fmac_f32_e32 v211, v152, v134
	v_fmac_f32_e32 v212, v156, v134
	v_fmac_f32_e32 v213, v160, v134
	v_fmac_f32_e32 v214, v164, v134
	v_fmac_f32_e32 v215, v168, v134
	v_fmac_f32_e32 v216, v172, v134
	v_fmac_f32_e32 v217, v176, v134
	v_mul_f32_e32 v135, v135, v221
	v_fmac_f32_e32 v210, v149, v135
	v_fmac_f32_e32 v211, v153, v135
	v_fmac_f32_e32 v212, v157, v135
	v_fmac_f32_e32 v213, v161, v135
	v_fmac_f32_e32 v214, v165, v135
	v_fmac_f32_e32 v215, v169, v135
	v_fmac_f32_e32 v216, v173, v135
	v_fmac_f32_e32 v217, v177, v135
	ds_read_b128 v[146:149], v41 offset:224
	ds_read_b128 v[150:153], v41 offset:736
	ds_read_b128 v[154:157], v41 offset:1248
	ds_read_b128 v[158:161], v41 offset:1760
	ds_read_b128 v[162:165], v41 offset:2272
	ds_read_b128 v[166:169], v41 offset:2784
	ds_read_b128 v[170:173], v41 offset:3296
	ds_read_b128 v[174:177], v41 offset:3808
	ds_read_b128 v[218:221], v41 offset:4320
	global_load_dword v222, v40, s[44:45]
	s_add_u32 s44, s44, 0x1000
	s_addc_u32 s45, s45, 0
	global_load_dword v223, v40, s[44:45]
	s_add_u32 s44, s44, 0x1000
	s_addc_u32 s45, s45, 0
	global_load_dword v134, v40, s[44:45]
	s_add_u32 s44, s44, 0x1000
	s_addc_u32 s45, s45, 0
	global_load_dword v135, v40, s[44:45]
	s_add_u32 s44, s44, 0x1000
	s_addc_u32 s45, s45, 0
	s_waitcnt lgkmcnt(9)
	s_waitcnt vmcnt(28)
	v_mul_f32_e32 v136, v136, v130
	v_fmac_f32_e32 v210, v178, v136
	v_fmac_f32_e32 v211, v182, v136
	v_fmac_f32_e32 v212, v186, v136
	v_fmac_f32_e32 v213, v190, v136
	v_fmac_f32_e32 v214, v114, v136
	v_fmac_f32_e32 v215, v118, v136
	v_fmac_f32_e32 v216, v122, v136
	v_fmac_f32_e32 v217, v126, v136
	v_mul_f32_e32 v194, v194, v131
	v_fmac_f32_e32 v210, v179, v194
	v_fmac_f32_e32 v211, v183, v194
	v_fmac_f32_e32 v212, v187, v194
	v_fmac_f32_e32 v213, v191, v194
	v_fmac_f32_e32 v214, v115, v194
	v_fmac_f32_e32 v215, v119, v194
	v_fmac_f32_e32 v216, v123, v194
	v_fmac_f32_e32 v217, v127, v194
	v_mul_f32_e32 v195, v195, v132
	v_fmac_f32_e32 v210, v180, v195
	v_fmac_f32_e32 v211, v184, v195
	v_fmac_f32_e32 v212, v188, v195
	v_fmac_f32_e32 v213, v192, v195
	v_fmac_f32_e32 v214, v116, v195
	v_fmac_f32_e32 v215, v120, v195
	v_fmac_f32_e32 v216, v124, v195
	v_fmac_f32_e32 v217, v128, v195
	v_mul_f32_e32 v24, v24, v133
	v_fmac_f32_e32 v210, v181, v24
	v_fmac_f32_e32 v211, v185, v24
	v_fmac_f32_e32 v212, v189, v24
	v_fmac_f32_e32 v213, v193, v24
	v_fmac_f32_e32 v214, v117, v24
	v_fmac_f32_e32 v215, v121, v24
	v_fmac_f32_e32 v216, v125, v24
	v_fmac_f32_e32 v217, v129, v24
	ds_read_b128 v[178:181], v41 offset:240
	ds_read_b128 v[182:185], v41 offset:752
	ds_read_b128 v[186:189], v41 offset:1264
	ds_read_b128 v[190:193], v41 offset:1776
	ds_read_b128 v[114:117], v41 offset:2288
	ds_read_b128 v[118:121], v41 offset:2800
	ds_read_b128 v[122:125], v41 offset:3312
	ds_read_b128 v[126:129], v41 offset:3824
	ds_read_b128 v[130:133], v41 offset:4336
	global_load_dword v136, v40, s[44:45]
	s_add_u32 s44, s44, 0x1000
	s_addc_u32 s45, s45, 0
	global_load_dword v194, v40, s[44:45]
	s_add_u32 s44, s44, 0x1000
	s_addc_u32 s45, s45, 0
	global_load_dword v195, v40, s[44:45]
	s_add_u32 s44, s44, 0x1000
	s_addc_u32 s45, s45, 0
	global_load_dword v24, v40, s[44:45]
	s_add_u32 s44, s44, 0x1000
	s_addc_u32 s45, s45, 0
	s_waitcnt lgkmcnt(9)
	s_waitcnt vmcnt(28)
	v_mul_f32_e32 v25, v25, v218
	v_fmac_f32_e32 v210, v146, v25
	v_fmac_f32_e32 v211, v150, v25
	v_fmac_f32_e32 v212, v154, v25
	v_fmac_f32_e32 v213, v158, v25
	v_fmac_f32_e32 v214, v162, v25
	v_fmac_f32_e32 v215, v166, v25
	v_fmac_f32_e32 v216, v170, v25
	v_fmac_f32_e32 v217, v174, v25
	v_mul_f32_e32 v26, v26, v219
	v_fmac_f32_e32 v210, v147, v26
	v_fmac_f32_e32 v211, v151, v26
	v_fmac_f32_e32 v212, v155, v26
	v_fmac_f32_e32 v213, v159, v26
	v_fmac_f32_e32 v214, v163, v26
	v_fmac_f32_e32 v215, v167, v26
	v_fmac_f32_e32 v216, v171, v26
	v_fmac_f32_e32 v217, v175, v26
	v_mul_f32_e32 v27, v27, v220
	v_fmac_f32_e32 v210, v148, v27
	v_fmac_f32_e32 v211, v152, v27
	v_fmac_f32_e32 v212, v156, v27
	v_fmac_f32_e32 v213, v160, v27
	v_fmac_f32_e32 v214, v164, v27
	v_fmac_f32_e32 v215, v168, v27
	v_fmac_f32_e32 v216, v172, v27
	v_fmac_f32_e32 v217, v176, v27
	v_mul_f32_e32 v29, v29, v221
	v_fmac_f32_e32 v210, v149, v29
	v_fmac_f32_e32 v211, v153, v29
	v_fmac_f32_e32 v212, v157, v29
	v_fmac_f32_e32 v213, v161, v29
	v_fmac_f32_e32 v214, v165, v29
	v_fmac_f32_e32 v215, v169, v29
	v_fmac_f32_e32 v216, v173, v29
	v_fmac_f32_e32 v217, v177, v29
	ds_read_b128 v[146:149], v41 offset:256
	ds_read_b128 v[150:153], v41 offset:768
	ds_read_b128 v[154:157], v41 offset:1280
	ds_read_b128 v[158:161], v41 offset:1792
	ds_read_b128 v[162:165], v41 offset:2304
	ds_read_b128 v[166:169], v41 offset:2816
	ds_read_b128 v[170:173], v41 offset:3328
	ds_read_b128 v[174:177], v41 offset:3840
	ds_read_b128 v[218:221], v41 offset:4352
	global_load_dword v25, v40, s[44:45]
	s_add_u32 s44, s44, 0x1000
	s_addc_u32 s45, s45, 0
	global_load_dword v26, v40, s[44:45]
	s_add_u32 s44, s44, 0x1000
	s_addc_u32 s45, s45, 0
	global_load_dword v27, v40, s[44:45]
	s_add_u32 s44, s44, 0x1000
	s_addc_u32 s45, s45, 0
	global_load_dword v29, v40, s[44:45]
	s_add_u32 s44, s44, 0x1000
	s_addc_u32 s45, s45, 0
	s_waitcnt lgkmcnt(9)
; __device__ __forceinline__ void phase_prologue(PtrTab TB, unsigned char* ws, float* xout, int l, LAS unsigned char* lds, int gw, int NGW, int lane, int wave) {
;     ...
; #pragma unroll 16
;           for (int j = 0; j < 128; ++j) { const float u = ua[(size_t)j * D] * sc[j];
; #pragma unroll
;               for (int c = 0; c < 8; ++c) acc[c] += wp[c * 128 + j] * u; }
	s_waitcnt vmcnt(28)
	v_mul_f32_e32 v30, v30, v130
	v_fmac_f32_e32 v210, v178, v30
	v_fmac_f32_e32 v211, v182, v30
	v_fmac_f32_e32 v212, v186, v30
	v_fmac_f32_e32 v213, v190, v30
	v_fmac_f32_e32 v214, v114, v30
	v_fmac_f32_e32 v215, v118, v30
	v_fmac_f32_e32 v216, v122, v30
	v_fmac_f32_e32 v217, v126, v30
	v_mul_f32_e32 v31, v31, v131
	v_fmac_f32_e32 v210, v179, v31
	v_fmac_f32_e32 v211, v183, v31
	v_fmac_f32_e32 v212, v187, v31
	v_fmac_f32_e32 v213, v191, v31
	v_fmac_f32_e32 v214, v115, v31
	v_fmac_f32_e32 v215, v119, v31
	v_fmac_f32_e32 v216, v123, v31
	v_fmac_f32_e32 v217, v127, v31
	v_mul_f32_e32 v32, v32, v132
	v_fmac_f32_e32 v210, v180, v32
	v_fmac_f32_e32 v211, v184, v32
	v_fmac_f32_e32 v212, v188, v32
	v_fmac_f32_e32 v213, v192, v32
	v_fmac_f32_e32 v214, v116, v32
	v_fmac_f32_e32 v215, v120, v32
	v_fmac_f32_e32 v216, v124, v32
	v_fmac_f32_e32 v217, v128, v32
	v_mul_f32_e32 v33, v33, v133
	v_fmac_f32_e32 v210, v181, v33
	v_fmac_f32_e32 v211, v185, v33
	v_fmac_f32_e32 v212, v189, v33
	v_fmac_f32_e32 v213, v193, v33
	v_fmac_f32_e32 v214, v117, v33
	v_fmac_f32_e32 v215, v121, v33
	v_fmac_f32_e32 v216, v125, v33
	v_fmac_f32_e32 v217, v129, v33
	ds_read_b128 v[178:181], v41 offset:272
	ds_read_b128 v[182:185], v41 offset:784
	ds_read_b128 v[186:189], v41 offset:1296
	ds_read_b128 v[190:193], v41 offset:1808
	ds_read_b128 v[114:117], v41 offset:2320
	ds_read_b128 v[118:121], v41 offset:2832
	ds_read_b128 v[122:125], v41 offset:3344
	ds_read_b128 v[126:129], v41 offset:3856
	ds_read_b128 v[130:133], v41 offset:4368
	global_load_dword v30, v40, s[44:45]
	s_add_u32 s44, s44, 0x1000
	s_addc_u32 s45, s45, 0
	global_load_dword v31, v40, s[44:45]
	s_add_u32 s44, s44, 0x1000
	s_addc_u32 s45, s45, 0
	global_load_dword v32, v40, s[44:45]
	s_add_u32 s44, s44, 0x1000
	s_addc_u32 s45, s45, 0
	global_load_dword v33, v40, s[44:45]
	s_add_u32 s44, s44, 0x1000
	s_addc_u32 s45, s45, 0
	s_waitcnt lgkmcnt(9)
	s_waitcnt vmcnt(28)
	v_mul_f32_e32 v242, v242, v218
	v_fmac_f32_e32 v210, v146, v242
	v_fmac_f32_e32 v211, v150, v242
	v_fmac_f32_e32 v212, v154, v242
	v_fmac_f32_e32 v213, v158, v242
	v_fmac_f32_e32 v214, v162, v242
	v_fmac_f32_e32 v215, v166, v242
	v_fmac_f32_e32 v216, v170, v242
	v_fmac_f32_e32 v217, v174, v242
	v_mul_f32_e32 v243, v243, v219
	v_fmac_f32_e32 v210, v147, v243
	v_fmac_f32_e32 v211, v151, v243
	v_fmac_f32_e32 v212, v155, v243
	v_fmac_f32_e32 v213, v159, v243
	v_fmac_f32_e32 v214, v163, v243
	v_fmac_f32_e32 v215, v167, v243
	v_fmac_f32_e32 v216, v171, v243
	v_fmac_f32_e32 v217, v175, v243
	v_mul_f32_e32 v244, v244, v220
	v_fmac_f32_e32 v210, v148, v244
	v_fmac_f32_e32 v211, v152, v244
	v_fmac_f32_e32 v212, v156, v244
	v_fmac_f32_e32 v213, v160, v244
	v_fmac_f32_e32 v214, v164, v244
	v_fmac_f32_e32 v215, v168, v244
	v_fmac_f32_e32 v216, v172, v244
	v_fmac_f32_e32 v217, v176, v244
	v_mul_f32_e32 v245, v245, v221
	v_fmac_f32_e32 v210, v149, v245
	v_fmac_f32_e32 v211, v153, v245
	v_fmac_f32_e32 v212, v157, v245
	v_fmac_f32_e32 v213, v161, v245
	v_fmac_f32_e32 v214, v165, v245
	v_fmac_f32_e32 v215, v169, v245
	v_fmac_f32_e32 v216, v173, v245
	v_fmac_f32_e32 v217, v177, v245
	ds_read_b128 v[146:149], v41 offset:288
	ds_read_b128 v[150:153], v41 offset:800
	ds_read_b128 v[154:157], v41 offset:1312
	ds_read_b128 v[158:161], v41 offset:1824
	ds_read_b128 v[162:165], v41 offset:2336
	ds_read_b128 v[166:169], v41 offset:2848
	ds_read_b128 v[170:173], v41 offset:3360
	ds_read_b128 v[174:177], v41 offset:3872
	ds_read_b128 v[218:221], v41 offset:4384
	global_load_dword v242, v40, s[44:45]
	s_add_u32 s44, s44, 0x1000
	s_addc_u32 s45, s45, 0
	global_load_dword v243, v40, s[44:45]
	s_add_u32 s44, s44, 0x1000
	s_addc_u32 s45, s45, 0
	global_load_dword v244, v40, s[44:45]
	s_add_u32 s44, s44, 0x1000
	s_addc_u32 s45, s45, 0
	global_load_dword v245, v40, s[44:45]
	s_add_u32 s44, s44, 0x1000
	s_addc_u32 s45, s45, 0
	s_waitcnt lgkmcnt(9)
	s_waitcnt vmcnt(28)
	v_mul_f32_e32 v246, v246, v130
	v_fmac_f32_e32 v210, v178, v246
	v_fmac_f32_e32 v211, v182, v246
	v_fmac_f32_e32 v212, v186, v246
	v_fmac_f32_e32 v213, v190, v246
	v_fmac_f32_e32 v214, v114, v246
	v_fmac_f32_e32 v215, v118, v246
	v_fmac_f32_e32 v216, v122, v246
	v_fmac_f32_e32 v217, v126, v246
	v_mul_f32_e32 v247, v247, v131
	v_fmac_f32_e32 v210, v179, v247
	v_fmac_f32_e32 v211, v183, v247
	v_fmac_f32_e32 v212, v187, v247
	v_fmac_f32_e32 v213, v191, v247
	v_fmac_f32_e32 v214, v115, v247
	v_fmac_f32_e32 v215, v119, v247
	v_fmac_f32_e32 v216, v123, v247
	v_fmac_f32_e32 v217, v127, v247
	v_mul_f32_e32 v248, v248, v132
	v_fmac_f32_e32 v210, v180, v248
	v_fmac_f32_e32 v211, v184, v248
	v_fmac_f32_e32 v212, v188, v248
	v_fmac_f32_e32 v213, v192, v248
	v_fmac_f32_e32 v214, v116, v248
	v_fmac_f32_e32 v215, v120, v248
	v_fmac_f32_e32 v216, v124, v248
	v_fmac_f32_e32 v217, v128, v248
	v_mul_f32_e32 v249, v249, v133
	v_fmac_f32_e32 v210, v181, v249
	v_fmac_f32_e32 v211, v185, v249
	v_fmac_f32_e32 v212, v189, v249
	v_fmac_f32_e32 v213, v193, v249
	v_fmac_f32_e32 v214, v117, v249
	v_fmac_f32_e32 v215, v121, v249
	v_fmac_f32_e32 v216, v125, v249
	v_fmac_f32_e32 v217, v129, v249
	ds_read_b128 v[178:181], v41 offset:304
	ds_read_b128 v[182:185], v41 offset:816
	ds_read_b128 v[186:189], v41 offset:1328
	ds_read_b128 v[190:193], v41 offset:1840
	ds_read_b128 v[114:117], v41 offset:2352
	ds_read_b128 v[118:121], v41 offset:2864
	ds_read_b128 v[122:125], v41 offset:3376
	ds_read_b128 v[126:129], v41 offset:3888
	ds_read_b128 v[130:133], v41 offset:4400
	global_load_dword v246, v40, s[44:45]
	s_add_u32 s44, s44, 0x1000
	s_addc_u32 s45, s45, 0
	global_load_dword v247, v40, s[44:45]
	s_add_u32 s44, s44, 0x1000
	s_addc_u32 s45, s45, 0
	global_load_dword v248, v40, s[44:45]
	s_add_u32 s44, s44, 0x1000
	s_addc_u32 s45, s45, 0
	global_load_dword v249, v40, s[44:45]
	s_add_u32 s44, s44, 0x1000
	s_addc_u32 s45, s45, 0
	s_waitcnt lgkmcnt(9)
; __device__ __forceinline__ void phase_prologue(PtrTab TB, unsigned char* ws, float* xout, int l, LAS unsigned char* lds, int gw, int NGW, int lane, int wave) {
;     ...
; #pragma unroll 16
;           for (int j = 0; j < 128; ++j) { const float u = ua[(size_t)j * D] * sc[j];
; #pragma unroll
;               for (int c = 0; c < 8; ++c) acc[c] += wp[c * 128 + j] * u; }
	s_waitcnt vmcnt(28)
	v_mul_f32_e32 v250, v250, v218
	v_fmac_f32_e32 v210, v146, v250
	v_fmac_f32_e32 v211, v150, v250
	v_fmac_f32_e32 v212, v154, v250
	v_fmac_f32_e32 v213, v158, v250
	v_fmac_f32_e32 v214, v162, v250
	v_fmac_f32_e32 v215, v166, v250
	v_fmac_f32_e32 v216, v170, v250
	v_fmac_f32_e32 v217, v174, v250
	v_mul_f32_e32 v251, v251, v219
	v_fmac_f32_e32 v210, v147, v251
	v_fmac_f32_e32 v211, v151, v251
	v_fmac_f32_e32 v212, v155, v251
	v_fmac_f32_e32 v213, v159, v251
	v_fmac_f32_e32 v214, v163, v251
	v_fmac_f32_e32 v215, v167, v251
	v_fmac_f32_e32 v216, v171, v251
	v_fmac_f32_e32 v217, v175, v251
	v_mul_f32_e32 v252, v252, v220
	v_fmac_f32_e32 v210, v148, v252
	v_fmac_f32_e32 v211, v152, v252
	v_fmac_f32_e32 v212, v156, v252
	v_fmac_f32_e32 v213, v160, v252
	v_fmac_f32_e32 v214, v164, v252
	v_fmac_f32_e32 v215, v168, v252
	v_fmac_f32_e32 v216, v172, v252
	v_fmac_f32_e32 v217, v176, v252
	v_mul_f32_e32 v253, v253, v221
	v_fmac_f32_e32 v210, v149, v253
	v_fmac_f32_e32 v211, v153, v253
	v_fmac_f32_e32 v212, v157, v253
	v_fmac_f32_e32 v213, v161, v253
	v_fmac_f32_e32 v214, v165, v253
	v_fmac_f32_e32 v215, v169, v253
	v_fmac_f32_e32 v216, v173, v253
	v_fmac_f32_e32 v217, v177, v253
	ds_read_b128 v[146:149], v41 offset:320
	ds_read_b128 v[150:153], v41 offset:832
	ds_read_b128 v[154:157], v41 offset:1344
	ds_read_b128 v[158:161], v41 offset:1856
	ds_read_b128 v[162:165], v41 offset:2368
	ds_read_b128 v[166:169], v41 offset:2880
	ds_read_b128 v[170:173], v41 offset:3392
	ds_read_b128 v[174:177], v41 offset:3904
	ds_read_b128 v[218:221], v41 offset:4416
	global_load_dword v250, v40, s[44:45]
	s_add_u32 s44, s44, 0x1000
	s_addc_u32 s45, s45, 0
	global_load_dword v251, v40, s[44:45]
	s_add_u32 s44, s44, 0x1000
	s_addc_u32 s45, s45, 0
	global_load_dword v252, v40, s[44:45]
	s_add_u32 s44, s44, 0x1000
	s_addc_u32 s45, s45, 0
	global_load_dword v253, v40, s[44:45]
	s_add_u32 s44, s44, 0x1000
	s_addc_u32 s45, s45, 0
	s_waitcnt lgkmcnt(9)
	s_waitcnt vmcnt(28)
	v_mul_f32_e32 v230, v230, v130
	v_fmac_f32_e32 v210, v178, v230
	v_fmac_f32_e32 v211, v182, v230
	v_fmac_f32_e32 v212, v186, v230
	v_fmac_f32_e32 v213, v190, v230
	v_fmac_f32_e32 v214, v114, v230
	v_fmac_f32_e32 v215, v118, v230
	v_fmac_f32_e32 v216, v122, v230
	v_fmac_f32_e32 v217, v126, v230
	v_mul_f32_e32 v231, v231, v131
	v_fmac_f32_e32 v210, v179, v231
	v_fmac_f32_e32 v211, v183, v231
	v_fmac_f32_e32 v212, v187, v231
	v_fmac_f32_e32 v213, v191, v231
	v_fmac_f32_e32 v214, v115, v231
	v_fmac_f32_e32 v215, v119, v231
	v_fmac_f32_e32 v216, v123, v231
	v_fmac_f32_e32 v217, v127, v231
	v_mul_f32_e32 v232, v232, v132
	v_fmac_f32_e32 v210, v180, v232
	v_fmac_f32_e32 v211, v184, v232
	v_fmac_f32_e32 v212, v188, v232
	v_fmac_f32_e32 v213, v192, v232
	v_fmac_f32_e32 v214, v116, v232
	v_fmac_f32_e32 v215, v120, v232
	v_fmac_f32_e32 v216, v124, v232
	v_fmac_f32_e32 v217, v128, v232
	v_mul_f32_e32 v233, v233, v133
	v_fmac_f32_e32 v210, v181, v233
	v_fmac_f32_e32 v211, v185, v233
	v_fmac_f32_e32 v212, v189, v233
	v_fmac_f32_e32 v213, v193, v233
	v_fmac_f32_e32 v214, v117, v233
	v_fmac_f32_e32 v215, v121, v233
	v_fmac_f32_e32 v216, v125, v233
	v_fmac_f32_e32 v217, v129, v233
	ds_read_b128 v[178:181], v41 offset:336
	ds_read_b128 v[182:185], v41 offset:848
	ds_read_b128 v[186:189], v41 offset:1360
	ds_read_b128 v[190:193], v41 offset:1872
	ds_read_b128 v[114:117], v41 offset:2384
	ds_read_b128 v[118:121], v41 offset:2896
	ds_read_b128 v[122:125], v41 offset:3408
	ds_read_b128 v[126:129], v41 offset:3920
	ds_read_b128 v[130:133], v41 offset:4432
	global_load_dword v230, v40, s[44:45]
	s_add_u32 s44, s44, 0x1000
	s_addc_u32 s45, s45, 0
	global_load_dword v231, v40, s[44:45]
	s_add_u32 s44, s44, 0x1000
	s_addc_u32 s45, s45, 0
	global_load_dword v232, v40, s[44:45]
	s_add_u32 s44, s44, 0x1000
	s_addc_u32 s45, s45, 0
	global_load_dword v233, v40, s[44:45]
	s_add_u32 s44, s44, 0x1000
	s_addc_u32 s45, s45, 0
	s_waitcnt lgkmcnt(9)
	s_waitcnt vmcnt(28)
	v_mul_f32_e32 v222, v222, v218
	v_fmac_f32_e32 v210, v146, v222
	v_fmac_f32_e32 v211, v150, v222
	v_fmac_f32_e32 v212, v154, v222
	v_fmac_f32_e32 v213, v158, v222
	v_fmac_f32_e32 v214, v162, v222
	v_fmac_f32_e32 v215, v166, v222
	v_fmac_f32_e32 v216, v170, v222
	v_fmac_f32_e32 v217, v174, v222
	v_mul_f32_e32 v223, v223, v219
	v_fmac_f32_e32 v210, v147, v223
	v_fmac_f32_e32 v211, v151, v223
	v_fmac_f32_e32 v212, v155, v223
	v_fmac_f32_e32 v213, v159, v223
	v_fmac_f32_e32 v214, v163, v223
	v_fmac_f32_e32 v215, v167, v223
	v_fmac_f32_e32 v216, v171, v223
	v_fmac_f32_e32 v217, v175, v223
	v_mul_f32_e32 v134, v134, v220
	v_fmac_f32_e32 v210, v148, v134
	v_fmac_f32_e32 v211, v152, v134
	v_fmac_f32_e32 v212, v156, v134
	v_fmac_f32_e32 v213, v160, v134
	v_fmac_f32_e32 v214, v164, v134
	v_fmac_f32_e32 v215, v168, v134
	v_fmac_f32_e32 v216, v172, v134
	v_fmac_f32_e32 v217, v176, v134
	v_mul_f32_e32 v135, v135, v221
	v_fmac_f32_e32 v210, v149, v135
	v_fmac_f32_e32 v211, v153, v135
	v_fmac_f32_e32 v212, v157, v135
	v_fmac_f32_e32 v213, v161, v135
	v_fmac_f32_e32 v214, v165, v135
	v_fmac_f32_e32 v215, v169, v135
	v_fmac_f32_e32 v216, v173, v135
	v_fmac_f32_e32 v217, v177, v135
	ds_read_b128 v[146:149], v41 offset:352
	ds_read_b128 v[150:153], v41 offset:864
	ds_read_b128 v[154:157], v41 offset:1376
	ds_read_b128 v[158:161], v41 offset:1888
	ds_read_b128 v[162:165], v41 offset:2400
	ds_read_b128 v[166:169], v41 offset:2912
	ds_read_b128 v[170:173], v41 offset:3424
	ds_read_b128 v[174:177], v41 offset:3936
	ds_read_b128 v[218:221], v41 offset:4448
	global_load_dword v222, v40, s[44:45]
	s_add_u32 s44, s44, 0x1000
	s_addc_u32 s45, s45, 0
	global_load_dword v223, v40, s[44:45]
	s_add_u32 s44, s44, 0x1000
	s_addc_u32 s45, s45, 0
	global_load_dword v134, v40, s[44:45]
	s_add_u32 s44, s44, 0x1000
	s_addc_u32 s45, s45, 0
	global_load_dword v135, v40, s[44:45]
	s_add_u32 s44, s44, 0x1000
	s_addc_u32 s45, s45, 0
	s_waitcnt lgkmcnt(9)
; __device__ __forceinline__ void phase_prologue(PtrTab TB, unsigned char* ws, float* xout, int l, LAS unsigned char* lds, int gw, int NGW, int lane, int wave) {
;     ...
; #pragma unroll 16
;           for (int j = 0; j < 128; ++j) { const float u = ua[(size_t)j * D] * sc[j];
; #pragma unroll
;               for (int c = 0; c < 8; ++c) acc[c] += wp[c * 128 + j] * u; }
	s_waitcnt vmcnt(28)
	v_mul_f32_e32 v136, v136, v130
	v_fmac_f32_e32 v210, v178, v136
	v_fmac_f32_e32 v211, v182, v136
	v_fmac_f32_e32 v212, v186, v136
	v_fmac_f32_e32 v213, v190, v136
	v_fmac_f32_e32 v214, v114, v136
	v_fmac_f32_e32 v215, v118, v136
	v_fmac_f32_e32 v216, v122, v136
	v_fmac_f32_e32 v217, v126, v136
	v_mul_f32_e32 v194, v194, v131
	v_fmac_f32_e32 v210, v179, v194
	v_fmac_f32_e32 v211, v183, v194
	v_fmac_f32_e32 v212, v187, v194
	v_fmac_f32_e32 v213, v191, v194
	v_fmac_f32_e32 v214, v115, v194
	v_fmac_f32_e32 v215, v119, v194
	v_fmac_f32_e32 v216, v123, v194
	v_fmac_f32_e32 v217, v127, v194
	v_mul_f32_e32 v195, v195, v132
	v_fmac_f32_e32 v210, v180, v195
	v_fmac_f32_e32 v211, v184, v195
	v_fmac_f32_e32 v212, v188, v195
	v_fmac_f32_e32 v213, v192, v195
	v_fmac_f32_e32 v214, v116, v195
	v_fmac_f32_e32 v215, v120, v195
	v_fmac_f32_e32 v216, v124, v195
	v_fmac_f32_e32 v217, v128, v195
	v_mul_f32_e32 v24, v24, v133
	v_fmac_f32_e32 v210, v181, v24
	v_fmac_f32_e32 v211, v185, v24
	v_fmac_f32_e32 v212, v189, v24
	v_fmac_f32_e32 v213, v193, v24
	v_fmac_f32_e32 v214, v117, v24
	v_fmac_f32_e32 v215, v121, v24
	v_fmac_f32_e32 v216, v125, v24
	v_fmac_f32_e32 v217, v129, v24
	ds_read_b128 v[178:181], v41 offset:368
	ds_read_b128 v[182:185], v41 offset:880
	ds_read_b128 v[186:189], v41 offset:1392
	ds_read_b128 v[190:193], v41 offset:1904
	ds_read_b128 v[114:117], v41 offset:2416
	ds_read_b128 v[118:121], v41 offset:2928
	ds_read_b128 v[122:125], v41 offset:3440
	ds_read_b128 v[126:129], v41 offset:3952
	ds_read_b128 v[130:133], v41 offset:4464
	global_load_dword v136, v40, s[44:45]
	s_add_u32 s44, s44, 0x1000
	s_addc_u32 s45, s45, 0
	global_load_dword v194, v40, s[44:45]
	s_add_u32 s44, s44, 0x1000
	s_addc_u32 s45, s45, 0
	global_load_dword v195, v40, s[44:45]
	s_add_u32 s44, s44, 0x1000
	s_addc_u32 s45, s45, 0
	global_load_dword v24, v40, s[44:45]
	s_add_u32 s44, s44, 0x1000
	s_addc_u32 s45, s45, 0
	s_waitcnt lgkmcnt(9)
	s_waitcnt vmcnt(28)
	v_mul_f32_e32 v25, v25, v218
	v_fmac_f32_e32 v210, v146, v25
	v_fmac_f32_e32 v211, v150, v25
	v_fmac_f32_e32 v212, v154, v25
	v_fmac_f32_e32 v213, v158, v25
	v_fmac_f32_e32 v214, v162, v25
	v_fmac_f32_e32 v215, v166, v25
	v_fmac_f32_e32 v216, v170, v25
	v_fmac_f32_e32 v217, v174, v25
	v_mul_f32_e32 v26, v26, v219
	v_fmac_f32_e32 v210, v147, v26
	v_fmac_f32_e32 v211, v151, v26
	v_fmac_f32_e32 v212, v155, v26
	v_fmac_f32_e32 v213, v159, v26
	v_fmac_f32_e32 v214, v163, v26
	v_fmac_f32_e32 v215, v167, v26
	v_fmac_f32_e32 v216, v171, v26
	v_fmac_f32_e32 v217, v175, v26
	v_mul_f32_e32 v27, v27, v220
	v_fmac_f32_e32 v210, v148, v27
	v_fmac_f32_e32 v211, v152, v27
	v_fmac_f32_e32 v212, v156, v27
	v_fmac_f32_e32 v213, v160, v27
	v_fmac_f32_e32 v214, v164, v27
	v_fmac_f32_e32 v215, v168, v27
	v_fmac_f32_e32 v216, v172, v27
	v_fmac_f32_e32 v217, v176, v27
	v_mul_f32_e32 v29, v29, v221
	v_fmac_f32_e32 v210, v149, v29
	v_fmac_f32_e32 v211, v153, v29
	v_fmac_f32_e32 v212, v157, v29
	v_fmac_f32_e32 v213, v161, v29
	v_fmac_f32_e32 v214, v165, v29
	v_fmac_f32_e32 v215, v169, v29
	v_fmac_f32_e32 v216, v173, v29
	v_fmac_f32_e32 v217, v177, v29
	ds_read_b128 v[146:149], v41 offset:384
	ds_read_b128 v[150:153], v41 offset:896
	ds_read_b128 v[154:157], v41 offset:1408
	ds_read_b128 v[158:161], v41 offset:1920
	ds_read_b128 v[162:165], v41 offset:2432
	ds_read_b128 v[166:169], v41 offset:2944
	ds_read_b128 v[170:173], v41 offset:3456
	ds_read_b128 v[174:177], v41 offset:3968
	ds_read_b128 v[218:221], v41 offset:4480
	global_load_dword v25, v40, s[44:45]
	s_add_u32 s44, s44, 0x1000
	s_addc_u32 s45, s45, 0
	global_load_dword v26, v40, s[44:45]
	s_add_u32 s44, s44, 0x1000
	s_addc_u32 s45, s45, 0
	global_load_dword v27, v40, s[44:45]
	s_add_u32 s44, s44, 0x1000
	s_addc_u32 s45, s45, 0
	global_load_dword v29, v40, s[44:45]
	s_add_u32 s44, s44, 0x1000
	s_addc_u32 s45, s45, 0
	s_waitcnt lgkmcnt(9)
	s_waitcnt vmcnt(28)
	v_mul_f32_e32 v30, v30, v130
	v_fmac_f32_e32 v210, v178, v30
	v_fmac_f32_e32 v211, v182, v30
	v_fmac_f32_e32 v212, v186, v30
	v_fmac_f32_e32 v213, v190, v30
	v_fmac_f32_e32 v214, v114, v30
	v_fmac_f32_e32 v215, v118, v30
	v_fmac_f32_e32 v216, v122, v30
	v_fmac_f32_e32 v217, v126, v30
	v_mul_f32_e32 v31, v31, v131
	v_fmac_f32_e32 v210, v179, v31
	v_fmac_f32_e32 v211, v183, v31
	v_fmac_f32_e32 v212, v187, v31
	v_fmac_f32_e32 v213, v191, v31
	v_fmac_f32_e32 v214, v115, v31
	v_fmac_f32_e32 v215, v119, v31
	v_fmac_f32_e32 v216, v123, v31
	v_fmac_f32_e32 v217, v127, v31
	v_mul_f32_e32 v32, v32, v132
	v_fmac_f32_e32 v210, v180, v32
	v_fmac_f32_e32 v211, v184, v32
	v_fmac_f32_e32 v212, v188, v32
	v_fmac_f32_e32 v213, v192, v32
	v_fmac_f32_e32 v214, v116, v32
	v_fmac_f32_e32 v215, v120, v32
	v_fmac_f32_e32 v216, v124, v32
	v_fmac_f32_e32 v217, v128, v32
	v_mul_f32_e32 v33, v33, v133
	v_fmac_f32_e32 v210, v181, v33
	v_fmac_f32_e32 v211, v185, v33
	v_fmac_f32_e32 v212, v189, v33
	v_fmac_f32_e32 v213, v193, v33
	v_fmac_f32_e32 v214, v117, v33
	v_fmac_f32_e32 v215, v121, v33
	v_fmac_f32_e32 v216, v125, v33
	v_fmac_f32_e32 v217, v129, v33
	ds_read_b128 v[178:181], v41 offset:400
	ds_read_b128 v[182:185], v41 offset:912
	ds_read_b128 v[186:189], v41 offset:1424
	ds_read_b128 v[190:193], v41 offset:1936
	ds_read_b128 v[114:117], v41 offset:2448
	ds_read_b128 v[118:121], v41 offset:2960
	ds_read_b128 v[122:125], v41 offset:3472
	ds_read_b128 v[126:129], v41 offset:3984
	ds_read_b128 v[130:133], v41 offset:4496
	global_load_dword v30, v40, s[44:45]
	s_add_u32 s44, s44, 0x1000
	s_addc_u32 s45, s45, 0
	global_load_dword v31, v40, s[44:45]
	s_add_u32 s44, s44, 0x1000
	s_addc_u32 s45, s45, 0
	global_load_dword v32, v40, s[44:45]
	s_add_u32 s44, s44, 0x1000
	s_addc_u32 s45, s45, 0
	global_load_dword v33, v40, s[44:45]
	s_add_u32 s44, s44, 0x1000
	s_addc_u32 s45, s45, 0
	s_waitcnt lgkmcnt(9)
; __device__ __forceinline__ void phase_prologue(PtrTab TB, unsigned char* ws, float* xout, int l, LAS unsigned char* lds, int gw, int NGW, int lane, int wave) {
;     ...
; #pragma unroll 16
;           for (int j = 0; j < 128; ++j) { const float u = ua[(size_t)j * D] * sc[j];
; #pragma unroll
;               for (int c = 0; c < 8; ++c) acc[c] += wp[c * 128 + j] * u; }
	s_waitcnt vmcnt(28)
	v_mul_f32_e32 v242, v242, v218
	v_fmac_f32_e32 v210, v146, v242
	v_fmac_f32_e32 v211, v150, v242
	v_fmac_f32_e32 v212, v154, v242
	v_fmac_f32_e32 v213, v158, v242
	v_fmac_f32_e32 v214, v162, v242
	v_fmac_f32_e32 v215, v166, v242
	v_fmac_f32_e32 v216, v170, v242
	v_fmac_f32_e32 v217, v174, v242
	v_mul_f32_e32 v243, v243, v219
	v_fmac_f32_e32 v210, v147, v243
	v_fmac_f32_e32 v211, v151, v243
	v_fmac_f32_e32 v212, v155, v243
	v_fmac_f32_e32 v213, v159, v243
	v_fmac_f32_e32 v214, v163, v243
	v_fmac_f32_e32 v215, v167, v243
	v_fmac_f32_e32 v216, v171, v243
	v_fmac_f32_e32 v217, v175, v243
	v_mul_f32_e32 v244, v244, v220
	v_fmac_f32_e32 v210, v148, v244
	v_fmac_f32_e32 v211, v152, v244
	v_fmac_f32_e32 v212, v156, v244
	v_fmac_f32_e32 v213, v160, v244
	v_fmac_f32_e32 v214, v164, v244
	v_fmac_f32_e32 v215, v168, v244
	v_fmac_f32_e32 v216, v172, v244
	v_fmac_f32_e32 v217, v176, v244
	v_mul_f32_e32 v245, v245, v221
	v_fmac_f32_e32 v210, v149, v245
	v_fmac_f32_e32 v211, v153, v245
	v_fmac_f32_e32 v212, v157, v245
	v_fmac_f32_e32 v213, v161, v245
	v_fmac_f32_e32 v214, v165, v245
	v_fmac_f32_e32 v215, v169, v245
	v_fmac_f32_e32 v216, v173, v245
	v_fmac_f32_e32 v217, v177, v245
	ds_read_b128 v[146:149], v41 offset:416
	ds_read_b128 v[150:153], v41 offset:928
	ds_read_b128 v[154:157], v41 offset:1440
	ds_read_b128 v[158:161], v41 offset:1952
	ds_read_b128 v[162:165], v41 offset:2464
	ds_read_b128 v[166:169], v41 offset:2976
	ds_read_b128 v[170:173], v41 offset:3488
	ds_read_b128 v[174:177], v41 offset:4000
	ds_read_b128 v[218:221], v41 offset:4512
	s_waitcnt lgkmcnt(9)
	s_waitcnt vmcnt(24)
	v_mul_f32_e32 v246, v246, v130
	v_fmac_f32_e32 v210, v178, v246
	v_fmac_f32_e32 v211, v182, v246
	v_fmac_f32_e32 v212, v186, v246
	v_fmac_f32_e32 v213, v190, v246
	v_fmac_f32_e32 v214, v114, v246
	v_fmac_f32_e32 v215, v118, v246
	v_fmac_f32_e32 v216, v122, v246
	v_fmac_f32_e32 v217, v126, v246
	v_mul_f32_e32 v247, v247, v131
	v_fmac_f32_e32 v210, v179, v247
	v_fmac_f32_e32 v211, v183, v247
	v_fmac_f32_e32 v212, v187, v247
	v_fmac_f32_e32 v213, v191, v247
	v_fmac_f32_e32 v214, v115, v247
	v_fmac_f32_e32 v215, v119, v247
	v_fmac_f32_e32 v216, v123, v247
	v_fmac_f32_e32 v217, v127, v247
	v_mul_f32_e32 v248, v248, v132
	v_fmac_f32_e32 v210, v180, v248
	v_fmac_f32_e32 v211, v184, v248
	v_fmac_f32_e32 v212, v188, v248
	v_fmac_f32_e32 v213, v192, v248
	v_fmac_f32_e32 v214, v116, v248
	v_fmac_f32_e32 v215, v120, v248
	v_fmac_f32_e32 v216, v124, v248
	v_fmac_f32_e32 v217, v128, v248
	v_mul_f32_e32 v249, v249, v133
	v_fmac_f32_e32 v210, v181, v249
	v_fmac_f32_e32 v211, v185, v249
	v_fmac_f32_e32 v212, v189, v249
	v_fmac_f32_e32 v213, v193, v249
	v_fmac_f32_e32 v214, v117, v249
	v_fmac_f32_e32 v215, v121, v249
	v_fmac_f32_e32 v216, v125, v249
	v_fmac_f32_e32 v217, v129, v249
	ds_read_b128 v[178:181], v41 offset:432
	ds_read_b128 v[182:185], v41 offset:944
	ds_read_b128 v[186:189], v41 offset:1456
	ds_read_b128 v[190:193], v41 offset:1968
	ds_read_b128 v[114:117], v41 offset:2480
	ds_read_b128 v[118:121], v41 offset:2992
	ds_read_b128 v[122:125], v41 offset:3504
	ds_read_b128 v[126:129], v41 offset:4016
	ds_read_b128 v[130:133], v41 offset:4528
	s_waitcnt lgkmcnt(9)
	s_waitcnt vmcnt(20)
	v_mul_f32_e32 v250, v250, v218
	v_fmac_f32_e32 v210, v146, v250
	v_fmac_f32_e32 v211, v150, v250
	v_fmac_f32_e32 v212, v154, v250
	v_fmac_f32_e32 v213, v158, v250
	v_fmac_f32_e32 v214, v162, v250
	v_fmac_f32_e32 v215, v166, v250
	v_fmac_f32_e32 v216, v170, v250
	v_fmac_f32_e32 v217, v174, v250
	v_mul_f32_e32 v251, v251, v219
	v_fmac_f32_e32 v210, v147, v251
	v_fmac_f32_e32 v211, v151, v251
	v_fmac_f32_e32 v212, v155, v251
	v_fmac_f32_e32 v213, v159, v251
	v_fmac_f32_e32 v214, v163, v251
	v_fmac_f32_e32 v215, v167, v251
	v_fmac_f32_e32 v216, v171, v251
	v_fmac_f32_e32 v217, v175, v251
	v_mul_f32_e32 v252, v252, v220
	v_fmac_f32_e32 v210, v148, v252
	v_fmac_f32_e32 v211, v152, v252
	v_fmac_f32_e32 v212, v156, v252
	v_fmac_f32_e32 v213, v160, v252
	v_fmac_f32_e32 v214, v164, v252
	v_fmac_f32_e32 v215, v168, v252
	v_fmac_f32_e32 v216, v172, v252
	v_fmac_f32_e32 v217, v176, v252
	v_mul_f32_e32 v253, v253, v221
	v_fmac_f32_e32 v210, v149, v253
	v_fmac_f32_e32 v211, v153, v253
	v_fmac_f32_e32 v212, v157, v253
	v_fmac_f32_e32 v213, v161, v253
	v_fmac_f32_e32 v214, v165, v253
	v_fmac_f32_e32 v215, v169, v253
	v_fmac_f32_e32 v216, v173, v253
	v_fmac_f32_e32 v217, v177, v253
	ds_read_b128 v[146:149], v41 offset:448
	ds_read_b128 v[150:153], v41 offset:960
	ds_read_b128 v[154:157], v41 offset:1472
	ds_read_b128 v[158:161], v41 offset:1984
	ds_read_b128 v[162:165], v41 offset:2496
	ds_read_b128 v[166:169], v41 offset:3008
	ds_read_b128 v[170:173], v41 offset:3520
	ds_read_b128 v[174:177], v41 offset:4032
	ds_read_b128 v[218:221], v41 offset:4544
	s_waitcnt lgkmcnt(9)
	s_waitcnt vmcnt(16)
	v_mul_f32_e32 v230, v230, v130
	v_fmac_f32_e32 v210, v178, v230
	v_fmac_f32_e32 v211, v182, v230
	v_fmac_f32_e32 v212, v186, v230
	v_fmac_f32_e32 v213, v190, v230
	v_fmac_f32_e32 v214, v114, v230
	v_fmac_f32_e32 v215, v118, v230
	v_fmac_f32_e32 v216, v122, v230
	v_fmac_f32_e32 v217, v126, v230
	v_mul_f32_e32 v231, v231, v131
	v_fmac_f32_e32 v210, v179, v231
	v_fmac_f32_e32 v211, v183, v231
	v_fmac_f32_e32 v212, v187, v231
	v_fmac_f32_e32 v213, v191, v231
	v_fmac_f32_e32 v214, v115, v231
	v_fmac_f32_e32 v215, v119, v231
	v_fmac_f32_e32 v216, v123, v231
	v_fmac_f32_e32 v217, v127, v231
	v_mul_f32_e32 v232, v232, v132
	v_fmac_f32_e32 v210, v180, v232
	v_fmac_f32_e32 v211, v184, v232
	v_fmac_f32_e32 v212, v188, v232
	v_fmac_f32_e32 v213, v192, v232
	v_fmac_f32_e32 v214, v116, v232
	v_fmac_f32_e32 v215, v120, v232
	v_fmac_f32_e32 v216, v124, v232
	v_fmac_f32_e32 v217, v128, v232
	v_mul_f32_e32 v233, v233, v133
	v_fmac_f32_e32 v210, v181, v233
	v_fmac_f32_e32 v211, v185, v233
	v_fmac_f32_e32 v212, v189, v233
	v_fmac_f32_e32 v213, v193, v233
	v_fmac_f32_e32 v214, v117, v233
	v_fmac_f32_e32 v215, v121, v233
	v_fmac_f32_e32 v216, v125, v233
	v_fmac_f32_e32 v217, v129, v233
	ds_read_b128 v[178:181], v41 offset:464
	ds_read_b128 v[182:185], v41 offset:976
	ds_read_b128 v[186:189], v41 offset:1488
	ds_read_b128 v[190:193], v41 offset:2000
	ds_read_b128 v[114:117], v41 offset:2512
	ds_read_b128 v[118:121], v41 offset:3024
	ds_read_b128 v[122:125], v41 offset:3536
	ds_read_b128 v[126:129], v41 offset:4048
	ds_read_b128 v[130:133], v41 offset:4560
	s_waitcnt lgkmcnt(9)
; __device__ __forceinline__ unsigned pk2(float lo, float hi) { return f2bf(lo) | (f2bf(hi) << 16); }
; __device__ __forceinline__ void phase_prologue(PtrTab TB, unsigned char* ws, float* xout, int l, LAS unsigned char* lds, int gw, int NGW, int lane, int wave) {
;     ...
;           for (int j = 0; j < 128; ++j) { const float u = ua[(size_t)j * D] * sc[j];
; #pragma unroll
;               for (int c = 0; c < 8; ++c) acc[c] += wp[c * 128 + j] * u; }
;           v4u o; o.x = pk2(acc[0], acc[1]); o.y = pk2(acc[2], acc[3]); o.z = pk2(acc[4], acc[5]); o.w = pk2(acc[6], acc[7]);
;           *(v4u*)(UaT + (size_t)n * 512 + g * 128 + c0) = o; } }
	s_waitcnt vmcnt(12)
	v_mul_f32_e32 v222, v222, v218
	v_fmac_f32_e32 v210, v146, v222
	v_fmac_f32_e32 v211, v150, v222
	v_fmac_f32_e32 v212, v154, v222
	v_fmac_f32_e32 v213, v158, v222
	v_fmac_f32_e32 v214, v162, v222
	v_fmac_f32_e32 v215, v166, v222
	v_fmac_f32_e32 v216, v170, v222
	v_fmac_f32_e32 v217, v174, v222
	v_mul_f32_e32 v223, v223, v219
	v_fmac_f32_e32 v210, v147, v223
	v_fmac_f32_e32 v211, v151, v223
	v_fmac_f32_e32 v212, v155, v223
	v_fmac_f32_e32 v213, v159, v223
	v_fmac_f32_e32 v214, v163, v223
	v_fmac_f32_e32 v215, v167, v223
	v_fmac_f32_e32 v216, v171, v223
	v_fmac_f32_e32 v217, v175, v223
	v_mul_f32_e32 v134, v134, v220
	v_fmac_f32_e32 v210, v148, v134
	v_fmac_f32_e32 v211, v152, v134
	v_fmac_f32_e32 v212, v156, v134
	v_fmac_f32_e32 v213, v160, v134
	v_fmac_f32_e32 v214, v164, v134
	v_fmac_f32_e32 v215, v168, v134
	v_fmac_f32_e32 v216, v172, v134
	v_fmac_f32_e32 v217, v176, v134
	v_mul_f32_e32 v135, v135, v221
	v_fmac_f32_e32 v210, v149, v135
	v_fmac_f32_e32 v211, v153, v135
	v_fmac_f32_e32 v212, v157, v135
	v_fmac_f32_e32 v213, v161, v135
	v_fmac_f32_e32 v214, v165, v135
	v_fmac_f32_e32 v215, v169, v135
	v_fmac_f32_e32 v216, v173, v135
	v_fmac_f32_e32 v217, v177, v135
	ds_read_b128 v[146:149], v41 offset:480
	ds_read_b128 v[150:153], v41 offset:992
	ds_read_b128 v[154:157], v41 offset:1504
	ds_read_b128 v[158:161], v41 offset:2016
	ds_read_b128 v[162:165], v41 offset:2528
	ds_read_b128 v[166:169], v41 offset:3040
	ds_read_b128 v[170:173], v41 offset:3552
	ds_read_b128 v[174:177], v41 offset:4064
	ds_read_b128 v[218:221], v41 offset:4576
	s_waitcnt lgkmcnt(9)
	s_waitcnt vmcnt(8)
	v_mul_f32_e32 v136, v136, v130
	v_fmac_f32_e32 v210, v178, v136
	v_fmac_f32_e32 v211, v182, v136
	v_fmac_f32_e32 v212, v186, v136
	v_fmac_f32_e32 v213, v190, v136
	v_fmac_f32_e32 v214, v114, v136
	v_fmac_f32_e32 v215, v118, v136
	v_fmac_f32_e32 v216, v122, v136
	v_fmac_f32_e32 v217, v126, v136
	v_mul_f32_e32 v194, v194, v131
	v_fmac_f32_e32 v210, v179, v194
	v_fmac_f32_e32 v211, v183, v194
	v_fmac_f32_e32 v212, v187, v194
	v_fmac_f32_e32 v213, v191, v194
	v_fmac_f32_e32 v214, v115, v194
	v_fmac_f32_e32 v215, v119, v194
	v_fmac_f32_e32 v216, v123, v194
	v_fmac_f32_e32 v217, v127, v194
	v_mul_f32_e32 v195, v195, v132
	v_fmac_f32_e32 v210, v180, v195
	v_fmac_f32_e32 v211, v184, v195
	v_fmac_f32_e32 v212, v188, v195
	v_fmac_f32_e32 v213, v192, v195
	v_fmac_f32_e32 v214, v116, v195
	v_fmac_f32_e32 v215, v120, v195
	v_fmac_f32_e32 v216, v124, v195
	v_fmac_f32_e32 v217, v128, v195
	v_mul_f32_e32 v24, v24, v133
	v_fmac_f32_e32 v210, v181, v24
	v_fmac_f32_e32 v211, v185, v24
	v_fmac_f32_e32 v212, v189, v24
	v_fmac_f32_e32 v213, v193, v24
	v_fmac_f32_e32 v214, v117, v24
	v_fmac_f32_e32 v215, v121, v24
	v_fmac_f32_e32 v216, v125, v24
	v_fmac_f32_e32 v217, v129, v24
	ds_read_b128 v[178:181], v41 offset:496
	ds_read_b128 v[182:185], v41 offset:1008
	ds_read_b128 v[186:189], v41 offset:1520
	ds_read_b128 v[190:193], v41 offset:2032
	ds_read_b128 v[114:117], v41 offset:2544
	ds_read_b128 v[118:121], v41 offset:3056
	ds_read_b128 v[122:125], v41 offset:3568
	ds_read_b128 v[126:129], v41 offset:4080
	ds_read_b128 v[130:133], v41 offset:4592
	s_waitcnt lgkmcnt(9)
	s_waitcnt vmcnt(4)
	v_mul_f32_e32 v25, v25, v218
	v_fmac_f32_e32 v210, v146, v25
	v_fmac_f32_e32 v211, v150, v25
	v_fmac_f32_e32 v212, v154, v25
	v_fmac_f32_e32 v213, v158, v25
	v_fmac_f32_e32 v214, v162, v25
	v_fmac_f32_e32 v215, v166, v25
	v_fmac_f32_e32 v216, v170, v25
	v_fmac_f32_e32 v217, v174, v25
	v_mul_f32_e32 v26, v26, v219
	v_fmac_f32_e32 v210, v147, v26
	v_fmac_f32_e32 v211, v151, v26
	v_fmac_f32_e32 v212, v155, v26
	v_fmac_f32_e32 v213, v159, v26
	v_fmac_f32_e32 v214, v163, v26
	v_fmac_f32_e32 v215, v167, v26
	v_fmac_f32_e32 v216, v171, v26
	v_fmac_f32_e32 v217, v175, v26
	v_mul_f32_e32 v27, v27, v220
	v_fmac_f32_e32 v210, v148, v27
	v_fmac_f32_e32 v211, v152, v27
	v_fmac_f32_e32 v212, v156, v27
	v_fmac_f32_e32 v213, v160, v27
	v_fmac_f32_e32 v214, v164, v27
	v_fmac_f32_e32 v215, v168, v27
	v_fmac_f32_e32 v216, v172, v27
	v_fmac_f32_e32 v217, v176, v27
	v_mul_f32_e32 v29, v29, v221
	v_fmac_f32_e32 v210, v149, v29
	v_fmac_f32_e32 v211, v153, v29
	v_fmac_f32_e32 v212, v157, v29
	v_fmac_f32_e32 v213, v161, v29
	v_fmac_f32_e32 v214, v165, v29
	v_fmac_f32_e32 v215, v169, v29
	v_fmac_f32_e32 v216, v173, v29
	v_fmac_f32_e32 v217, v177, v29
	s_waitcnt lgkmcnt(0)
	s_waitcnt vmcnt(0)
	v_mul_f32_e32 v30, v30, v130
	v_fmac_f32_e32 v210, v178, v30
	v_fmac_f32_e32 v211, v182, v30
	v_fmac_f32_e32 v212, v186, v30
	v_fmac_f32_e32 v213, v190, v30
	v_fmac_f32_e32 v214, v114, v30
	v_fmac_f32_e32 v215, v118, v30
	v_fmac_f32_e32 v216, v122, v30
	v_fmac_f32_e32 v217, v126, v30
	v_mul_f32_e32 v31, v31, v131
	v_fmac_f32_e32 v210, v179, v31
	v_fmac_f32_e32 v211, v183, v31
	v_fmac_f32_e32 v212, v187, v31
	v_fmac_f32_e32 v213, v191, v31
	v_fmac_f32_e32 v214, v115, v31
	v_fmac_f32_e32 v215, v119, v31
	v_fmac_f32_e32 v216, v123, v31
	v_fmac_f32_e32 v217, v127, v31
	v_mul_f32_e32 v32, v32, v132
	v_fmac_f32_e32 v210, v180, v32
	v_fmac_f32_e32 v211, v184, v32
	v_fmac_f32_e32 v212, v188, v32
	v_fmac_f32_e32 v213, v192, v32
	v_fmac_f32_e32 v214, v116, v32
	v_fmac_f32_e32 v215, v120, v32
	v_fmac_f32_e32 v216, v124, v32
	v_fmac_f32_e32 v217, v128, v32
	v_mul_f32_e32 v33, v33, v133
	v_fmac_f32_e32 v210, v181, v33
	v_fmac_f32_e32 v211, v185, v33
	v_fmac_f32_e32 v212, v189, v33
	v_fmac_f32_e32 v213, v193, v33
	v_fmac_f32_e32 v214, v117, v33
	v_fmac_f32_e32 v215, v121, v33
	v_fmac_f32_e32 v216, v125, v33
	v_fmac_f32_e32 v217, v129, v33
	v_cvt_pk_bf16_f32 v48, v210, v211
	v_cvt_pk_bf16_f32 v49, v212, v213
	v_cvt_pk_bf16_f32 v50, v214, v215
	v_cvt_pk_bf16_f32 v51, v216, v217
	s_lshl_b32 s21, s9, 15
	s_add_u32 s21, s21, s20
	s_add_u32 s21, s21, s13
	s_lshl_b32 s21, s21, 1
	s_add_u32 s21, s21, 0x2700000
	s_add_u32 s24, s82, s21
	s_addc_u32 s25, s83, 0
	global_store_dwordx4 v45, v[48:51], s[24:25]
	s_add_i32 s5, s5, s8
	s_cmpk_gt_i32 s5, 0x3ff
	s_cbranch_scc0 .LUa_item

; template <class Epi, class Sched, bool ALIGN_EPI = false, bool SP2 = false>
; __device__ __forceinline__ void gemm_phase(PG8_LAS unsigned char* lds, const Gemm g, const Sched& S, const Epi& E) {
;     ...
;         const char* nA = has_next ? (const char*)g.A + (size_t)nxt.pm * tstepA + (size_t)nxt.pn * g.a_pn_off * 2 : cA; const char* nB = has_next ? (const char*)g.Bt + (size_t)nxt.pn * tstepB : cB;
;         for (int t = 0; t < nt; t += 2) {
;             const bool last = (t == nt - 2);
;             const char* a1 = cA + (size_t)(t + 1) * kstep;
;             const char* a2 = last ? nA : cA + (size_t)(t + 2) * kstep; const char* b2 = last ? nB : cB + (size_t)(t + 2) * kstep;
;             const char* a3 = a2 + kstep; const char* b3 = b2 + kstep;
;     ...
;         for (int a = 0; a < 2; ++a)
; #pragma unroll
;             for (int b = 0; b < 2; ++b)
; #pragma unroll
;                 for (int m = 0; m < 4; ++m)
; #pragma unroll
;                     for (int n = 0; n < 2; ++n) acc[a][b][m][n] = (f32x4){0.f, 0.f, 0.f, 0.f};
.LBB0_303:
	s_ashr_i32 s13, s12, 31
	s_lshl_b64 s[6:7], s[12:13], 19
	s_add_u32 s14, s26, s6
	s_addc_u32 s15, s27, s7
	s_and_b64 s[6:7], s[2:3], exec
	s_cselect_b32 s6, s15, s19
	s_cselect_b32 s7, s14, s18
	s_ashr_i32 s11, s10, 31
	s_lshl_b64 s[16:17], s[10:11], 19
	s_add_u32 s16, s39, s16
	s_addc_u32 s17, s44, s17
	s_and_b64 s[22:23], s[2:3], exec
	s_cselect_b32 s11, s17, s21
	s_cselect_b32 s13, s16, s20
	s_add_u32 s18, s18, 0x40080
	s_addc_u32 s19, s19, 0
	s_add_u32 s22, s20, 0x100
	v_mov_b32_e32 v0, 0
	s_addc_u32 s23, s21, 0
	s_mov_b32 s24, -2
	v_mov_b32_e32 v1, v0
	v_mov_b32_e32 v2, v0
	v_mov_b32_e32 v3, v0
	v_mov_b32_e32 v4, v0
	v_mov_b32_e32 v5, v0
	v_mov_b32_e32 v6, v0
	v_mov_b32_e32 v7, v0
	v_mov_b32_e32 v16, v0
	v_mov_b32_e32 v17, v0
	v_mov_b32_e32 v18, v0
	v_mov_b32_e32 v19, v0
	v_mov_b32_e32 v20, v0
	v_mov_b32_e32 v21, v0
	v_mov_b32_e32 v22, v0
	v_mov_b32_e32 v23, v0
	v_mov_b32_e32 v32, v0
	v_mov_b32_e32 v33, v0
	v_mov_b32_e32 v34, v0
	v_mov_b32_e32 v35, v0
	v_mov_b32_e32 v36, v0
	v_mov_b32_e32 v37, v0
	v_mov_b32_e32 v38, v0
	v_mov_b32_e32 v39, v0
	v_mov_b32_e32 v48, v0
	v_mov_b32_e32 v49, v0
	v_mov_b32_e32 v50, v0
	v_mov_b32_e32 v51, v0
	v_mov_b32_e32 v52, v0
	v_mov_b32_e32 v53, v0
	v_mov_b32_e32 v54, v0
	v_mov_b32_e32 v55, v0
	v_mov_b32_e32 v8, v0
	v_mov_b32_e32 v9, v0
	v_mov_b32_e32 v10, v0
	v_mov_b32_e32 v11, v0
	v_mov_b32_e32 v12, v0
	v_mov_b32_e32 v13, v0
	v_mov_b32_e32 v14, v0
	v_mov_b32_e32 v15, v0
	v_mov_b32_e32 v24, v0
	v_mov_b32_e32 v25, v0
	v_mov_b32_e32 v26, v0
	v_mov_b32_e32 v27, v0
	v_mov_b32_e32 v28, v0
	v_mov_b32_e32 v29, v0
	v_mov_b32_e32 v30, v0
	v_mov_b32_e32 v31, v0
	v_mov_b32_e32 v40, v0
	v_mov_b32_e32 v41, v0
	v_mov_b32_e32 v42, v0
	v_mov_b32_e32 v43, v0
	v_mov_b32_e32 v44, v0
	v_mov_b32_e32 v45, v0
	v_mov_b32_e32 v46, v0
	v_mov_b32_e32 v47, v0
	v_mov_b32_e32 v56, v0
	v_mov_b32_e32 v57, v0
	v_mov_b32_e32 v58, v0
	v_mov_b32_e32 v59, v0
	v_mov_b32_e32 v60, v0
	v_mov_b32_e32 v61, v0
	v_mov_b32_e32 v62, v0
	v_mov_b32_e32 v63, v0
	v_mov_b32_e32 v66, v0
	v_mov_b32_e32 v67, v0
	v_mov_b32_e32 v68, v0
	v_mov_b32_e32 v69, v0
	v_mov_b32_e32 v70, v0
	v_mov_b32_e32 v71, v0
	v_mov_b32_e32 v72, v0
	v_mov_b32_e32 v73, v0
	v_mov_b32_e32 v82, v0
	v_mov_b32_e32 v83, v0
	v_mov_b32_e32 v84, v0
	v_mov_b32_e32 v85, v0
	v_mov_b32_e32 v86, v0
	v_mov_b32_e32 v87, v0
	v_mov_b32_e32 v88, v0
	v_mov_b32_e32 v89, v0
	v_mov_b32_e32 v98, v0
	v_mov_b32_e32 v99, v0
	v_mov_b32_e32 v100, v0
	v_mov_b32_e32 v101, v0
	v_mov_b32_e32 v102, v0
	v_mov_b32_e32 v103, v0
	v_mov_b32_e32 v104, v0
	v_mov_b32_e32 v105, v0
	v_mov_b32_e32 v114, v0
	v_mov_b32_e32 v115, v0
	v_mov_b32_e32 v116, v0
	v_mov_b32_e32 v117, v0
	v_mov_b32_e32 v118, v0
	v_mov_b32_e32 v119, v0
	v_mov_b32_e32 v120, v0
	v_mov_b32_e32 v121, v0
	v_mov_b32_e32 v74, v0
	v_mov_b32_e32 v75, v0
	v_mov_b32_e32 v76, v0
	v_mov_b32_e32 v77, v0
	v_mov_b32_e32 v78, v0
	v_mov_b32_e32 v79, v0
	v_mov_b32_e32 v80, v0
	v_mov_b32_e32 v81, v0
	v_mov_b32_e32 v90, v0
	v_mov_b32_e32 v91, v0
	v_mov_b32_e32 v92, v0
	v_mov_b32_e32 v93, v0
	v_mov_b32_e32 v94, v0
	v_mov_b32_e32 v95, v0
	v_mov_b32_e32 v96, v0
	v_mov_b32_e32 v97, v0
	v_mov_b32_e32 v106, v0
	v_mov_b32_e32 v107, v0
	v_mov_b32_e32 v108, v0
	v_mov_b32_e32 v109, v0
	v_mov_b32_e32 v110, v0
	v_mov_b32_e32 v111, v0
	v_mov_b32_e32 v112, v0
	v_mov_b32_e32 v113, v0
	v_mov_b32_e32 v122, v0
	v_mov_b32_e32 v123, v0
	v_mov_b32_e32 v124, v0
	v_mov_b32_e32 v125, v0
	v_mov_b32_e32 v126, v0
	v_mov_b32_e32 v127, v0
	v_mov_b32_e32 v128, v0
	v_mov_b32_e32 v129, v0

;     __device__ __forceinline__ bool next(int i, Unit& u) const { if (i) return false; u.pm = pm; u.pn = pn; return true; }
; #define PG8_STAGE(bufoff, gbase, voff) do { _Pragma("unroll") for (int _i = 0; _i < 2; ++_i) \
;         __builtin_amdgcn_global_load_lds((const unsigned*)((const char*)(gbase) + (voff)[_i]), (PG8_LAS unsigned*)(lds + (bufoff) + ldsw + _i * 8192), 16, 0, 0); } while (0)
; #define PG8_LDA(dst, b, h) do { _Pragma("unroll") for (int m = 0; m < 4; ++m) _Pragma("unroll") for (int k = 0; k < 2; ++k) dst[m][k] = *(const PG8_LAS bf16x8*)(lds + PG8_SA(b, h) + aoff + m * 2048 + k * 1024); } while (0)
; #define PG8_LDB(dst, b, h) do { _Pragma("unroll") for (int n = 0; n < 2; ++n) _Pragma("unroll") for (int k = 0; k < 2; ++k) dst[n][k] = *(const PG8_LAS bf16x8*)(lds + PG8_SB(b, h) + boff + n * 2048 + k * 1024); } while (0)
; #define PG8_SCHED __builtin_amdgcn_sched_barrier(0)
; template <class Epi, class Sched, bool ALIGN_EPI = false, bool SP2 = false>
; __device__ __forceinline__ void gemm_phase(PG8_LAS unsigned char* lds, const Gemm g, const Sched& S, const Epi& E) {
;     ...
;         const bool has_next = S.next(ui + 1, nxt);
;         const char* nA = has_next ? (const char*)g.A + (size_t)nxt.pm * tstepA + (size_t)nxt.pn * g.a_pn_off * 2 : cA; const char* nB = has_next ? (const char*)g.Bt + (size_t)nxt.pn * tstepB : cB;
;         for (int t = 0; t < nt; t += 2) {
;             const bool last = (t == nt - 2);
;             const char* a1 = cA + (size_t)(t + 1) * kstep;
;             const char* a2 = last ? nA : cA + (size_t)(t + 2) * kstep; const char* b2 = last ? nB : cB + (size_t)(t + 2) * kstep;
;             const char* a3 = a2 + kstep; const char* b3 = b2 + kstep;
;             if (last && has_next) S.a_ready(nxt);
;             if constexpr (SP2) {
;             PG8_LDB(B0, 0, 0); PG8_LDB(B1, 0, 1); PG8_SCHED; PG8_LDA(At, 0, 0); PG8_STAGE(PG8_SA(1, 1), a1 + hstepA, voffA);
;     ...
;         for (int a = 0; a < 2; ++a)
; #pragma unroll
;             for (int b = 0; b < 2; ++b)
; #pragma unroll
;                 for (int m = 0; m < 4; ++m)
; #pragma unroll
;                     for (int n = 0; n < 2; ++n) acc[a][b][m][n] = (f32x4){0.f, 0.f, 0.f, 0.f};
.LBB0_328:
	s_ashr_i32 s13, s12, 31
	s_lshl_b64 s[6:7], s[12:13], 19
	s_add_u32 s16, s43, s6
	s_addc_u32 s17, s44, s7
	s_and_b64 s[6:7], s[8:9], exec
	s_cselect_b32 s6, s17, s21
	s_cselect_b32 s7, s16, s20
	s_ashr_i32 s11, s10, 31
	s_lshl_b64 s[18:19], s[10:11], 19
	s_add_u32 s18, s45, s18
	s_addc_u32 s19, s62, s19
	s_and_b64 s[24:25], s[8:9], exec
	s_cselect_b32 s11, s19, s31
	s_cselect_b32 s13, s18, s30
	s_add_u32 s20, s20, 0x40080
	s_addc_u32 s21, s21, 0
	s_add_u32 s24, s30, 0x100
	v_mov_b32_e32 v0, 0
	s_addc_u32 s25, s31, 0
	s_mov_b32 s60, -2
	v_mov_b32_e32 v1, v0
	v_mov_b32_e32 v2, v0
	v_mov_b32_e32 v3, v0
	v_mov_b32_e32 v4, v0
	v_mov_b32_e32 v5, v0
	v_mov_b32_e32 v6, v0
	v_mov_b32_e32 v7, v0
	v_mov_b32_e32 v8, v0
	v_mov_b32_e32 v9, v0
	v_mov_b32_e32 v10, v0
	v_mov_b32_e32 v11, v0
	v_mov_b32_e32 v16, v0
	v_mov_b32_e32 v17, v0
	v_mov_b32_e32 v18, v0
	v_mov_b32_e32 v19, v0
	v_mov_b32_e32 v24, v0
	v_mov_b32_e32 v25, v0
	v_mov_b32_e32 v26, v0
	v_mov_b32_e32 v27, v0
	v_mov_b32_e32 v32, v0
	v_mov_b32_e32 v33, v0
	v_mov_b32_e32 v34, v0
	v_mov_b32_e32 v35, v0
	v_mov_b32_e32 v40, v0
	v_mov_b32_e32 v41, v0
	v_mov_b32_e32 v42, v0
	v_mov_b32_e32 v43, v0
	v_mov_b32_e32 v48, v0
	v_mov_b32_e32 v49, v0
	v_mov_b32_e32 v50, v0
	v_mov_b32_e32 v51, v0
	v_mov_b32_e32 v12, v0
	v_mov_b32_e32 v13, v0
	v_mov_b32_e32 v14, v0
	v_mov_b32_e32 v15, v0
	v_mov_b32_e32 v20, v0
	v_mov_b32_e32 v21, v0
	v_mov_b32_e32 v22, v0
	v_mov_b32_e32 v23, v0
	v_mov_b32_e32 v28, v0
	v_mov_b32_e32 v29, v0
	v_mov_b32_e32 v30, v0
	v_mov_b32_e32 v31, v0
	v_mov_b32_e32 v36, v0
	v_mov_b32_e32 v37, v0
	v_mov_b32_e32 v38, v0
	v_mov_b32_e32 v39, v0
	v_mov_b32_e32 v44, v0
	v_mov_b32_e32 v45, v0
	v_mov_b32_e32 v46, v0
	v_mov_b32_e32 v47, v0
	v_mov_b32_e32 v52, v0
	v_mov_b32_e32 v53, v0
	v_mov_b32_e32 v54, v0
	v_mov_b32_e32 v55, v0
	v_mov_b32_e32 v56, v0
	v_mov_b32_e32 v57, v0
	v_mov_b32_e32 v58, v0
	v_mov_b32_e32 v59, v0
	v_mov_b32_e32 v60, v0
	v_mov_b32_e32 v61, v0
	v_mov_b32_e32 v62, v0
	v_mov_b32_e32 v63, v0
	v_mov_b32_e32 v66, v0
	v_mov_b32_e32 v67, v0
	v_mov_b32_e32 v68, v0
	v_mov_b32_e32 v69, v0
	v_mov_b32_e32 v70, v0
	v_mov_b32_e32 v71, v0
	v_mov_b32_e32 v72, v0
	v_mov_b32_e32 v73, v0
	v_mov_b32_e32 v74, v0
	v_mov_b32_e32 v75, v0
	v_mov_b32_e32 v76, v0
	v_mov_b32_e32 v77, v0
	v_mov_b32_e32 v82, v0
	v_mov_b32_e32 v83, v0
	v_mov_b32_e32 v84, v0
	v_mov_b32_e32 v85, v0
	v_mov_b32_e32 v90, v0
	v_mov_b32_e32 v91, v0
	v_mov_b32_e32 v92, v0
	v_mov_b32_e32 v93, v0
	v_mov_b32_e32 v98, v0
	v_mov_b32_e32 v99, v0
	v_mov_b32_e32 v100, v0
	v_mov_b32_e32 v101, v0
	v_mov_b32_e32 v106, v0
	v_mov_b32_e32 v107, v0
	v_mov_b32_e32 v108, v0
	v_mov_b32_e32 v109, v0
	v_mov_b32_e32 v114, v0
	v_mov_b32_e32 v115, v0
	v_mov_b32_e32 v116, v0
	v_mov_b32_e32 v117, v0
	v_mov_b32_e32 v78, v0
	v_mov_b32_e32 v79, v0
	v_mov_b32_e32 v80, v0
	v_mov_b32_e32 v81, v0
	v_mov_b32_e32 v86, v0
	v_mov_b32_e32 v87, v0
	v_mov_b32_e32 v88, v0
	v_mov_b32_e32 v89, v0
	v_mov_b32_e32 v94, v0
	v_mov_b32_e32 v95, v0
	v_mov_b32_e32 v96, v0
	v_mov_b32_e32 v97, v0
	v_mov_b32_e32 v102, v0
	v_mov_b32_e32 v103, v0
	v_mov_b32_e32 v104, v0
	v_mov_b32_e32 v105, v0
	v_mov_b32_e32 v110, v0
	v_mov_b32_e32 v111, v0
	v_mov_b32_e32 v112, v0
	v_mov_b32_e32 v113, v0
	v_mov_b32_e32 v118, v0
	v_mov_b32_e32 v119, v0
	v_mov_b32_e32 v120, v0
	v_mov_b32_e32 v121, v0
	v_mov_b32_e32 v122, v0
	v_mov_b32_e32 v123, v0
	v_mov_b32_e32 v124, v0
	v_mov_b32_e32 v125, v0
	v_mov_b32_e32 v126, v0
	v_mov_b32_e32 v127, v0
	v_mov_b32_e32 v128, v0
	v_mov_b32_e32 v129, v0

; #define PG8_STAGE(bufoff, gbase, voff) do { _Pragma("unroll") for (int _i = 0; _i < 2; ++_i) \
;         __builtin_amdgcn_global_load_lds((const unsigned*)((const char*)(gbase) + (voff)[_i]), (PG8_LAS unsigned*)(lds + (bufoff) + ldsw + _i * 8192), 16, 0, 0); } while (0)
; #define PG8_WAIT_V(n) asm volatile("s_waitcnt vmcnt(" #n ")" ::: "memory")
; #define PG8_BAR __builtin_amdgcn_s_barrier()
; template <class Epi, class Sched, bool ALIGN_EPI = false, bool SP2 = false>
; __device__ __forceinline__ void gemm_phase(PG8_LAS unsigned char* lds, const Gemm g, const Sched& S, const Epi& E) {
;     ...
;     f32x4 acc[2][2][4][2];
; #pragma unroll
;     for (int a = 0; a < 2; ++a)
; #pragma unroll
;         for (int b = 0; b < 2; ++b)
; #pragma unroll
;             for (int m = 0; m < 4; ++m)
; #pragma unroll
;                 for (int n = 0; n < 2; ++n) acc[a][b][m][n] = (f32x4){0.f, 0.f, 0.f, 0.f};
;     ...
;         PG8_STAGE(PG8_SB(0, 0), cB, voffB); PG8_STAGE(PG8_SB(0, 1), cB + hstepB, voffB); PG8_STAGE(PG8_SA(0, 0), cA, voffA); PG8_STAGE(PG8_SA(0, 1), cA + hstepA, voffA);
;         if (wr == 1) PG8_BAR;
;         PG8_WAIT_V(2); PG8_BAR;
;         PG8_STAGE(PG8_SB(1, 0), cB + kstep, voffB); PG8_STAGE(PG8_SA(1, 0), cA + kstep, voffA); PG8_STAGE(PG8_SB(1, 1), cB + hstepB + kstep, voffB);
;         PG8_WAIT_V(6); PG8_BAR;
.LBB0_1028:
	v_lshrrev_b32_e32 v16, 1, v4
	v_lshl_add_u64 v[8:9], s[0:1], 0, v[64:65]
	v_mov_b32_e32 v103, v65
	v_and_b32_e32 v116, 24, v16
	s_lshl_b32 s3, s3, 5
	v_lshl_add_u64 v[10:11], s[0:1], 0, v[102:103]
	v_mov_b32_e32 v99, v65
	v_and_b32_e32 v7, 15, v4
	v_lshlrev_b32_e32 v16, 1, v116
	v_lshlrev_b32_e32 v4, 2, v4
	s_and_b32 s60, s3, 0x60
	s_add_i32 m0, s31, 0x18000
	v_lshl_add_u64 v[8:9], v[8:9], 0, s[48:49]
	v_lshl_add_u64 v[12:13], s[10:11], 0, v[98:99]
	v_mov_b32_e32 v101, v65
	v_lshl_or_b32 v146, s2, 6, v7
	v_lshl_or_b32 v7, v7, 6, v16
	v_and_b32_e32 v4, 32, v4
	s_lshl_b32 s2, s2, 13
	s_lshl_b32 s3, s60, 7
	s_waitcnt vmcnt(2)
	s_barrier
	global_load_lds_dwordx4 v[8:9], off
	v_lshl_add_u64 v[8:9], v[10:11], 0, s[48:49]
	s_add_i32 m0, s31, 0x1a000
	s_add_i32 s61, s31, 0x8000
	s_add_i32 vcc_lo, s31, 0xa000
	v_lshl_add_u64 v[14:15], s[10:11], 0, v[100:101]
	v_bitop3_b32 v117, v7, s3, v4 bitop3:0xde
	v_bitop3_b32 v4, v7, s2, v4 bitop3:0xde
	global_load_lds_dwordx4 v[8:9], off
	v_lshl_add_u64 v[8:9], v[12:13], 0, s[48:49]
	s_mov_b32 m0, s61
	s_add_u32 s2, s0, 0x40080
	global_load_lds_dwordx4 v[8:9], off
	v_lshl_add_u64 v[8:9], v[14:15], 0, s[48:49]
	s_mov_b32 m0, vcc_lo
	s_addc_u32 s3, s1, 0
	global_load_lds_dwordx4 v[8:9], off
	s_add_i32 m0, s31, 0x1c000
	v_lshl_add_u64 v[8:9], s[2:3], 0, v[64:65]
	global_load_lds_dwordx4 v[8:9], off
	v_lshl_add_u64 v[8:9], s[2:3], 0, v[102:103]
	s_add_i32 m0, s31, 0x1e000
	v_lshlrev_b32_e32 v7, 14, v0
	global_load_lds_dwordx4 v[8:9], off
	v_and_b32_e32 v7, 0xffff8000, v7
	v_lshl_add_u32 v1, v1, 11, v7
	v_and_b32_e32 v0, 1, v0
	v_lshl_or_b32 v0, v0, 6, v1
	v_lshl_add_u32 v0, v2, 1, v0
	v_mov_b32_e32 v1, v65
	v_lshl_add_u64 v[104:105], s[14:15], 0, v[0:1]
	v_lshlrev_b32_e32 v0, 14, v3
	v_and_b32_e32 v0, 0xffff8000, v0
	v_lshl_add_u32 v0, v5, 11, v0
	v_and_b32_e32 v1, 1, v3
	v_lshl_or_b32 v0, v1, 6, v0
	s_waitcnt vmcnt(6)
	v_lshl_add_u32 v0, v6, 1, v0
	v_mov_b32_e32 v1, v65
	v_lshl_add_u64 v[114:115], s[14:15], 0, v[0:1]
	v_mov_b32_e32 v0, 0
	s_mov_b32 s62, -2
	s_mov_b64 s[2:3], 0
	v_add_u32_e32 v118, 0, v4
	v_mov_b32_e32 v1, v0
	v_mov_b32_e32 v2, v0
	v_mov_b32_e32 v3, v0
	v_mov_b32_e32 v4, v0
	v_mov_b32_e32 v5, v0
	v_mov_b32_e32 v6, v0
	v_mov_b32_e32 v7, v0
	v_mov_b32_e32 v16, v0
	v_mov_b32_e32 v17, v0
	v_mov_b32_e32 v18, v0
	v_mov_b32_e32 v19, v0
	v_mov_b32_e32 v20, v0
	v_mov_b32_e32 v21, v0
	v_mov_b32_e32 v22, v0
	v_mov_b32_e32 v23, v0
	v_mov_b32_e32 v32, v0
	v_mov_b32_e32 v33, v0
	v_mov_b32_e32 v34, v0
	v_mov_b32_e32 v35, v0
	v_mov_b32_e32 v36, v0
	v_mov_b32_e32 v37, v0
	v_mov_b32_e32 v38, v0
	v_mov_b32_e32 v39, v0
	v_mov_b32_e32 v48, v0
	v_mov_b32_e32 v49, v0
	v_mov_b32_e32 v50, v0
	v_mov_b32_e32 v51, v0
	v_mov_b32_e32 v52, v0
	v_mov_b32_e32 v53, v0
	v_mov_b32_e32 v54, v0
	v_mov_b32_e32 v55, v0
	v_mov_b32_e32 v8, v0
	v_mov_b32_e32 v9, v0
	v_mov_b32_e32 v10, v0
	v_mov_b32_e32 v11, v0
	v_mov_b32_e32 v12, v0
	v_mov_b32_e32 v13, v0
	v_mov_b32_e32 v14, v0
	v_mov_b32_e32 v15, v0
	v_mov_b32_e32 v24, v0
	v_mov_b32_e32 v25, v0
	v_mov_b32_e32 v26, v0
	v_mov_b32_e32 v27, v0
	v_mov_b32_e32 v28, v0
	v_mov_b32_e32 v29, v0
	v_mov_b32_e32 v30, v0
	v_mov_b32_e32 v31, v0
	v_mov_b32_e32 v40, v0
	v_mov_b32_e32 v41, v0
	v_mov_b32_e32 v42, v0
	v_mov_b32_e32 v43, v0
	v_mov_b32_e32 v44, v0
	v_mov_b32_e32 v45, v0
	v_mov_b32_e32 v46, v0
	v_mov_b32_e32 v47, v0
	v_mov_b32_e32 v56, v0
	v_mov_b32_e32 v57, v0
	v_mov_b32_e32 v58, v0
	v_mov_b32_e32 v59, v0
	v_mov_b32_e32 v60, v0
	v_mov_b32_e32 v61, v0
	v_mov_b32_e32 v62, v0
	v_mov_b32_e32 v63, v0
	v_mov_b32_e32 v66, v0
	v_mov_b32_e32 v67, v0
	v_mov_b32_e32 v68, v0
	v_mov_b32_e32 v69, v0
	v_mov_b32_e32 v70, v0
	v_mov_b32_e32 v71, v0
	v_mov_b32_e32 v72, v0
	v_mov_b32_e32 v73, v0
	v_mov_b32_e32 v82, v0
	v_mov_b32_e32 v83, v0
	v_mov_b32_e32 v84, v0
	v_mov_b32_e32 v85, v0
	v_mov_b32_e32 v86, v0
	v_mov_b32_e32 v87, v0
	v_mov_b32_e32 v88, v0
	v_mov_b32_e32 v89, v0
	v_mov_b32_e32 v106, v0
	v_mov_b32_e32 v107, v0
	v_mov_b32_e32 v108, v0
	v_mov_b32_e32 v109, v0
	v_mov_b32_e32 v110, v0
	v_mov_b32_e32 v111, v0
	v_mov_b32_e32 v112, v0
	v_mov_b32_e32 v113, v0
	v_mov_b32_e32 v130, v0
	v_mov_b32_e32 v131, v0
	v_mov_b32_e32 v132, v0
	v_mov_b32_e32 v133, v0
	v_mov_b32_e32 v134, v0
	v_mov_b32_e32 v135, v0
	v_mov_b32_e32 v136, v0
	v_mov_b32_e32 v137, v0
	v_mov_b32_e32 v74, v0
	v_mov_b32_e32 v75, v0
	v_mov_b32_e32 v76, v0
	v_mov_b32_e32 v77, v0
	v_mov_b32_e32 v78, v0
	v_mov_b32_e32 v79, v0
	v_mov_b32_e32 v80, v0
	v_mov_b32_e32 v81, v0
	v_mov_b32_e32 v90, v0
	v_mov_b32_e32 v91, v0
	v_mov_b32_e32 v92, v0
	v_mov_b32_e32 v93, v0
	v_mov_b32_e32 v94, v0
	v_mov_b32_e32 v95, v0
	v_mov_b32_e32 v96, v0
	v_mov_b32_e32 v97, v0
	v_mov_b32_e32 v122, v0
	v_mov_b32_e32 v123, v0
	v_mov_b32_e32 v124, v0
	v_mov_b32_e32 v125, v0
	v_mov_b32_e32 v126, v0
	v_mov_b32_e32 v127, v0
	v_mov_b32_e32 v128, v0
	v_mov_b32_e32 v129, v0
	v_mov_b32_e32 v138, v0
	v_mov_b32_e32 v139, v0
	v_mov_b32_e32 v140, v0
	v_mov_b32_e32 v141, v0
	v_mov_b32_e32 v142, v0
	v_mov_b32_e32 v143, v0
	v_mov_b32_e32 v144, v0
	v_mov_b32_e32 v145, v0
	s_barrier

; #define PG8_STAGE(bufoff, gbase, voff) do { _Pragma("unroll") for (int _i = 0; _i < 2; ++_i) \
;         __builtin_amdgcn_global_load_lds((const unsigned*)((const char*)(gbase) + (voff)[_i]), (PG8_LAS unsigned*)(lds + (bufoff) + ldsw + _i * 8192), 16, 0, 0); } while (0)
; #define PG8_WAIT_V(n) asm volatile("s_waitcnt vmcnt(" #n ")" ::: "memory")
; #define PG8_BAR __builtin_amdgcn_s_barrier()
; template <class Epi, class Sched, bool ALIGN_EPI = false, bool SP2 = false>
; __device__ __forceinline__ void gemm_phase(PG8_LAS unsigned char* lds, const Gemm g, const Sched& S, const Epi& E) {
;     ...
;     f32x4 acc[2][2][4][2];
; #pragma unroll
;     for (int a = 0; a < 2; ++a)
; #pragma unroll
;         for (int b = 0; b < 2; ++b)
; #pragma unroll
;             for (int m = 0; m < 4; ++m)
; #pragma unroll
;                 for (int n = 0; n < 2; ++n) acc[a][b][m][n] = (f32x4){0.f, 0.f, 0.f, 0.f};
;     ...
;         PG8_STAGE(PG8_SB(0, 0), cB, voffB); PG8_STAGE(PG8_SB(0, 1), cB + hstepB, voffB); PG8_STAGE(PG8_SA(0, 0), cA, voffA); PG8_STAGE(PG8_SA(0, 1), cA + hstepA, voffA);
;         if (wr == 1) PG8_BAR;
;         PG8_WAIT_V(2); PG8_BAR;
;         PG8_STAGE(PG8_SB(1, 0), cB + kstep, voffB); PG8_STAGE(PG8_SA(1, 0), cA + kstep, voffA); PG8_STAGE(PG8_SB(1, 1), cB + hstepB + kstep, voffB);
;         PG8_WAIT_V(6); PG8_BAR;
.LBB0_1182:
	v_and_b32_e32 v138, 15, v136
	v_and_b32_e32 v14, 48, v136
	v_lshlrev_b32_e32 v137, 2, v138
	s_and_b32 s24, s8, 3
	s_lshl_b32 s8, s9, 13
	v_lshl_or_b32 v14, v138, 6, v14
	v_and_b32_e32 v15, 32, v137
	s_add_i32 m0, s23, 0x18000
	v_lshl_add_u64 v[6:7], v[6:7], 0, s[48:49]
	s_lshl_b32 s30, s9, 6
	v_bitop3_b32 v16, v14, s8, v15 bitop3:0xde
	s_lshl_b32 s8, s24, 12
	s_waitcnt vmcnt(2)
	s_barrier
	global_load_lds_dwordx4 v[6:7], off
	v_lshl_add_u64 v[4:5], v[4:5], 0, s[48:49]
	s_add_i32 m0, s23, 0x1a000
	s_add_i32 s38, s23, 0x8000
	s_add_i32 s39, s23, 0xa000
	v_bitop3_b32 v139, v14, s8, v15 bitop3:0xde
	global_load_lds_dwordx4 v[4:5], off
	v_lshl_add_u64 v[2:3], v[2:3], 0, s[48:49]
	s_mov_b32 m0, s38
	s_add_u32 s8, s0, 0x40080
	global_load_lds_dwordx4 v[2:3], off
	v_lshl_add_u64 v[0:1], v[0:1], 0, s[48:49]
	s_mov_b32 m0, s39
	s_addc_u32 s9, s1, 0
	global_load_lds_dwordx4 v[0:1], off
	s_add_i32 m0, s23, 0x1c000
	v_lshl_add_u64 v[0:1], s[8:9], 0, v[64:65]
	global_load_lds_dwordx4 v[0:1], off
	v_lshl_add_u64 v[0:1], s[8:9], 0, v[130:131]
	s_add_i32 m0, s23, 0x1e000
	s_add_u32 s6, s82, s6
	global_load_lds_dwordx4 v[0:1], off
	v_lshlrev_b32_e32 v0, 14, v8
	v_and_b32_e32 v0, 0xffff8000, v0
	v_lshl_add_u32 v0, v9, 11, v0
	v_and_b32_e32 v1, 1, v8
	v_lshl_or_b32 v0, v1, 6, v0
	v_lshl_add_u32 v0, v11, 1, v0
	v_mov_b32_e32 v1, v65
	s_addc_u32 s7, s83, s7
	v_lshl_add_u64 v[132:133], s[6:7], 0, v[0:1]
	v_lshlrev_b32_e32 v0, 14, v10
	v_and_b32_e32 v0, 0xffff8000, v0
	v_lshl_add_u32 v0, v12, 11, v0
	v_and_b32_e32 v1, 1, v10
	v_lshl_or_b32 v0, v1, 6, v0
	s_waitcnt vmcnt(6)
	v_lshl_add_u32 v0, v13, 1, v0
	v_mov_b32_e32 v1, v65
	v_lshl_add_u64 v[134:135], s[6:7], 0, v[0:1]
	v_mov_b32_e32 v0, 0
	v_or_b32_e32 v179, s30, v138
	s_mov_b32 s43, -2
	s_mov_b64 s[6:7], 0xc640080
	v_add_u32_e32 v140, 0, v16
	v_mov_b32_e32 v1, v0
	v_mov_b32_e32 v2, v0
	v_mov_b32_e32 v3, v0
	v_mov_b32_e32 v4, v0
	v_mov_b32_e32 v5, v0
	v_mov_b32_e32 v6, v0
	v_mov_b32_e32 v7, v0
	v_mov_b32_e32 v16, v0
	v_mov_b32_e32 v17, v0
	v_mov_b32_e32 v18, v0
	v_mov_b32_e32 v19, v0
	v_mov_b32_e32 v20, v0
	v_mov_b32_e32 v21, v0
	v_mov_b32_e32 v22, v0
	v_mov_b32_e32 v23, v0
	v_mov_b32_e32 v32, v0
	v_mov_b32_e32 v33, v0
	v_mov_b32_e32 v34, v0
	v_mov_b32_e32 v35, v0
	v_mov_b32_e32 v36, v0
	v_mov_b32_e32 v37, v0
	v_mov_b32_e32 v38, v0
	v_mov_b32_e32 v39, v0
	v_mov_b32_e32 v48, v0
	v_mov_b32_e32 v49, v0
	v_mov_b32_e32 v50, v0
	v_mov_b32_e32 v51, v0
	v_mov_b32_e32 v52, v0
	v_mov_b32_e32 v53, v0
	v_mov_b32_e32 v54, v0
	v_mov_b32_e32 v55, v0
	v_mov_b32_e32 v8, v0
	v_mov_b32_e32 v9, v0
	v_mov_b32_e32 v10, v0
	v_mov_b32_e32 v11, v0
	v_mov_b32_e32 v12, v0
	v_mov_b32_e32 v13, v0
	v_mov_b32_e32 v14, v0
	v_mov_b32_e32 v15, v0
	v_mov_b32_e32 v24, v0
	v_mov_b32_e32 v25, v0
	v_mov_b32_e32 v26, v0
	v_mov_b32_e32 v27, v0
	v_mov_b32_e32 v28, v0
	v_mov_b32_e32 v29, v0
	v_mov_b32_e32 v30, v0
	v_mov_b32_e32 v31, v0
	v_mov_b32_e32 v40, v0
	v_mov_b32_e32 v41, v0
	v_mov_b32_e32 v42, v0
	v_mov_b32_e32 v43, v0
	v_mov_b32_e32 v44, v0
	v_mov_b32_e32 v45, v0
	v_mov_b32_e32 v46, v0
	v_mov_b32_e32 v47, v0
	v_mov_b32_e32 v56, v0
	v_mov_b32_e32 v57, v0
	v_mov_b32_e32 v58, v0
	v_mov_b32_e32 v59, v0
	v_mov_b32_e32 v60, v0
	v_mov_b32_e32 v61, v0
	v_mov_b32_e32 v62, v0
	v_mov_b32_e32 v63, v0
	v_mov_b32_e32 v66, v0
	v_mov_b32_e32 v67, v0
	v_mov_b32_e32 v68, v0
	v_mov_b32_e32 v69, v0
	v_mov_b32_e32 v70, v0
	v_mov_b32_e32 v71, v0
	v_mov_b32_e32 v72, v0
	v_mov_b32_e32 v73, v0
	v_mov_b32_e32 v82, v0
	v_mov_b32_e32 v83, v0
	v_mov_b32_e32 v84, v0
	v_mov_b32_e32 v85, v0
	v_mov_b32_e32 v86, v0
	v_mov_b32_e32 v87, v0
	v_mov_b32_e32 v88, v0
	v_mov_b32_e32 v89, v0
	v_mov_b32_e32 v98, v0
	v_mov_b32_e32 v99, v0
	v_mov_b32_e32 v100, v0
	v_mov_b32_e32 v101, v0
	v_mov_b32_e32 v102, v0
	v_mov_b32_e32 v103, v0
	v_mov_b32_e32 v104, v0
	v_mov_b32_e32 v105, v0
	v_mov_b32_e32 v114, v0
	v_mov_b32_e32 v115, v0
	v_mov_b32_e32 v116, v0
	v_mov_b32_e32 v117, v0
	v_mov_b32_e32 v118, v0
	v_mov_b32_e32 v119, v0
	v_mov_b32_e32 v120, v0
	v_mov_b32_e32 v121, v0
	v_mov_b32_e32 v74, v0
	v_mov_b32_e32 v75, v0
	v_mov_b32_e32 v76, v0
	v_mov_b32_e32 v77, v0
	v_mov_b32_e32 v78, v0
	v_mov_b32_e32 v79, v0
	v_mov_b32_e32 v80, v0
	v_mov_b32_e32 v81, v0
	v_mov_b32_e32 v90, v0
	v_mov_b32_e32 v91, v0
	v_mov_b32_e32 v92, v0
	v_mov_b32_e32 v93, v0
	v_mov_b32_e32 v94, v0
	v_mov_b32_e32 v95, v0
	v_mov_b32_e32 v96, v0
	v_mov_b32_e32 v97, v0
	v_mov_b32_e32 v106, v0
	v_mov_b32_e32 v107, v0
	v_mov_b32_e32 v108, v0
	v_mov_b32_e32 v109, v0
	v_mov_b32_e32 v110, v0
	v_mov_b32_e32 v111, v0
	v_mov_b32_e32 v112, v0
	v_mov_b32_e32 v113, v0
	v_mov_b32_e32 v122, v0
	v_mov_b32_e32 v123, v0
	v_mov_b32_e32 v124, v0
	v_mov_b32_e32 v125, v0
	v_mov_b32_e32 v126, v0
	v_mov_b32_e32 v127, v0
	v_mov_b32_e32 v128, v0
	v_mov_b32_e32 v129, v0
	s_barrier

; #define PG8_STAGE(bufoff, gbase, voff) do { _Pragma("unroll") for (int _i = 0; _i < 2; ++_i) \
;         __builtin_amdgcn_global_load_lds((const unsigned*)((const char*)(gbase) + (voff)[_i]), (PG8_LAS unsigned*)(lds + (bufoff) + ldsw + _i * 8192), 16, 0, 0); } while (0)
; #define PG8_WAIT_V(n) asm volatile("s_waitcnt vmcnt(" #n ")" ::: "memory")
; #define PG8_BAR __builtin_amdgcn_s_barrier()
; template <class Epi, class Sched, bool ALIGN_EPI = false, bool SP2 = false>
; __device__ __forceinline__ void gemm_phase(PG8_LAS unsigned char* lds, const Gemm g, const Sched& S, const Epi& E) {
;     ...
;     f32x4 acc[2][2][4][2];
; #pragma unroll
;     for (int a = 0; a < 2; ++a)
; #pragma unroll
;         for (int b = 0; b < 2; ++b)
; #pragma unroll
;             for (int m = 0; m < 4; ++m)
; #pragma unroll
;                 for (int n = 0; n < 2; ++n) acc[a][b][m][n] = (f32x4){0.f, 0.f, 0.f, 0.f};
;     ...
;         PG8_STAGE(PG8_SB(0, 0), cB, voffB); PG8_STAGE(PG8_SB(0, 1), cB + hstepB, voffB); PG8_STAGE(PG8_SA(0, 0), cA, voffA); PG8_STAGE(PG8_SA(0, 1), cA + hstepA, voffA);
;         if (wr == 1) PG8_BAR;
;         PG8_WAIT_V(2); PG8_BAR;
;         PG8_STAGE(PG8_SB(1, 0), cB + kstep, voffB); PG8_STAGE(PG8_SA(1, 0), cA + kstep, voffA); PG8_STAGE(PG8_SB(1, 1), cB + hstepB + kstep, voffB);
;         PG8_WAIT_V(6); PG8_BAR;
.LBB0_1263:
	v_lshrrev_b32_e32 v16, 1, v14
	v_and_b32_e32 v164, 24, v16
	s_lshl_b32 s23, s23, 5
	v_and_b32_e32 v15, 15, v14
	v_lshlrev_b32_e32 v16, 1, v164
	v_lshlrev_b32_e32 v14, 2, v14
	s_and_b32 s23, s23, 0x60
	s_add_i32 m0, s84, 0x18000
	v_lshl_add_u64 v[6:7], v[6:7], 0, s[48:49]
	s_lshl_b64 s[14:15], s[0:1], 18
	v_lshl_or_b32 v146, s30, 6, v15
	v_lshl_or_b32 v15, v15, 6, v16
	v_and_b32_e32 v14, 32, v14
	s_lshl_b32 s30, s30, 13
	s_lshl_b32 s31, s23, 7
	s_waitcnt vmcnt(2)
	s_barrier
	global_load_lds_dwordx4 v[6:7], off
	v_lshl_add_u64 v[4:5], v[4:5], 0, s[48:49]
	s_add_i32 m0, s84, 0x1a000
	s_add_i32 s61, s84, 0x8000
	s_add_i32 s87, s84, 0xa000
	v_bitop3_b32 v140, v15, s31, v14 bitop3:0xde
	v_bitop3_b32 v14, v15, s30, v14 bitop3:0xde
	global_load_lds_dwordx4 v[4:5], off
	v_lshl_add_u64 v[2:3], v[2:3], 0, s[48:49]
	s_mov_b32 m0, s61
	s_add_u32 s30, s18, 0x40080
	global_load_lds_dwordx4 v[2:3], off
	v_lshl_add_u64 v[0:1], v[0:1], 0, s[48:49]
	s_mov_b32 m0, s87
	s_addc_u32 s31, s19, 0
	global_load_lds_dwordx4 v[0:1], off
	s_add_i32 m0, s84, 0x1c000
	v_lshl_add_u64 v[0:1], s[30:31], 0, v[64:65]
	global_load_lds_dwordx4 v[0:1], off
	v_lshl_add_u64 v[0:1], s[30:31], 0, v[134:135]
	s_add_i32 m0, s84, 0x1e000
	v_readlane_b32 s30, v254, 3
	global_load_lds_dwordx4 v[0:1], off
	v_lshlrev_b32_e32 v0, 14, v8
	v_and_b32_e32 v0, 0xffff8000, v0
	v_lshl_add_u32 v0, v9, 11, v0
	v_and_b32_e32 v1, 1, v8
	v_lshl_or_b32 v0, v1, 6, v0
	v_readlane_b32 s31, v254, 4
	s_add_u32 s20, s30, s20
	v_lshl_add_u32 v0, v10, 1, v0
	v_mov_b32_e32 v1, v65
	s_addc_u32 s21, s31, s21
	v_lshl_add_u64 v[136:137], s[20:21], 0, v[0:1]
	v_lshlrev_b32_e32 v0, 14, v11
	v_and_b32_e32 v0, 0xffff8000, v0
	v_lshl_add_u32 v0, v12, 11, v0
	v_and_b32_e32 v1, 1, v11
	v_lshl_or_b32 v0, v1, 6, v0
	s_waitcnt vmcnt(6)
	v_lshl_add_u32 v0, v13, 1, v0
	v_mov_b32_e32 v1, v65
	v_lshl_add_u64 v[138:139], s[20:21], 0, v[0:1]
	v_mov_b32_e32 v0, 0
	s_mov_b32 s91, -2
	s_mov_b64 s[20:21], 0x4640080
	v_add_u32_e32 v141, 0, v14
	v_mov_b32_e32 v1, v0
	v_mov_b32_e32 v2, v0
	v_mov_b32_e32 v3, v0
	v_mov_b32_e32 v4, v0
	v_mov_b32_e32 v5, v0
	v_mov_b32_e32 v6, v0
	v_mov_b32_e32 v7, v0
	v_mov_b32_e32 v12, v0
	v_mov_b32_e32 v13, v0
	v_mov_b32_e32 v14, v0
	v_mov_b32_e32 v15, v0
	v_mov_b32_e32 v20, v0
	v_mov_b32_e32 v21, v0
	v_mov_b32_e32 v22, v0
	v_mov_b32_e32 v23, v0
	v_mov_b32_e32 v28, v0
	v_mov_b32_e32 v29, v0
	v_mov_b32_e32 v30, v0
	v_mov_b32_e32 v31, v0
	v_mov_b32_e32 v36, v0
	v_mov_b32_e32 v37, v0
	v_mov_b32_e32 v38, v0
	v_mov_b32_e32 v39, v0
	v_mov_b32_e32 v44, v0
	v_mov_b32_e32 v45, v0
	v_mov_b32_e32 v46, v0
	v_mov_b32_e32 v47, v0
	v_mov_b32_e32 v52, v0
	v_mov_b32_e32 v53, v0
	v_mov_b32_e32 v54, v0
	v_mov_b32_e32 v55, v0
	v_mov_b32_e32 v8, v0
	v_mov_b32_e32 v9, v0
	v_mov_b32_e32 v10, v0
	v_mov_b32_e32 v11, v0
	v_mov_b32_e32 v16, v0
	v_mov_b32_e32 v17, v0
	v_mov_b32_e32 v18, v0
	v_mov_b32_e32 v19, v0
	v_mov_b32_e32 v24, v0
	v_mov_b32_e32 v25, v0
	v_mov_b32_e32 v26, v0
	v_mov_b32_e32 v27, v0
	v_mov_b32_e32 v32, v0
	v_mov_b32_e32 v33, v0
	v_mov_b32_e32 v34, v0
	v_mov_b32_e32 v35, v0
	v_mov_b32_e32 v40, v0
	v_mov_b32_e32 v41, v0
	v_mov_b32_e32 v42, v0
	v_mov_b32_e32 v43, v0
	v_mov_b32_e32 v48, v0
	v_mov_b32_e32 v49, v0
	v_mov_b32_e32 v50, v0
	v_mov_b32_e32 v51, v0
	v_mov_b32_e32 v56, v0
	v_mov_b32_e32 v57, v0
	v_mov_b32_e32 v58, v0
	v_mov_b32_e32 v59, v0
	v_mov_b32_e32 v60, v0
	v_mov_b32_e32 v61, v0
	v_mov_b32_e32 v62, v0
	v_mov_b32_e32 v63, v0
	v_mov_b32_e32 v66, v0
	v_mov_b32_e32 v67, v0
	v_mov_b32_e32 v68, v0
	v_mov_b32_e32 v69, v0
	v_mov_b32_e32 v70, v0
	v_mov_b32_e32 v71, v0
	v_mov_b32_e32 v72, v0
	v_mov_b32_e32 v73, v0
	v_mov_b32_e32 v78, v0
	v_mov_b32_e32 v79, v0
	v_mov_b32_e32 v80, v0
	v_mov_b32_e32 v81, v0
	v_mov_b32_e32 v86, v0
	v_mov_b32_e32 v87, v0
	v_mov_b32_e32 v88, v0
	v_mov_b32_e32 v89, v0
	v_mov_b32_e32 v94, v0
	v_mov_b32_e32 v95, v0
	v_mov_b32_e32 v96, v0
	v_mov_b32_e32 v97, v0
	v_mov_b32_e32 v102, v0
	v_mov_b32_e32 v103, v0
	v_mov_b32_e32 v104, v0
	v_mov_b32_e32 v105, v0
	v_mov_b32_e32 v110, v0
	v_mov_b32_e32 v111, v0
	v_mov_b32_e32 v112, v0
	v_mov_b32_e32 v113, v0
	v_mov_b32_e32 v118, v0
	v_mov_b32_e32 v119, v0
	v_mov_b32_e32 v120, v0
	v_mov_b32_e32 v121, v0
	v_mov_b32_e32 v74, v0
	v_mov_b32_e32 v75, v0
	v_mov_b32_e32 v76, v0
	v_mov_b32_e32 v77, v0
	v_mov_b32_e32 v82, v0
	v_mov_b32_e32 v83, v0
	v_mov_b32_e32 v84, v0
	v_mov_b32_e32 v85, v0
	v_mov_b32_e32 v90, v0
	v_mov_b32_e32 v91, v0
	v_mov_b32_e32 v92, v0
	v_mov_b32_e32 v93, v0
	v_mov_b32_e32 v98, v0
	v_mov_b32_e32 v99, v0
	v_mov_b32_e32 v100, v0
	v_mov_b32_e32 v101, v0
	v_mov_b32_e32 v106, v0
	v_mov_b32_e32 v107, v0
	v_mov_b32_e32 v108, v0
	v_mov_b32_e32 v109, v0
	v_mov_b32_e32 v114, v0
	v_mov_b32_e32 v115, v0
	v_mov_b32_e32 v116, v0
	v_mov_b32_e32 v117, v0
	v_mov_b32_e32 v122, v0
	v_mov_b32_e32 v123, v0
	v_mov_b32_e32 v124, v0
	v_mov_b32_e32 v125, v0
	v_mov_b32_e32 v126, v0
	v_mov_b32_e32 v127, v0
	v_mov_b32_e32 v128, v0
	v_mov_b32_e32 v129, v0
	s_barrier

; #define PG8_STAGE(bufoff, gbase, voff) do { _Pragma("unroll") for (int _i = 0; _i < 2; ++_i) \
;         __builtin_amdgcn_global_load_lds((const unsigned*)((const char*)(gbase) + (voff)[_i]), (PG8_LAS unsigned*)(lds + (bufoff) + ldsw + _i * 8192), 16, 0, 0); } while (0)
; #define PG8_WAIT_V(n) asm volatile("s_waitcnt vmcnt(" #n ")" ::: "memory")
; #define PG8_BAR __builtin_amdgcn_s_barrier()
; template <class Epi, class Sched, bool ALIGN_EPI = false, bool SP2 = false>
; __device__ __forceinline__ void gemm_phase(PG8_LAS unsigned char* lds, const Gemm g, const Sched& S, const Epi& E) {
;     ...
;     f32x4 acc[2][2][4][2];
; #pragma unroll
;     for (int a = 0; a < 2; ++a)
; #pragma unroll
;         for (int b = 0; b < 2; ++b)
; #pragma unroll
;             for (int m = 0; m < 4; ++m)
; #pragma unroll
;                 for (int n = 0; n < 2; ++n) acc[a][b][m][n] = (f32x4){0.f, 0.f, 0.f, 0.f};
;     ...
;         PG8_STAGE(PG8_SB(0, 0), cB, voffB); PG8_STAGE(PG8_SB(0, 1), cB + hstepB, voffB); PG8_STAGE(PG8_SA(0, 0), cA, voffA); PG8_STAGE(PG8_SA(0, 1), cA + hstepA, voffA);
;         if (wr == 1) PG8_BAR;
;         PG8_WAIT_V(2); PG8_BAR;
;         PG8_STAGE(PG8_SB(1, 0), cB + kstep, voffB); PG8_STAGE(PG8_SA(1, 0), cA + kstep, voffA); PG8_STAGE(PG8_SB(1, 1), cB + hstepB + kstep, voffB);
;         PG8_WAIT_V(6); PG8_BAR;
.LBB0_1367:
	v_and_b32_e32 v138, 15, v136
	v_and_b32_e32 v14, 48, v136
	v_lshlrev_b32_e32 v137, 2, v138
	s_and_b32 s24, s8, 3
	s_lshl_b32 s8, s9, 13
	v_lshl_or_b32 v14, v138, 6, v14
	v_and_b32_e32 v15, 32, v137
	s_add_i32 m0, s23, 0x18000
	v_lshl_add_u64 v[6:7], v[6:7], 0, s[48:49]
	s_lshl_b32 s30, s9, 6
	v_bitop3_b32 v16, v14, s8, v15 bitop3:0xde
	s_lshl_b32 s8, s24, 12
	s_waitcnt vmcnt(2)
	s_barrier
	global_load_lds_dwordx4 v[6:7], off
	v_lshl_add_u64 v[4:5], v[4:5], 0, s[48:49]
	s_add_i32 m0, s23, 0x1a000
	s_add_i32 s38, s23, 0x8000
	s_add_i32 s39, s23, 0xa000
	v_bitop3_b32 v139, v14, s8, v15 bitop3:0xde
	global_load_lds_dwordx4 v[4:5], off
	v_lshl_add_u64 v[2:3], v[2:3], 0, s[48:49]
	s_mov_b32 m0, s38
	s_add_u32 s8, s0, 0x40080
	global_load_lds_dwordx4 v[2:3], off
	v_lshl_add_u64 v[0:1], v[0:1], 0, s[48:49]
	s_mov_b32 m0, s39
	s_addc_u32 s9, s1, 0
	global_load_lds_dwordx4 v[0:1], off
	s_add_i32 m0, s23, 0x1c000
	v_lshl_add_u64 v[0:1], s[8:9], 0, v[64:65]
	global_load_lds_dwordx4 v[0:1], off
	v_lshl_add_u64 v[0:1], s[8:9], 0, v[130:131]
	s_add_i32 m0, s23, 0x1e000
	s_add_u32 s6, s82, s6
	global_load_lds_dwordx4 v[0:1], off
	v_lshlrev_b32_e32 v0, 14, v8
	v_and_b32_e32 v0, 0xffff8000, v0
	v_lshl_add_u32 v0, v9, 11, v0
	v_and_b32_e32 v1, 1, v8
	v_lshl_or_b32 v0, v1, 6, v0
	v_lshl_add_u32 v0, v11, 1, v0
	v_mov_b32_e32 v1, v65
	s_addc_u32 s7, s83, s7
	v_lshl_add_u64 v[132:133], s[6:7], 0, v[0:1]
	v_lshlrev_b32_e32 v0, 14, v10
	v_and_b32_e32 v0, 0xffff8000, v0
	v_lshl_add_u32 v0, v12, 11, v0
	v_and_b32_e32 v1, 1, v10
	v_lshl_or_b32 v0, v1, 6, v0
	s_waitcnt vmcnt(6)
	v_lshl_add_u32 v0, v13, 1, v0
	v_mov_b32_e32 v1, v65
	v_lshl_add_u64 v[134:135], s[6:7], 0, v[0:1]
	v_mov_b32_e32 v0, 0
	v_or_b32_e32 v179, s30, v138
	s_mov_b32 s43, -2
	s_mov_b64 s[6:7], 0x9640080
	v_add_u32_e32 v140, 0, v16
	v_mov_b32_e32 v1, v0
	v_mov_b32_e32 v2, v0
	v_mov_b32_e32 v3, v0
	v_mov_b32_e32 v4, v0
	v_mov_b32_e32 v5, v0
	v_mov_b32_e32 v6, v0
	v_mov_b32_e32 v7, v0
	v_mov_b32_e32 v16, v0
	v_mov_b32_e32 v17, v0
	v_mov_b32_e32 v18, v0
	v_mov_b32_e32 v19, v0
	v_mov_b32_e32 v20, v0
	v_mov_b32_e32 v21, v0
	v_mov_b32_e32 v22, v0
	v_mov_b32_e32 v23, v0
	v_mov_b32_e32 v32, v0
	v_mov_b32_e32 v33, v0
	v_mov_b32_e32 v34, v0
	v_mov_b32_e32 v35, v0
	v_mov_b32_e32 v36, v0
	v_mov_b32_e32 v37, v0
	v_mov_b32_e32 v38, v0
	v_mov_b32_e32 v39, v0
	v_mov_b32_e32 v48, v0
	v_mov_b32_e32 v49, v0
	v_mov_b32_e32 v50, v0
	v_mov_b32_e32 v51, v0
	v_mov_b32_e32 v52, v0
	v_mov_b32_e32 v53, v0
	v_mov_b32_e32 v54, v0
	v_mov_b32_e32 v55, v0
	v_mov_b32_e32 v8, v0
	v_mov_b32_e32 v9, v0
	v_mov_b32_e32 v10, v0
	v_mov_b32_e32 v11, v0
	v_mov_b32_e32 v12, v0
	v_mov_b32_e32 v13, v0
	v_mov_b32_e32 v14, v0
	v_mov_b32_e32 v15, v0
	v_mov_b32_e32 v24, v0
	v_mov_b32_e32 v25, v0
	v_mov_b32_e32 v26, v0
	v_mov_b32_e32 v27, v0
	v_mov_b32_e32 v28, v0
	v_mov_b32_e32 v29, v0
	v_mov_b32_e32 v30, v0
	v_mov_b32_e32 v31, v0
	v_mov_b32_e32 v40, v0
	v_mov_b32_e32 v41, v0
	v_mov_b32_e32 v42, v0
	v_mov_b32_e32 v43, v0
	v_mov_b32_e32 v44, v0
	v_mov_b32_e32 v45, v0
	v_mov_b32_e32 v46, v0
	v_mov_b32_e32 v47, v0
	v_mov_b32_e32 v56, v0
	v_mov_b32_e32 v57, v0
	v_mov_b32_e32 v58, v0
	v_mov_b32_e32 v59, v0
	v_mov_b32_e32 v60, v0
	v_mov_b32_e32 v61, v0
	v_mov_b32_e32 v62, v0
	v_mov_b32_e32 v63, v0
	v_mov_b32_e32 v66, v0
	v_mov_b32_e32 v67, v0
	v_mov_b32_e32 v68, v0
	v_mov_b32_e32 v69, v0
	v_mov_b32_e32 v70, v0
	v_mov_b32_e32 v71, v0
	v_mov_b32_e32 v72, v0
	v_mov_b32_e32 v73, v0
	v_mov_b32_e32 v82, v0
	v_mov_b32_e32 v83, v0
	v_mov_b32_e32 v84, v0
	v_mov_b32_e32 v85, v0
	v_mov_b32_e32 v86, v0
	v_mov_b32_e32 v87, v0
	v_mov_b32_e32 v88, v0
	v_mov_b32_e32 v89, v0
	v_mov_b32_e32 v98, v0
	v_mov_b32_e32 v99, v0
	v_mov_b32_e32 v100, v0
	v_mov_b32_e32 v101, v0
	v_mov_b32_e32 v102, v0
	v_mov_b32_e32 v103, v0
	v_mov_b32_e32 v104, v0
	v_mov_b32_e32 v105, v0
	v_mov_b32_e32 v114, v0
	v_mov_b32_e32 v115, v0
	v_mov_b32_e32 v116, v0
	v_mov_b32_e32 v117, v0
	v_mov_b32_e32 v118, v0
	v_mov_b32_e32 v119, v0
	v_mov_b32_e32 v120, v0
	v_mov_b32_e32 v121, v0
	v_mov_b32_e32 v74, v0
	v_mov_b32_e32 v75, v0
	v_mov_b32_e32 v76, v0
	v_mov_b32_e32 v77, v0
	v_mov_b32_e32 v78, v0
	v_mov_b32_e32 v79, v0
	v_mov_b32_e32 v80, v0
	v_mov_b32_e32 v81, v0
	v_mov_b32_e32 v90, v0
	v_mov_b32_e32 v91, v0
	v_mov_b32_e32 v92, v0
	v_mov_b32_e32 v93, v0
	v_mov_b32_e32 v94, v0
	v_mov_b32_e32 v95, v0
	v_mov_b32_e32 v96, v0
	v_mov_b32_e32 v97, v0
	v_mov_b32_e32 v106, v0
	v_mov_b32_e32 v107, v0
	v_mov_b32_e32 v108, v0
	v_mov_b32_e32 v109, v0
	v_mov_b32_e32 v110, v0
	v_mov_b32_e32 v111, v0
	v_mov_b32_e32 v112, v0
	v_mov_b32_e32 v113, v0
	v_mov_b32_e32 v122, v0
	v_mov_b32_e32 v123, v0
	v_mov_b32_e32 v124, v0
	v_mov_b32_e32 v125, v0
	v_mov_b32_e32 v126, v0
	v_mov_b32_e32 v127, v0
	v_mov_b32_e32 v128, v0
	v_mov_b32_e32 v129, v0
	s_barrier

;     __device__ __forceinline__ bool next(int i, Unit& u) const { if (i) return false; u.pm = pm; u.pn = pn; return true; }
; #define PG8_STAGE(bufoff, gbase, voff) do { _Pragma("unroll") for (int _i = 0; _i < 2; ++_i) \
;         __builtin_amdgcn_global_load_lds((const unsigned*)((const char*)(gbase) + (voff)[_i]), (PG8_LAS unsigned*)(lds + (bufoff) + ldsw + _i * 8192), 16, 0, 0); } while (0)
; #define PG8_LDA(dst, b, h) do { _Pragma("unroll") for (int m = 0; m < 4; ++m) _Pragma("unroll") for (int k = 0; k < 2; ++k) dst[m][k] = *(const PG8_LAS bf16x8*)(lds + PG8_SA(b, h) + aoff + m * 2048 + k * 1024); } while (0)
; #define PG8_LDB(dst, b, h) do { _Pragma("unroll") for (int n = 0; n < 2; ++n) _Pragma("unroll") for (int k = 0; k < 2; ++k) dst[n][k] = *(const PG8_LAS bf16x8*)(lds + PG8_SB(b, h) + boff + n * 2048 + k * 1024); } while (0)
; #define PG8_SCHED __builtin_amdgcn_sched_barrier(0)
; template <class Epi, class Sched, bool ALIGN_EPI = false, bool SP2 = false>
; __device__ __forceinline__ void gemm_phase(PG8_LAS unsigned char* lds, const Gemm g, const Sched& S, const Epi& E) {
;     ...
;         const bool has_next = S.next(ui + 1, nxt);
;         const char* nA = has_next ? (const char*)g.A + (size_t)nxt.pm * tstepA + (size_t)nxt.pn * g.a_pn_off * 2 : cA; const char* nB = has_next ? (const char*)g.Bt + (size_t)nxt.pn * tstepB : cB;
;         for (int t = 0; t < nt; t += 2) {
;             const bool last = (t == nt - 2);
;             const char* a1 = cA + (size_t)(t + 1) * kstep;
;             const char* a2 = last ? nA : cA + (size_t)(t + 2) * kstep; const char* b2 = last ? nB : cB + (size_t)(t + 2) * kstep;
;             const char* a3 = a2 + kstep; const char* b3 = b2 + kstep;
;             if (last && has_next) S.a_ready(nxt);
;             if constexpr (SP2) {
;             PG8_LDB(B0, 0, 0); PG8_LDB(B1, 0, 1); PG8_SCHED; PG8_LDA(At, 0, 0); PG8_STAGE(PG8_SA(1, 1), a1 + hstepA, voffA);
;     ...
;         for (int a = 0; a < 2; ++a)
; #pragma unroll
;             for (int b = 0; b < 2; ++b)
; #pragma unroll
;                 for (int m = 0; m < 4; ++m)
; #pragma unroll
;                     for (int n = 0; n < 2; ++n) acc[a][b][m][n] = (f32x4){0.f, 0.f, 0.f, 0.f};
.LBB0_1449:
	s_ashr_i32 s13, s12, 31
	s_lshl_b64 s[14:15], s[12:13], 19
	s_add_u32 s14, s26, s14
	s_addc_u32 s15, s27, s15
	s_and_b64 s[16:17], s[2:3], exec
	s_cselect_b32 s13, s15, s19
	s_cselect_b32 s22, s14, s18
	s_ashr_i32 s11, s10, 31
	s_lshl_b64 s[16:17], s[10:11], 19
	s_add_u32 s16, s39, s16
	s_addc_u32 s17, s44, s17
	s_and_b64 s[24:25], s[2:3], exec
	s_cselect_b32 s11, s17, s21
	s_cselect_b32 s23, s16, s20
	s_add_u32 s18, s18, 0x40080
	s_addc_u32 s19, s19, 0
	s_add_u32 s24, s20, 0x100
	v_mov_b32_e32 v0, 0
	s_addc_u32 s25, s21, 0
	s_mov_b32 s43, -2
	v_mov_b32_e32 v1, v0
	v_mov_b32_e32 v2, v0
	v_mov_b32_e32 v3, v0
	v_mov_b32_e32 v4, v0
	v_mov_b32_e32 v5, v0
	v_mov_b32_e32 v6, v0
	v_mov_b32_e32 v7, v0
	v_mov_b32_e32 v16, v0
	v_mov_b32_e32 v17, v0
	v_mov_b32_e32 v18, v0
	v_mov_b32_e32 v19, v0
	v_mov_b32_e32 v20, v0
	v_mov_b32_e32 v21, v0
	v_mov_b32_e32 v22, v0
	v_mov_b32_e32 v23, v0
	v_mov_b32_e32 v32, v0
	v_mov_b32_e32 v33, v0
	v_mov_b32_e32 v34, v0
	v_mov_b32_e32 v35, v0
	v_mov_b32_e32 v36, v0
	v_mov_b32_e32 v37, v0
	v_mov_b32_e32 v38, v0
	v_mov_b32_e32 v39, v0
	v_mov_b32_e32 v48, v0
	v_mov_b32_e32 v49, v0
	v_mov_b32_e32 v50, v0
	v_mov_b32_e32 v51, v0
	v_mov_b32_e32 v52, v0
	v_mov_b32_e32 v53, v0
	v_mov_b32_e32 v54, v0
	v_mov_b32_e32 v55, v0
	v_mov_b32_e32 v8, v0
	v_mov_b32_e32 v9, v0
	v_mov_b32_e32 v10, v0
	v_mov_b32_e32 v11, v0
	v_mov_b32_e32 v12, v0
	v_mov_b32_e32 v13, v0
	v_mov_b32_e32 v14, v0
	v_mov_b32_e32 v15, v0
	v_mov_b32_e32 v24, v0
	v_mov_b32_e32 v25, v0
	v_mov_b32_e32 v26, v0
	v_mov_b32_e32 v27, v0
	v_mov_b32_e32 v28, v0
	v_mov_b32_e32 v29, v0
	v_mov_b32_e32 v30, v0
	v_mov_b32_e32 v31, v0
	v_mov_b32_e32 v40, v0
	v_mov_b32_e32 v41, v0
	v_mov_b32_e32 v42, v0
	v_mov_b32_e32 v43, v0
	v_mov_b32_e32 v44, v0
	v_mov_b32_e32 v45, v0
	v_mov_b32_e32 v46, v0
	v_mov_b32_e32 v47, v0
	v_mov_b32_e32 v56, v0
	v_mov_b32_e32 v57, v0
	v_mov_b32_e32 v58, v0
	v_mov_b32_e32 v59, v0
	v_mov_b32_e32 v60, v0
	v_mov_b32_e32 v61, v0
	v_mov_b32_e32 v62, v0
	v_mov_b32_e32 v63, v0
	v_mov_b32_e32 v66, v0
	v_mov_b32_e32 v67, v0
	v_mov_b32_e32 v68, v0
	v_mov_b32_e32 v69, v0
	v_mov_b32_e32 v70, v0
	v_mov_b32_e32 v71, v0
	v_mov_b32_e32 v72, v0
	v_mov_b32_e32 v73, v0
	v_mov_b32_e32 v82, v0
	v_mov_b32_e32 v83, v0
	v_mov_b32_e32 v84, v0
	v_mov_b32_e32 v85, v0
	v_mov_b32_e32 v86, v0
	v_mov_b32_e32 v87, v0
	v_mov_b32_e32 v88, v0
	v_mov_b32_e32 v89, v0
	v_mov_b32_e32 v98, v0
	v_mov_b32_e32 v99, v0
	v_mov_b32_e32 v100, v0
	v_mov_b32_e32 v101, v0
	v_mov_b32_e32 v102, v0
	v_mov_b32_e32 v103, v0
	v_mov_b32_e32 v104, v0
	v_mov_b32_e32 v105, v0
	v_mov_b32_e32 v114, v0
	v_mov_b32_e32 v115, v0
	v_mov_b32_e32 v116, v0
	v_mov_b32_e32 v117, v0
	v_mov_b32_e32 v118, v0
	v_mov_b32_e32 v119, v0
	v_mov_b32_e32 v120, v0
	v_mov_b32_e32 v121, v0
	v_mov_b32_e32 v74, v0
	v_mov_b32_e32 v75, v0
	v_mov_b32_e32 v76, v0
	v_mov_b32_e32 v77, v0
	v_mov_b32_e32 v78, v0
	v_mov_b32_e32 v79, v0
	v_mov_b32_e32 v80, v0
	v_mov_b32_e32 v81, v0
	v_mov_b32_e32 v90, v0
	v_mov_b32_e32 v91, v0
	v_mov_b32_e32 v92, v0
	v_mov_b32_e32 v93, v0
	v_mov_b32_e32 v94, v0
	v_mov_b32_e32 v95, v0
	v_mov_b32_e32 v96, v0
	v_mov_b32_e32 v97, v0
	v_mov_b32_e32 v106, v0
	v_mov_b32_e32 v107, v0
	v_mov_b32_e32 v108, v0
	v_mov_b32_e32 v109, v0
	v_mov_b32_e32 v110, v0
	v_mov_b32_e32 v111, v0
	v_mov_b32_e32 v112, v0
	v_mov_b32_e32 v113, v0
	v_mov_b32_e32 v122, v0
	v_mov_b32_e32 v123, v0
	v_mov_b32_e32 v124, v0
	v_mov_b32_e32 v125, v0
	v_mov_b32_e32 v126, v0
	v_mov_b32_e32 v127, v0
	v_mov_b32_e32 v128, v0
	v_mov_b32_e32 v129, v0

; #define g1 (tab_in(TB, 2) + l * D)
; #define gm (tab_in(TB, 5) + l * D)
; __device__ __forceinline__ void phase_prologue(PtrTab TB, unsigned char* ws, float* xout, int l, LAS unsigned char* lds, int gw, int NGW, int lane, int wave) {
;     ...
;     for (int it = gw; it < S14; it += NGW) {
;         if (it < S1 || (it >= S12 && it < S13)) {
;             const bool second = it >= S12; const int r = second ? it - S12 : it; const int kb = r / 88, nb = r % 88; const int n = nb * 64;
;             const int half = n >= DFF ? 1 : 0, nn = n - half * DFF; const int drow = (nn >> 7) * 256 + half * 128 + (nn & 127);
;             tr_item(second ? w2i : w1i, 2 * DFF, n, kb * 64, second ? g2 : g1, (bf16*)(ws + (second ? WS_W2IN : WS_W1IN)), D, drow, scr, lane);
;         } else if (it < S2 || it >= S13) {
;             const bool second = it >= S13; const int r = second ? it - S13 : it - S1; const int kb = r / 16, nb = r % 16;
;             tr_item(second ? w2o : w1o, D, nb * 64, kb * 64, nullptr, (bf16*)(ws + (second ? WS_W2OUT : WS_W1OUT)), DFF, nb * 64, scr, lane);
;         } else if (it < S3) { const int r = it - S2, kb = r / 64, nb = r % 64; tr_item(win, INW, nb * 64, kb * 64, gm, (bf16*)(ws + WS_WIN), D, nb * 64, scr, lane);
;         } else if (it < S4) { const int r = it - S3, kb = r / 48, nb = r % 48; tr_item(win, INW, 4104 + nb * 64, kb * 64, gm, (bf16*)(ws + WS_WG), D, nb * 64, scr, lane);
;         } else if (it < S5) { const int r = it - S4, kb = r / 16, nb = r % 16; tr_item(wub, D, nb * 64, kb * 64, nullptr, (bf16*)(ws + WS_UB), D, nb * 64, scr, lane);
;         } else if (it < S6) { const int r = it - S5, kb = r / 16, nb = r % 16; tr_item(wuc, D, nb * 64, kb * 64, nullptr, (bf16*)(ws + WS_UC), 512, nb * 64, scr, lane);
;         } else if (it < S8) { const bool xg = it >= S7; const int r = xg ? it - S7 : it - S6; const int hh = r >> 2, kb = (r >> 1) & 1, nb = r & 1;
;             tr_item((xg ? wrx : wra) + hh * 16384, 128, nb * 64, kb * 64, nullptr, (bf16*)(ws + (xg ? WS_WXT : WS_WAT)) + hh * 16384, 128, nb * 64, scr, lane);
;         } else if (it < S9) { const int r = it - S8, kb = r / 16, nb = r % 16; tr_item(wo, D, nb * 64, kb * 64, nullptr, (bf16*)(ws + WS_WO), D, nb * 64, scr, lane);
;         } else if (it < S10) { const int r = it - S9, kb = r / 16, nb = r % 16; tr_item(wxq, D, nb * 64, kb * 64, gc, (bf16*)(ws + WS_WXQ), D, nb * 64, scr, lane);
.LBB0_1457:
	v_readlane_b32 s0, v254, 58
	v_readlane_b32 s1, v254, 0
	v_readlane_b32 s2, v254, 2
	s_nop 3
	s_cmp_lg_u32 s0, 0
	s_cbranch_scc1 .Lofl_skip
	s_cmpk_lg_u32 s1, 0x100
	s_cbranch_scc1 .Lofl_skip
	s_cmpk_lt_u32 s2, 0x80
	s_cbranch_scc1 .Lofl_skip
	v_lshrrev_b32_e32 v50, 6, v197
	v_and_b32_e32 v49, 63, v197
	s_nop 0
	v_readfirstlane_b32 s3, v50
	s_nop 3
	s_sub_u32 s2, s2, 0x80
	s_lshl_b32 s2, s2, 3
	s_add_u32 s10, s2, s3
	s_mul_i32 s5, s3, 0x4100
	v_and_b32_e32 v40, 15, v49
	v_lshlrev_b32_e32 v40, 2, v40
	v_lshrrev_b32_e32 v41, 4, v49
	v_and_b32_e32 v42, 7, v49
	v_lshlrev_b32_e32 v42, 3, v42
	v_lshrrev_b32_e32 v44, 3, v49
	v_mul_u32_u24_e32 v45, 0x104, v41
	v_lshl_add_u32 v45, v40, 2, v45
	v_add_u32_e32 v45, s5, v45
	v_mul_u32_u24_e32 v48, 0x104, v42
	v_lshl_add_u32 v48, v44, 2, v48
	v_add_u32_e32 v48, s5, v48
.Lofl_item:
	s_mov_b32 s0, s10
	s_cmpk_lt_u32 s0, 1408
	s_cbranch_scc1 .Lofl_seg0
	s_cmpk_lt_u32 s0, 2112
	s_cbranch_scc1 .Lofl_seg1
	s_cmpk_lt_u32 s0, 3136
	s_cbranch_scc1 .Lofl_seg2
	s_cmpk_lt_u32 s0, 3904
	s_cbranch_scc1 .Lofl_seg3
	s_cmpk_lt_u32 s0, 4160
	s_cbranch_scc1 .Lofl_seg4
	s_cmpk_lt_u32 s0, 4288
	s_cbranch_scc1 .Lofl_seg5
	s_cmpk_lt_u32 s0, 4320
	s_cbranch_scc1 .Lofl_seg6
	s_cmpk_lt_u32 s0, 4352
	s_cbranch_scc1 .Lofl_seg7
	s_cmpk_lt_u32 s0, 4608
	s_cbranch_scc1 .Lofl_seg8
	s_cmpk_lt_u32 s0, 4864
	s_cbranch_scc1 .Lofl_seg9
	s_cmpk_lt_u32 s0, 5376
	s_cbranch_scc1 .Lofl_seg10
	s_cmpk_lt_u32 s0, 5632
	s_cbranch_scc1 .Lofl_seg11
	s_cmpk_lt_u32 s0, 7040
	s_cbranch_scc1 .Lofl_seg12
	s_branch .Lofl_seg13

; #define g1 (tab_in(TB, 2) + l * D)
; #define w1i (tab_in(TB, 3) + (size_t)l * D * 2 * DFF)
; #define w1o (tab_in(TB, 4) + (size_t)l * DFF * D)
; __device__ __forceinline__ void phase_prologue(PtrTab TB, unsigned char* ws, float* xout, int l, LAS unsigned char* lds, int gw, int NGW, int lane, int wave) {
;     ...
;             const bool second = it >= S12; const int r = second ? it - S12 : it; const int kb = r / 88, nb = r % 88; const int n = nb * 64;
;             const int half = n >= DFF ? 1 : 0, nn = n - half * DFF; const int drow = (nn >> 7) * 256 + half * 128 + (nn & 127);
;             tr_item(second ? w2i : w1i, 2 * DFF, n, kb * 64, second ? g2 : g1, (bf16*)(ws + (second ? WS_W2IN : WS_W1IN)), D, drow, scr, lane);
;         } else if (it < S2 || it >= S13) {
;             const bool second = it >= S13; const int r = second ? it - S13 : it - S1; const int kb = r / 16, nb = r % 16;
;             tr_item(second ? w2o : w1o, D, nb * 64, kb * 64, nullptr, (bf16*)(ws + (second ? WS_W2OUT : WS_W1OUT)), DFF, nb * 64, scr, lane);
.Lofl_common:
	s_load_dwordx2 s[16:17], s[100:101], s6
	s_mov_b64 s[72:73], 0
	s_bitcmp1_b32 s34, 2
	s_cbranch_scc0 .Lofl_nogptr
	s_load_dwordx2 s[72:73], s[100:101], s21
.Lofl_nogptr:
	s_mul_i32 s31, s0, s5
	s_lshr_b32 s31, s31, 16
	s_mul_i32 s87, s31, s1
	s_sub_u32 s87, s0, s87
	s_lshl_b32 s4, s31, 6
	s_lshl_b32 s9, s87, 6
	s_add_u32 s20, s20, s9
	s_bitcmp1_b32 s34, 0
	s_cbranch_scc0 .Lofl_noswi
	s_cmp_ge_u32 s87, 44
	s_cselect_b32 s24, 1, 0
	s_mul_i32 s25, s24, 44
	s_sub_u32 s25, s87, s25
	s_lshr_b32 s9, s25, 1
	s_lshl_b32 s9, s9, 8
	s_lshl_b32 s24, s24, 7
	s_add_u32 s9, s9, s24
	s_and_b32 s25, s25, 1
	s_lshl_b32 s25, s25, 6
	s_add_u32 s9, s9, s25

; #define LAS __attribute__((address_space(3)))
; __device__ __forceinline__ unsigned pk2(float lo, float hi) { return f2bf(lo) | (f2bf(hi) << 16); }
; #define LDS_WAIT() asm volatile("s_waitcnt lgkmcnt(0)" ::: "memory")
; #define g1 (tab_in(TB, 2) + l * D)
; #define w1i (tab_in(TB, 3) + (size_t)l * D * 2 * DFF)
; #define w1o (tab_in(TB, 4) + (size_t)l * DFF * D)
; #define gm (tab_in(TB, 5) + l * D)
; #define win (tab_in(TB, 6) + (size_t)l * D * INW)
; __device__ __forceinline__ void tr_item(const float* W, int ldn, int col0, int k0, const float* g, bf16* WT, int ldk, int drow0, LAS float* scr, int lane) {
;     ...
;     for (int i = 0; i < 16; ++i) { const int kk = 4 * i + kr; f32x4 v = *(const f32x4*)(W + (size_t)(k0 + kk) * ldn + col0 + n4); if (g) v = v * g[k0 + kk];
;         LAS float* d = scr + kk * 65 + n4; d[0] = v.x; d[1] = v.y; d[2] = v.z; d[3] = v.w; }
;     LDS_WAIT(); asm volatile("" ::: "memory");
;     const int c = lane & 7;
; #pragma unroll
;     for (int j = 0; j < 8; ++j) { const int n = (lane >> 3) + 8 * j; const LAS float* s = scr + (8 * c) * 65 + n;
;         v4u o; o.x = pk2(s[0 * 65], s[1 * 65]); o.y = pk2(s[2 * 65], s[3 * 65]); o.z = pk2(s[4 * 65], s[5 * 65]); o.w = pk2(s[6 * 65], s[7 * 65]);
;         *(v4u*)(WT + (size_t)(drow0 + n) * ldk + k0 + 8 * c) = o; }
; __device__ __forceinline__ void phase_prologue(PtrTab TB, unsigned char* ws, float* xout, int l, LAS unsigned char* lds, int gw, int NGW, int lane, int wave) {
;     ...
;             const bool second = it >= S12; const int r = second ? it - S12 : it; const int kb = r / 88, nb = r % 88; const int n = nb * 64;
;             const int half = n >= DFF ? 1 : 0, nn = n - half * DFF; const int drow = (nn >> 7) * 256 + half * 128 + (nn & 127);
;             tr_item(second ? w2i : w1i, 2 * DFF, n, kb * 64, second ? g2 : g1, (bf16*)(ws + (second ? WS_W2IN : WS_W1IN)), D, drow, scr, lane);
;         } else if (it < S2 || it >= S13) {
;             const bool second = it >= S13; const int r = second ? it - S13 : it - S1; const int kb = r / 16, nb = r % 16;
;             tr_item(second ? w2o : w1o, D, nb * 64, kb * 64, nullptr, (bf16*)(ws + (second ? WS_W2OUT : WS_W1OUT)), DFF, nb * 64, scr, lane);
;         } else if (it < S3) { const int r = it - S2, kb = r / 64, nb = r % 64; tr_item(win, INW, nb * 64, kb * 64, gm, (bf16*)(ws + WS_WIN), D, nb * 64, scr, lane);
.Lofl_norg:
	s_mov_b32 s95, s13
	s_mul_i32 s97, s4, s18
	s_add_u32 s97, s97, s20
	s_lshl_b32 s97, s97, 2
	s_add_u32 s95, s95, s97
	s_lshl_b32 s38, s18, 4
	s_lshl_b32 s44, s32, 4
	s_mul_i32 s24, s9, s32
	s_add_u32 s24, s24, s4
	s_lshl_b32 s24, s24, 1
	s_add_u32 s24, s24, s23
	s_add_u32 s24, s82, s24
	s_addc_u32 s25, s83, 0
	s_movk_i32 s97, 0x1000
	s_lshl_b32 s1, s4, 2
	s_add_u32 s97, s97, s1
	v_mul_u32_u24_e32 v232, s18, v41
	v_add_lshl_u32 v232, v232, v40, 2
	v_lshlrev_b32_e32 v233, 2, v41
	v_mul_u32_u24_e32 v244, s32, v44
	v_add_lshl_u32 v244, v244, v42, 1
	v_add_u32_e32 v245, s44, v244
	v_add_u32_e32 v246, s44, v245
	v_add_u32_e32 v247, s44, v246
	v_add_u32_e32 v248, s44, v247
	v_add_u32_e32 v249, s44, v248
	v_add_u32_e32 v250, s44, v249
	v_add_u32_e32 v251, s44, v250
	v_mov_b32_e32 v242, v45
	v_add_u32_e32 v243, 0x400, v48
	s_waitcnt lgkmcnt(0)
	s_add_u32 s2, s16, s95
	s_addc_u32 s3, s17, 0
	s_add_u32 s98, s72, s97
	s_addc_u32 s99, s73, 0
	s_bitcmp1_b32 s34, 2
	s_cbranch_scc0 .Lofl_gone
	global_load_dword v210, v233, s[98:99] offset:0
	global_load_dword v211, v233, s[98:99] offset:16
	global_load_dword v212, v233, s[98:99] offset:32
	global_load_dword v213, v233, s[98:99] offset:48
	global_load_dword v214, v233, s[98:99] offset:64
	global_load_dword v215, v233, s[98:99] offset:80
	global_load_dword v216, v233, s[98:99] offset:96
	global_load_dword v217, v233, s[98:99] offset:112
	global_load_dword v218, v233, s[98:99] offset:128
	global_load_dword v219, v233, s[98:99] offset:144
	global_load_dword v220, v233, s[98:99] offset:160
	global_load_dword v221, v233, s[98:99] offset:176
	global_load_dword v222, v233, s[98:99] offset:192
	global_load_dword v223, v233, s[98:99] offset:208
	global_load_dword v230, v233, s[98:99] offset:224
	global_load_dword v231, v233, s[98:99] offset:240
	s_branch .Lofl_gdone

; #define LAS __attribute__((address_space(3)))
; __device__ __forceinline__ void tr_item(const float* W, int ldn, int col0, int k0, const float* g, bf16* WT, int ldk, int drow0, LAS float* scr, int lane) {
;     ...
;     for (int i = 0; i < 16; ++i) { const int kk = 4 * i + kr; f32x4 v = *(const f32x4*)(W + (size_t)(k0 + kk) * ldn + col0 + n4); if (g) v = v * g[k0 + kk];
;         LAS float* d = scr + kk * 65 + n4; d[0] = v.x; d[1] = v.y; d[2] = v.z; d[3] = v.w; }
.Lofl_gdone:
	global_load_dwordx4 v[146:149], v232, s[2:3]
	v_add_u32_e32 v232, s38, v232
	global_load_dwordx4 v[150:153], v232, s[2:3]
	v_add_u32_e32 v232, s38, v232
	global_load_dwordx4 v[154:157], v232, s[2:3]
	v_add_u32_e32 v232, s38, v232
	global_load_dwordx4 v[158:161], v232, s[2:3]
	v_add_u32_e32 v232, s38, v232
	global_load_dwordx4 v[166:169], v232, s[2:3]
	v_add_u32_e32 v232, s38, v232
	global_load_dwordx4 v[170:173], v232, s[2:3]
	v_add_u32_e32 v232, s38, v232
	global_load_dwordx4 v[174:177], v232, s[2:3]
	v_add_u32_e32 v232, s38, v232
	global_load_dwordx4 v[178:181], v232, s[2:3]
	v_add_u32_e32 v232, s38, v232
	global_load_dwordx4 v[182:185], v232, s[2:3]
	v_add_u32_e32 v232, s38, v232
	global_load_dwordx4 v[186:189], v232, s[2:3]
	v_add_u32_e32 v232, s38, v232
	global_load_dwordx4 v[190:193], v232, s[2:3]
	v_add_u32_e32 v232, s38, v232
	global_load_dwordx4 v[108:111], v232, s[2:3]
	v_add_u32_e32 v232, s38, v232
	global_load_dwordx4 v[112:115], v232, s[2:3]
	v_add_u32_e32 v232, s38, v232
	global_load_dwordx4 v[116:119], v232, s[2:3]
	v_add_u32_e32 v232, s38, v232
	global_load_dwordx4 v[120:123], v232, s[2:3]
	v_add_u32_e32 v232, s38, v232
	global_load_dwordx4 v[124:127], v232, s[2:3]
	s_waitcnt vmcnt(15)
	v_mul_f32_e32 v146, v210, v146
	v_mul_f32_e32 v147, v210, v147
	v_mul_f32_e32 v148, v210, v148
	v_mul_f32_e32 v149, v210, v149
	ds_write2_b32 v242, v146, v147 offset1:1
	ds_write2_b32 v242, v148, v149 offset0:2 offset1:3
	v_add_u32_e32 v242, 0x410, v242
	s_waitcnt vmcnt(14)
	v_mul_f32_e32 v150, v211, v150
	v_mul_f32_e32 v151, v211, v151
	v_mul_f32_e32 v152, v211, v152
	v_mul_f32_e32 v153, v211, v153
	ds_write2_b32 v242, v150, v151 offset1:1
	ds_write2_b32 v242, v152, v153 offset0:2 offset1:3
	v_add_u32_e32 v242, 0x410, v242
	s_waitcnt vmcnt(13)
	v_mul_f32_e32 v154, v212, v154
	v_mul_f32_e32 v155, v212, v155
	v_mul_f32_e32 v156, v212, v156
	v_mul_f32_e32 v157, v212, v157
	ds_write2_b32 v242, v154, v155 offset1:1
	ds_write2_b32 v242, v156, v157 offset0:2 offset1:3
	v_add_u32_e32 v242, 0x410, v242
	s_waitcnt vmcnt(12)
	v_mul_f32_e32 v158, v213, v158
	v_mul_f32_e32 v159, v213, v159
	v_mul_f32_e32 v160, v213, v160
	v_mul_f32_e32 v161, v213, v161
	ds_write2_b32 v242, v158, v159 offset1:1
	ds_write2_b32 v242, v160, v161 offset0:2 offset1:3
	v_add_u32_e32 v242, 0x410, v242
	s_waitcnt vmcnt(11)
	v_mul_f32_e32 v166, v214, v166
	v_mul_f32_e32 v167, v214, v167
	v_mul_f32_e32 v168, v214, v168
	v_mul_f32_e32 v169, v214, v169
	ds_write2_b32 v242, v166, v167 offset1:1
	ds_write2_b32 v242, v168, v169 offset0:2 offset1:3
	v_add_u32_e32 v242, 0x410, v242
	s_waitcnt vmcnt(10)
	v_mul_f32_e32 v170, v215, v170
	v_mul_f32_e32 v171, v215, v171
	v_mul_f32_e32 v172, v215, v172
	v_mul_f32_e32 v173, v215, v173
	ds_write2_b32 v242, v170, v171 offset1:1
	ds_write2_b32 v242, v172, v173 offset0:2 offset1:3
	v_add_u32_e32 v242, 0x410, v242
	s_waitcnt vmcnt(9)
	v_mul_f32_e32 v174, v216, v174
	v_mul_f32_e32 v175, v216, v175
	v_mul_f32_e32 v176, v216, v176
	v_mul_f32_e32 v177, v216, v177
	ds_write2_b32 v242, v174, v175 offset1:1
	ds_write2_b32 v242, v176, v177 offset0:2 offset1:3
	v_add_u32_e32 v242, 0x410, v242
	s_waitcnt vmcnt(8)
	v_mul_f32_e32 v178, v217, v178
	v_mul_f32_e32 v179, v217, v179
	v_mul_f32_e32 v180, v217, v180
	v_mul_f32_e32 v181, v217, v181
	ds_write2_b32 v242, v178, v179 offset1:1
	ds_write2_b32 v242, v180, v181 offset0:2 offset1:3
	v_add_u32_e32 v242, 0x410, v242
	s_waitcnt vmcnt(7)
	v_mul_f32_e32 v182, v218, v182
	v_mul_f32_e32 v183, v218, v183
	v_mul_f32_e32 v184, v218, v184
	v_mul_f32_e32 v185, v218, v185
	ds_write2_b32 v242, v182, v183 offset1:1
	ds_write2_b32 v242, v184, v185 offset0:2 offset1:3
	v_add_u32_e32 v242, 0x410, v242
	s_waitcnt vmcnt(6)
	v_mul_f32_e32 v186, v219, v186
	v_mul_f32_e32 v187, v219, v187
	v_mul_f32_e32 v188, v219, v188
	v_mul_f32_e32 v189, v219, v189
	ds_write2_b32 v242, v186, v187 offset1:1
	ds_write2_b32 v242, v188, v189 offset0:2 offset1:3
	v_add_u32_e32 v242, 0x410, v242
	s_waitcnt vmcnt(5)
	v_mul_f32_e32 v190, v220, v190
	v_mul_f32_e32 v191, v220, v191
	v_mul_f32_e32 v192, v220, v192
	v_mul_f32_e32 v193, v220, v193
	ds_write2_b32 v242, v190, v191 offset1:1
	ds_write2_b32 v242, v192, v193 offset0:2 offset1:3
	v_add_u32_e32 v242, 0x410, v242
	s_waitcnt vmcnt(4)
	v_mul_f32_e32 v108, v221, v108
	v_mul_f32_e32 v109, v221, v109
	v_mul_f32_e32 v110, v221, v110
	v_mul_f32_e32 v111, v221, v111
	ds_write2_b32 v242, v108, v109 offset1:1
	ds_write2_b32 v242, v110, v111 offset0:2 offset1:3
	v_add_u32_e32 v242, 0x410, v242
	s_waitcnt vmcnt(3)
; #define LAS __attribute__((address_space(3)))
; __device__ __forceinline__ unsigned pk2(float lo, float hi) { return f2bf(lo) | (f2bf(hi) << 16); }
; #define LDS_WAIT() asm volatile("s_waitcnt lgkmcnt(0)" ::: "memory")
; __device__ __forceinline__ void tr_item(const float* W, int ldn, int col0, int k0, const float* g, bf16* WT, int ldk, int drow0, LAS float* scr, int lane) {
;     ...
;     LDS_WAIT(); asm volatile("" ::: "memory");
;     const int c = lane & 7;
; #pragma unroll
;     for (int j = 0; j < 8; ++j) { const int n = (lane >> 3) + 8 * j; const LAS float* s = scr + (8 * c) * 65 + n;
;         v4u o; o.x = pk2(s[0 * 65], s[1 * 65]); o.y = pk2(s[2 * 65], s[3 * 65]); o.z = pk2(s[4 * 65], s[5 * 65]); o.w = pk2(s[6 * 65], s[7 * 65]);
;         *(v4u*)(WT + (size_t)(drow0 + n) * ldk + k0 + 8 * c) = o; }
; __device__ __forceinline__ void phase_prologue(PtrTab TB, unsigned char* ws, float* xout, int l, LAS unsigned char* lds, int gw, int NGW, int lane, int wave) {
;     ...
;     for (int it = gw; it < S14; it += NGW) {
	v_mul_f32_e32 v112, v222, v112
	v_mul_f32_e32 v113, v222, v113
	v_mul_f32_e32 v114, v222, v114
	v_mul_f32_e32 v115, v222, v115
	ds_write2_b32 v242, v112, v113 offset1:1
	ds_write2_b32 v242, v114, v115 offset0:2 offset1:3
	v_add_u32_e32 v242, 0x410, v242
	s_waitcnt vmcnt(2)
	v_mul_f32_e32 v116, v223, v116
	v_mul_f32_e32 v117, v223, v117
	v_mul_f32_e32 v118, v223, v118
	v_mul_f32_e32 v119, v223, v119
	ds_write2_b32 v242, v116, v117 offset1:1
	ds_write2_b32 v242, v118, v119 offset0:2 offset1:3
	v_add_u32_e32 v242, 0x410, v242
	s_waitcnt vmcnt(1)
	v_mul_f32_e32 v120, v230, v120
	v_mul_f32_e32 v121, v230, v121
	v_mul_f32_e32 v122, v230, v122
	v_mul_f32_e32 v123, v230, v123
	ds_write2_b32 v242, v120, v121 offset1:1
	ds_write2_b32 v242, v122, v123 offset0:2 offset1:3
	v_add_u32_e32 v242, 0x410, v242
	s_waitcnt vmcnt(0)
	v_mul_f32_e32 v124, v231, v124
	v_mul_f32_e32 v125, v231, v125
	v_mul_f32_e32 v126, v231, v126
	v_mul_f32_e32 v127, v231, v127
	ds_write2_b32 v242, v124, v125 offset1:1
	ds_write2_b32 v242, v126, v127 offset0:2 offset1:3
	s_waitcnt lgkmcnt(0)
	ds_read2_b32 v[146:147], v48 offset0:0 offset1:65
	ds_read2_b32 v[148:149], v48 offset0:130 offset1:195
	ds_read2_b32 v[150:151], v243 offset0:4 offset1:69
	ds_read2_b32 v[152:153], v243 offset0:134 offset1:199
	ds_read2_b32 v[154:155], v48 offset0:8 offset1:73
	ds_read2_b32 v[156:157], v48 offset0:138 offset1:203
	ds_read2_b32 v[158:159], v243 offset0:12 offset1:77
	ds_read2_b32 v[160:161], v243 offset0:142 offset1:207
	ds_read2_b32 v[166:167], v48 offset0:16 offset1:81
	ds_read2_b32 v[168:169], v48 offset0:146 offset1:211
	ds_read2_b32 v[170:171], v243 offset0:20 offset1:85
	ds_read2_b32 v[172:173], v243 offset0:150 offset1:215
	s_waitcnt lgkmcnt(8)
	v_cvt_pk_bf16_f32 v146, v146, v147
	v_cvt_pk_bf16_f32 v147, v148, v149
	v_cvt_pk_bf16_f32 v148, v150, v151
	v_cvt_pk_bf16_f32 v149, v152, v153
	global_store_dwordx4 v244, v[146:149], s[24:25]
	ds_read2_b32 v[174:175], v48 offset0:24 offset1:89
	ds_read2_b32 v[176:177], v48 offset0:154 offset1:219
	ds_read2_b32 v[178:179], v243 offset0:28 offset1:93
	ds_read2_b32 v[180:181], v243 offset0:158 offset1:223
	s_waitcnt lgkmcnt(8)
	v_cvt_pk_bf16_f32 v154, v154, v155
	v_cvt_pk_bf16_f32 v155, v156, v157
	v_cvt_pk_bf16_f32 v156, v158, v159
	v_cvt_pk_bf16_f32 v157, v160, v161
	global_store_dwordx4 v245, v[154:157], s[24:25]
	ds_read2_b32 v[182:183], v48 offset0:32 offset1:97
	ds_read2_b32 v[184:185], v48 offset0:162 offset1:227
	ds_read2_b32 v[186:187], v243 offset0:36 offset1:101
	ds_read2_b32 v[188:189], v243 offset0:166 offset1:231
	s_waitcnt lgkmcnt(8)
	v_cvt_pk_bf16_f32 v166, v166, v167
	v_cvt_pk_bf16_f32 v167, v168, v169
	v_cvt_pk_bf16_f32 v168, v170, v171
	v_cvt_pk_bf16_f32 v169, v172, v173
	global_store_dwordx4 v246, v[166:169], s[24:25]
	ds_read2_b32 v[108:109], v48 offset0:40 offset1:105
	ds_read2_b32 v[110:111], v48 offset0:170 offset1:235
	ds_read2_b32 v[112:113], v243 offset0:44 offset1:109
	ds_read2_b32 v[114:115], v243 offset0:174 offset1:239
	s_waitcnt lgkmcnt(8)
	v_cvt_pk_bf16_f32 v174, v174, v175
	v_cvt_pk_bf16_f32 v175, v176, v177
	v_cvt_pk_bf16_f32 v176, v178, v179
	v_cvt_pk_bf16_f32 v177, v180, v181
	global_store_dwordx4 v247, v[174:177], s[24:25]
	ds_read2_b32 v[116:117], v48 offset0:48 offset1:113
	ds_read2_b32 v[118:119], v48 offset0:178 offset1:243
	ds_read2_b32 v[120:121], v243 offset0:52 offset1:117
	ds_read2_b32 v[122:123], v243 offset0:182 offset1:247
	s_waitcnt lgkmcnt(8)
	v_cvt_pk_bf16_f32 v182, v182, v183
	v_cvt_pk_bf16_f32 v183, v184, v185
	v_cvt_pk_bf16_f32 v184, v186, v187
	v_cvt_pk_bf16_f32 v185, v188, v189
	global_store_dwordx4 v248, v[182:185], s[24:25]
	ds_read2_b32 v[124:125], v48 offset0:56 offset1:121
	ds_read2_b32 v[126:127], v48 offset0:186 offset1:251
	ds_read2_b32 v[128:129], v243 offset0:60 offset1:125
	ds_read2_b32 v[130:131], v243 offset0:190 offset1:255
	s_waitcnt lgkmcnt(8)
	v_cvt_pk_bf16_f32 v108, v108, v109
	v_cvt_pk_bf16_f32 v109, v110, v111
	v_cvt_pk_bf16_f32 v110, v112, v113
	v_cvt_pk_bf16_f32 v111, v114, v115
	global_store_dwordx4 v249, v[108:111], s[24:25]
	s_waitcnt lgkmcnt(4)
	v_cvt_pk_bf16_f32 v116, v116, v117
	v_cvt_pk_bf16_f32 v117, v118, v119
	v_cvt_pk_bf16_f32 v118, v120, v121
	v_cvt_pk_bf16_f32 v119, v122, v123
	global_store_dwordx4 v250, v[116:119], s[24:25]
	s_waitcnt lgkmcnt(0)
	v_cvt_pk_bf16_f32 v124, v124, v125
	v_cvt_pk_bf16_f32 v125, v126, v127
	v_cvt_pk_bf16_f32 v126, v128, v129
	v_cvt_pk_bf16_f32 v127, v130, v131
	global_store_dwordx4 v251, v[124:127], s[24:25]
	s_addk_i32 s10, 0x400
	s_cmpk_lt_u32 s10, 0xc00
	s_cbranch_scc1 .Lofl_item

; #define PG8_STAGE(bufoff, gbase, voff) do { _Pragma("unroll") for (int _i = 0; _i < 2; ++_i) \
;         __builtin_amdgcn_global_load_lds((const unsigned*)((const char*)(gbase) + (voff)[_i]), (PG8_LAS unsigned*)(lds + (bufoff) + ldsw + _i * 8192), 16, 0, 0); } while (0)
; #define PG8_WAIT_V(n) asm volatile("s_waitcnt vmcnt(" #n ")" ::: "memory")
; #define PG8_BAR __builtin_amdgcn_s_barrier()
; template <class Epi, class Sched, bool ALIGN_EPI = false, bool SP2 = false>
; __device__ __forceinline__ void gemm_phase(PG8_LAS unsigned char* lds, const Gemm g, const Sched& S, const Epi& E) {
;     ...
;     f32x4 acc[2][2][4][2];
; #pragma unroll
;     for (int a = 0; a < 2; ++a)
; #pragma unroll
;         for (int b = 0; b < 2; ++b)
; #pragma unroll
;             for (int m = 0; m < 4; ++m)
; #pragma unroll
;                 for (int n = 0; n < 2; ++n) acc[a][b][m][n] = (f32x4){0.f, 0.f, 0.f, 0.f};
;     ...
;         PG8_STAGE(PG8_SB(0, 0), cB, voffB); PG8_STAGE(PG8_SB(0, 1), cB + hstepB, voffB); PG8_STAGE(PG8_SA(0, 0), cA, voffA); PG8_STAGE(PG8_SA(0, 1), cA + hstepA, voffA);
;         if (wr == 1) PG8_BAR;
;         PG8_WAIT_V(2); PG8_BAR;
;         PG8_STAGE(PG8_SB(1, 0), cB + kstep, voffB); PG8_STAGE(PG8_SA(1, 0), cA + kstep, voffA); PG8_STAGE(PG8_SB(1, 1), cB + hstepB + kstep, voffB);
;         PG8_WAIT_V(6); PG8_BAR;
.LBB0_1521:
	v_and_b32_e32 v138, 15, v136
	v_and_b32_e32 v16, 48, v136
	v_lshlrev_b32_e32 v137, 2, v138
	s_and_b32 s23, s6, 3
	s_lshl_b32 s6, s9, 13
	v_lshl_or_b32 v16, v138, 6, v16
	v_and_b32_e32 v17, 32, v137
	s_add_i32 m0, s21, 0x18000
	v_lshl_add_u64 v[6:7], v[6:7], 0, s[48:49]
	s_lshl_b32 s25, s9, 6
	v_bitop3_b32 v18, v16, s6, v17 bitop3:0xde
	s_lshl_b32 s6, s23, 12
	s_waitcnt vmcnt(2)
	s_barrier
	global_load_lds_dwordx4 v[6:7], off
	v_lshl_add_u64 v[4:5], v[4:5], 0, s[48:49]
	s_add_i32 m0, s21, 0x1a000
	s_add_i32 s31, s21, 0x8000
	s_add_i32 s34, s21, 0xa000
	global_load_lds_dwordx4 v[4:5], off
	v_lshl_add_u64 v[2:3], v[2:3], 0, s[48:49]
	s_mov_b32 m0, s31
	s_add_u32 s10, s2, 0xb0080
	global_load_lds_dwordx4 v[2:3], off
	v_lshl_add_u64 v[0:1], v[0:1], 0, s[48:49]
	s_mov_b32 m0, s34
	s_addc_u32 s11, s3, 0
	global_load_lds_dwordx4 v[0:1], off
	s_add_i32 m0, s21, 0x1c000
	v_lshl_add_u64 v[0:1], s[10:11], 0, v[64:65]
	global_load_lds_dwordx4 v[0:1], off
	v_lshl_add_u64 v[0:1], s[10:11], 0, v[130:131]
	s_add_i32 m0, s21, 0x1e000
	s_mov_b32 s9, 0xb000
	global_load_lds_dwordx4 v[0:1], off
	v_lshrrev_b32_e32 v1, 1, v8
	v_mul_lo_u32 v0, v11, s61
	v_mad_u64_u32 v[0:1], s[10:11], v1, s9, v[0:1]
	v_readlane_b32 s10, v254, 3
	v_bitop3_b32 v139, v16, s6, v17 bitop3:0xde
	v_or_b32_e32 v0, v0, v9
	v_readlane_b32 s11, v254, 4
	s_add_u32 s6, s10, s8
	v_add_lshl_u32 v0, v0, v12, 1
	v_mov_b32_e32 v1, v65
	s_addc_u32 s7, s11, s7
	v_lshl_add_u64 v[132:133], s[6:7], 0, v[0:1]
	v_lshrrev_b32_e32 v1, 1, v10
	v_mul_lo_u32 v0, v14, s61
	v_mad_u64_u32 v[0:1], s[8:9], v1, s9, v[0:1]
	v_or_b32_e32 v0, v0, v13
	s_waitcnt vmcnt(6)
	v_add_lshl_u32 v0, v0, v15, 1
	v_mov_b32_e32 v1, v65
	v_lshl_add_u64 v[134:135], s[6:7], 0, v[0:1]
	v_mov_b32_e32 v0, 0
	v_or_b32_e32 v179, s25, v138
	s_mov_b32 s38, -2
	s_mov_b64 s[6:7], 0x66b0080
	v_add_u32_e32 v140, 0, v18
	v_mov_b32_e32 v1, v0
	v_mov_b32_e32 v2, v0
	v_mov_b32_e32 v3, v0
	v_mov_b32_e32 v4, v0
	v_mov_b32_e32 v5, v0
	v_mov_b32_e32 v6, v0
	v_mov_b32_e32 v7, v0
	v_mov_b32_e32 v16, v0
	v_mov_b32_e32 v17, v0
	v_mov_b32_e32 v18, v0
	v_mov_b32_e32 v19, v0
	v_mov_b32_e32 v20, v0
	v_mov_b32_e32 v21, v0
	v_mov_b32_e32 v22, v0
	v_mov_b32_e32 v23, v0
	v_mov_b32_e32 v32, v0
	v_mov_b32_e32 v33, v0
	v_mov_b32_e32 v34, v0
	v_mov_b32_e32 v35, v0
	v_mov_b32_e32 v36, v0
	v_mov_b32_e32 v37, v0
	v_mov_b32_e32 v38, v0
	v_mov_b32_e32 v39, v0
	v_mov_b32_e32 v48, v0
	v_mov_b32_e32 v49, v0
	v_mov_b32_e32 v50, v0
	v_mov_b32_e32 v51, v0
	v_mov_b32_e32 v52, v0
	v_mov_b32_e32 v53, v0
	v_mov_b32_e32 v54, v0
	v_mov_b32_e32 v55, v0
	v_mov_b32_e32 v8, v0
	v_mov_b32_e32 v9, v0
	v_mov_b32_e32 v10, v0
	v_mov_b32_e32 v11, v0
	v_mov_b32_e32 v12, v0
	v_mov_b32_e32 v13, v0
	v_mov_b32_e32 v14, v0
	v_mov_b32_e32 v15, v0
	v_mov_b32_e32 v24, v0
	v_mov_b32_e32 v25, v0
	v_mov_b32_e32 v26, v0
	v_mov_b32_e32 v27, v0
	v_mov_b32_e32 v28, v0
	v_mov_b32_e32 v29, v0
	v_mov_b32_e32 v30, v0
	v_mov_b32_e32 v31, v0
	v_mov_b32_e32 v40, v0
	v_mov_b32_e32 v41, v0
	v_mov_b32_e32 v42, v0
	v_mov_b32_e32 v43, v0
	v_mov_b32_e32 v44, v0
	v_mov_b32_e32 v45, v0
	v_mov_b32_e32 v46, v0
	v_mov_b32_e32 v47, v0
	v_mov_b32_e32 v56, v0
	v_mov_b32_e32 v57, v0
	v_mov_b32_e32 v58, v0
	v_mov_b32_e32 v59, v0
	v_mov_b32_e32 v60, v0
	v_mov_b32_e32 v61, v0
	v_mov_b32_e32 v62, v0
	v_mov_b32_e32 v63, v0
	v_mov_b32_e32 v66, v0
	v_mov_b32_e32 v67, v0
	v_mov_b32_e32 v68, v0
	v_mov_b32_e32 v69, v0
	v_mov_b32_e32 v70, v0
	v_mov_b32_e32 v71, v0
	v_mov_b32_e32 v72, v0
	v_mov_b32_e32 v73, v0
	v_mov_b32_e32 v82, v0
	v_mov_b32_e32 v83, v0
	v_mov_b32_e32 v84, v0
	v_mov_b32_e32 v85, v0
	v_mov_b32_e32 v86, v0
	v_mov_b32_e32 v87, v0
	v_mov_b32_e32 v88, v0
	v_mov_b32_e32 v89, v0
	v_mov_b32_e32 v98, v0
	v_mov_b32_e32 v99, v0
	v_mov_b32_e32 v100, v0
	v_mov_b32_e32 v101, v0
	v_mov_b32_e32 v102, v0
	v_mov_b32_e32 v103, v0
	v_mov_b32_e32 v104, v0
	v_mov_b32_e32 v105, v0
	v_mov_b32_e32 v114, v0
	v_mov_b32_e32 v115, v0
	v_mov_b32_e32 v116, v0
	v_mov_b32_e32 v117, v0
	v_mov_b32_e32 v118, v0
	v_mov_b32_e32 v119, v0
	v_mov_b32_e32 v120, v0
	v_mov_b32_e32 v121, v0
	v_mov_b32_e32 v74, v0
	v_mov_b32_e32 v75, v0
	v_mov_b32_e32 v76, v0
	v_mov_b32_e32 v77, v0
	v_mov_b32_e32 v78, v0
	v_mov_b32_e32 v79, v0
	v_mov_b32_e32 v80, v0
	v_mov_b32_e32 v81, v0
	v_mov_b32_e32 v90, v0
	v_mov_b32_e32 v91, v0
	v_mov_b32_e32 v92, v0
	v_mov_b32_e32 v93, v0
	v_mov_b32_e32 v94, v0
	v_mov_b32_e32 v95, v0
	v_mov_b32_e32 v96, v0
	v_mov_b32_e32 v97, v0
	v_mov_b32_e32 v106, v0
	v_mov_b32_e32 v107, v0
	v_mov_b32_e32 v108, v0
	v_mov_b32_e32 v109, v0
	v_mov_b32_e32 v110, v0
	v_mov_b32_e32 v111, v0
	v_mov_b32_e32 v112, v0
	v_mov_b32_e32 v113, v0
	v_mov_b32_e32 v122, v0
	v_mov_b32_e32 v123, v0
	v_mov_b32_e32 v124, v0
	v_mov_b32_e32 v125, v0
	v_mov_b32_e32 v126, v0
	v_mov_b32_e32 v127, v0
	v_mov_b32_e32 v128, v0
	v_mov_b32_e32 v129, v0
	s_barrier
